# rs row-scale loads hoisted before the K-loop (epilogue drains kept) on top of SEC1 rewrite
# speedup vs baseline: 1.0125x; 1.0033x over previous
.LBB0_53:
	v_lshl_add_u32 v171, s48, 8, v241
	v_lshlrev_b32_e32 v171, 2, v171
	global_load_dword v164, v171, s[70:71]
	global_load_dword v165, v171, s[70:71] offset:64
	global_load_dword v166, v171, s[70:71] offset:128
	global_load_dword v167, v171, s[70:71] offset:192
	global_load_dword v246, v171, s[70:71] offset:512
	global_load_dword v247, v171, s[70:71] offset:576
	global_load_dword v248, v171, s[70:71] offset:640
	global_load_dword v249, v171, s[70:71] offset:704
	s_add_u32 s0, s4, 0x40080
	s_addc_u32 s1, s5, 0
	s_add_u32 s3, s20, 0x100
	v_mov_b32_e32 v4, 0
	s_addc_u32 s20, s21, 0
	s_mov_b32 s21, -2
	v_mov_b32_e32 v5, v4
	v_mov_b32_e32 v6, v4
	v_mov_b32_e32 v7, v4
	v_mov_b32_e32 v8, v4
	v_mov_b32_e32 v9, v4
	v_mov_b32_e32 v10, v4
	v_mov_b32_e32 v11, v4
	v_mov_b32_e32 v12, v4
	v_mov_b32_e32 v13, v4
	v_mov_b32_e32 v14, v4
	v_mov_b32_e32 v15, v4
	v_mov_b32_e32 v16, v4
	v_mov_b32_e32 v17, v4
	v_mov_b32_e32 v18, v4
	v_mov_b32_e32 v19, v4
	v_mov_b32_e32 v20, v4
	v_mov_b32_e32 v21, v4
	v_mov_b32_e32 v22, v4
	v_mov_b32_e32 v23, v4
	v_mov_b32_e32 v24, v4
	v_mov_b32_e32 v25, v4
	v_mov_b32_e32 v26, v4
	v_mov_b32_e32 v27, v4
	v_mov_b32_e32 v28, v4
	v_mov_b32_e32 v29, v4
	v_mov_b32_e32 v30, v4
	v_mov_b32_e32 v31, v4
	v_mov_b32_e32 v32, v4
	v_mov_b32_e32 v33, v4
	v_mov_b32_e32 v34, v4
	v_mov_b32_e32 v35, v4
	v_mov_b32_e32 v68, v4
	v_mov_b32_e32 v69, v4
	v_mov_b32_e32 v70, v4
	v_mov_b32_e32 v71, v4
	v_mov_b32_e32 v72, v4
	v_mov_b32_e32 v73, v4
	v_mov_b32_e32 v74, v4
	v_mov_b32_e32 v75, v4
	v_mov_b32_e32 v76, v4
	v_mov_b32_e32 v77, v4
	v_mov_b32_e32 v78, v4
	v_mov_b32_e32 v79, v4
	v_mov_b32_e32 v80, v4
	v_mov_b32_e32 v81, v4
	v_mov_b32_e32 v82, v4
	v_mov_b32_e32 v83, v4
	v_mov_b32_e32 v84, v4
	v_mov_b32_e32 v85, v4
	v_mov_b32_e32 v86, v4
	v_mov_b32_e32 v87, v4
	v_mov_b32_e32 v88, v4
	v_mov_b32_e32 v89, v4
	v_mov_b32_e32 v90, v4
	v_mov_b32_e32 v91, v4
	v_mov_b32_e32 v92, v4
	v_mov_b32_e32 v93, v4
	v_mov_b32_e32 v94, v4
	v_mov_b32_e32 v95, v4
	v_mov_b32_e32 v96, v4
	v_mov_b32_e32 v97, v4
	v_mov_b32_e32 v98, v4
	v_mov_b32_e32 v99, v4
	v_mov_b32_e32 v36, v4
	v_mov_b32_e32 v37, v4
	v_mov_b32_e32 v38, v4
	v_mov_b32_e32 v39, v4
	v_mov_b32_e32 v40, v4
	v_mov_b32_e32 v41, v4
	v_mov_b32_e32 v42, v4
	v_mov_b32_e32 v43, v4
	v_mov_b32_e32 v44, v4
	v_mov_b32_e32 v45, v4
	v_mov_b32_e32 v46, v4
	v_mov_b32_e32 v47, v4
	v_mov_b32_e32 v48, v4
	v_mov_b32_e32 v49, v4
	v_mov_b32_e32 v50, v4
	v_mov_b32_e32 v51, v4
	v_mov_b32_e32 v52, v4
	v_mov_b32_e32 v53, v4
	v_mov_b32_e32 v54, v4
	v_mov_b32_e32 v55, v4
	v_mov_b32_e32 v56, v4
	v_mov_b32_e32 v57, v4
	v_mov_b32_e32 v58, v4
	v_mov_b32_e32 v59, v4
	v_mov_b32_e32 v60, v4
	v_mov_b32_e32 v61, v4
	v_mov_b32_e32 v62, v4
	v_mov_b32_e32 v63, v4
	v_mov_b32_e32 v64, v4
	v_mov_b32_e32 v65, v4
	v_mov_b32_e32 v66, v4
	v_mov_b32_e32 v67, v4
	v_mov_b32_e32 v100, v4
	v_mov_b32_e32 v101, v4
	v_mov_b32_e32 v102, v4
	v_mov_b32_e32 v103, v4
	v_mov_b32_e32 v104, v4
	v_mov_b32_e32 v105, v4
	v_mov_b32_e32 v106, v4
	v_mov_b32_e32 v107, v4
	v_mov_b32_e32 v108, v4
	v_mov_b32_e32 v109, v4
	v_mov_b32_e32 v110, v4
	v_mov_b32_e32 v111, v4
	v_mov_b32_e32 v112, v4
	v_mov_b32_e32 v113, v4
	v_mov_b32_e32 v114, v4
	v_mov_b32_e32 v115, v4
	v_mov_b32_e32 v116, v4
	v_mov_b32_e32 v117, v4
	v_mov_b32_e32 v118, v4
	v_mov_b32_e32 v119, v4
	v_mov_b32_e32 v120, v4
	v_mov_b32_e32 v121, v4
	v_mov_b32_e32 v122, v4
	v_mov_b32_e32 v123, v4
	v_mov_b32_e32 v124, v4
	v_mov_b32_e32 v125, v4
	v_mov_b32_e32 v126, v4
	v_mov_b32_e32 v127, v4
	v_mov_b32_e32 v128, v4
	v_mov_b32_e32 v129, v4
	v_mov_b32_e32 v130, v4
	v_mov_b32_e32 v131, v4

.Lsec78_a:
	s_lshl_b32 s0, s48, 8
	v_add_u32_e32 v134, s0, v241
	v_ashrrev_i32_e32 v135, 31, v134
	v_lshl_add_u64 v[146:147], v[134:135], 2, s[70:71]
	v_mov_b32_e32 v148, v164
	v_mov_b32_e32 v144, v165
	v_mov_b32_e32 v140, v166
	v_mov_b32_e32 v2, v167
	v_or_b32_e32 v132, s74, v178
	v_ashrrev_i32_e32 v133, 31, v132
	v_lshlrev_b64 v[132:133], 1, v[132:133]
	s_mov_b32 s0, 0x9ce6000
	s_cmp_eq_u32 s2, 8
	s_cselect_b32 s0, 0xbd25800, s0
	v_or_b32_e32 v142, 16, v134
	v_ashrrev_i32_e32 v143, 31, v142
	v_lshlrev_b64 v[142:143], 11, v[142:143]
	v_lshl_add_u64 v[142:143], s[94:95], 0, v[142:143]
	v_or_b32_e32 v138, 32, v134
	v_ashrrev_i32_e32 v139, 31, v138
	v_lshlrev_b64 v[138:139], 11, v[138:139]
	v_lshl_add_u64 v[138:139], s[94:95], 0, v[138:139]
	v_or_b32_e32 v136, 48, v134
	v_ashrrev_i32_e32 v137, 31, v136
	v_lshlrev_b64 v[136:137], 11, v[136:137]
	v_lshl_add_u64 v[136:137], s[94:95], 0, v[136:137]
	s_cmp_eq_u32 s48, 64
	s_waitcnt vmcnt(0)
	v_pk_mul_f32 v[146:147], v[130:131], v[148:149] op_sel_hi:[1,0]
	s_nop 0
	v_mul_f32_e32 v146, 0xbfb8aa3b, v146
	v_exp_f32_e32 v146, v146
	v_pk_mul_f32 v[150:151], v[128:129], v[148:149] op_sel_hi:[1,0]
	v_add_f32_e32 v146, 1.0, v146
	v_rcp_f32_e32 v152, v146
	v_mul_f32_e32 v146, 0xbfb8aa3b, v147
	v_exp_f32_e32 v146, v146
	v_mul_f32_e32 v141, 0xbfb8aa3b, v150
	v_mul_f32_e32 v145, 0xbfb8aa3b, v151
	v_exp_f32_e32 v141, v141
	v_add_f32_e32 v146, 1.0, v146
	v_rcp_f32_e32 v153, v146
	v_pk_mul_f32 v[146:147], v[126:127], v[148:149] op_sel_hi:[1,0]
	v_pk_mul_f32 v[148:149], v[124:125], v[148:149] op_sel_hi:[1,0]
	v_mul_f32_e32 v146, 0xbfb8aa3b, v146
	v_exp_f32_e32 v146, v146
	v_mul_f32_e32 v148, 0xbfb8aa3b, v148
	v_mul_f32_e32 v149, 0xbfb8aa3b, v149
	v_exp_f32_e32 v145, v145
	v_add_f32_e32 v146, 1.0, v146
	v_rcp_f32_e32 v154, v146
	v_mul_f32_e32 v146, 0xbfb8aa3b, v147
	v_exp_f32_e32 v148, v148
	v_exp_f32_e32 v149, v149
	v_exp_f32_e32 v146, v146
	v_add_f32_e32 v141, 1.0, v141
	v_add_f32_e32 v145, 1.0, v145
	v_add_f32_e32 v148, 1.0, v148
	v_add_f32_e32 v149, 1.0, v149
	v_add_f32_e32 v146, 1.0, v146
	v_rcp_f32_e32 v141, v141
	v_rcp_f32_e32 v145, v145
	v_rcp_f32_e32 v148, v148
	v_rcp_f32_e32 v149, v149
	v_rcp_f32_e32 v155, v146
	v_lshlrev_b64 v[146:147], 11, v[134:135]
	v_lshl_add_u64 v[146:147], s[94:95], 0, v[146:147]
	v_lshl_add_u64 v[150:151], v[146:147], 0, v[132:133]
	v_add_co_u32_e32 v150, vcc, s0, v150
	v_cvt_pk_bf16_f32 v146, v141, v145
	v_cvt_pk_bf16_f32 v147, v152, v153
	v_cvt_pk_bf16_f32 v148, v148, v149
	v_cvt_pk_bf16_f32 v149, v154, v155
	v_addc_co_u32_e32 v151, vcc, 0, v151, vcc
	global_store_dwordx4 v[150:151], v[146:149], off offset:512
	s_nop 1
	v_pk_mul_f32 v[146:147], v[122:123], v[144:145] op_sel_hi:[1,0]
	v_pk_mul_f32 v[148:149], v[120:121], v[144:145] op_sel_hi:[1,0]
	v_mul_f32_e32 v145, 0xbfb8aa3b, v146
	v_exp_f32_e32 v145, v145
	v_mul_f32_e32 v135, 0xbfb8aa3b, v148
	v_mul_f32_e32 v141, 0xbfb8aa3b, v149
	v_exp_f32_e32 v135, v135
	v_add_f32_e32 v145, 1.0, v145
	v_rcp_f32_e32 v148, v145
	v_mul_f32_e32 v145, 0xbfb8aa3b, v147
	v_exp_f32_e32 v145, v145
	v_exp_f32_e32 v141, v141
	v_add_f32_e32 v135, 1.0, v135
	v_rcp_f32_e32 v135, v135
	v_add_f32_e32 v145, 1.0, v145
	v_pk_mul_f32 v[146:147], v[118:119], v[144:145] op_sel_hi:[1,0]
	v_rcp_f32_e32 v149, v145
	v_mul_f32_e32 v146, 0xbfb8aa3b, v146
	v_exp_f32_e32 v146, v146
	v_pk_mul_f32 v[144:145], v[116:117], v[144:145] op_sel_hi:[1,0]
	v_add_f32_e32 v141, 1.0, v141
	v_mul_f32_e32 v144, 0xbfb8aa3b, v144
	v_add_f32_e32 v146, 1.0, v146
	v_mul_f32_e32 v145, 0xbfb8aa3b, v145
	v_rcp_f32_e32 v150, v146
	v_mul_f32_e32 v146, 0xbfb8aa3b, v147
	v_exp_f32_e32 v144, v144
	v_exp_f32_e32 v145, v145
	v_exp_f32_e32 v146, v146
	v_rcp_f32_e32 v141, v141
	v_add_f32_e32 v144, 1.0, v144
	v_add_f32_e32 v145, 1.0, v145
	v_add_f32_e32 v146, 1.0, v146
	v_rcp_f32_e32 v144, v144
	v_rcp_f32_e32 v145, v145
	v_rcp_f32_e32 v151, v146
	v_lshl_add_u64 v[146:147], v[142:143], 0, v[132:133]
	v_add_co_u32_e32 v146, vcc, s0, v146
	v_cvt_pk_bf16_f32 v142, v135, v141
	v_cvt_pk_bf16_f32 v143, v148, v149
	v_cvt_pk_bf16_f32 v144, v144, v145
	v_cvt_pk_bf16_f32 v145, v150, v151
	v_addc_co_u32_e32 v147, vcc, 0, v147, vcc
	global_store_dwordx4 v[146:147], v[142:145], off offset:512
	s_nop 1
	v_pk_mul_f32 v[144:145], v[112:113], v[140:141] op_sel_hi:[1,0]
	v_pk_mul_f32 v[142:143], v[114:115], v[140:141] op_sel_hi:[1,0]
	v_mul_f32_e32 v141, 0xbfb8aa3b, v145
	v_exp_f32_e32 v141, v141
	v_mul_f32_e32 v135, 0xbfb8aa3b, v144
	v_exp_f32_e32 v135, v135
	v_add_f32_e32 v141, 1.0, v141
	v_rcp_f32_e32 v144, v141
	v_mul_f32_e32 v141, 0xbfb8aa3b, v142
	v_exp_f32_e32 v141, v141
	v_add_f32_e32 v135, 1.0, v135
	v_rcp_f32_e32 v135, v135
	v_add_f32_e32 v141, 1.0, v141
	v_rcp_f32_e32 v145, v141
	v_mul_f32_e32 v141, 0xbfb8aa3b, v143
	v_exp_f32_e32 v141, v141
	s_nop 0
	v_add_f32_e32 v141, 1.0, v141
	v_pk_mul_f32 v[142:143], v[110:111], v[140:141] op_sel_hi:[1,0]
	v_rcp_f32_e32 v146, v141
	v_mul_f32_e32 v142, 0xbfb8aa3b, v142
	v_exp_f32_e32 v142, v142
	v_pk_mul_f32 v[140:141], v[108:109], v[140:141] op_sel_hi:[1,0]
	v_add_f32_e32 v142, 1.0, v142
	v_mul_f32_e32 v140, 0xbfb8aa3b, v140
	v_mul_f32_e32 v141, 0xbfb8aa3b, v141
	v_rcp_f32_e32 v147, v142
	v_mul_f32_e32 v142, 0xbfb8aa3b, v143
	v_exp_f32_e32 v140, v140
	v_exp_f32_e32 v141, v141
	v_exp_f32_e32 v142, v142
	v_add_f32_e32 v140, 1.0, v140
	v_add_f32_e32 v141, 1.0, v141
	v_add_f32_e32 v142, 1.0, v142
	v_rcp_f32_e32 v140, v140
	v_rcp_f32_e32 v141, v141
	v_rcp_f32_e32 v148, v142
	v_lshl_add_u64 v[142:143], v[138:139], 0, v[132:133]
	v_add_co_u32_e32 v142, vcc, s0, v142
	v_cvt_pk_bf16_f32 v138, v135, v144
	v_cvt_pk_bf16_f32 v139, v145, v146
	v_cvt_pk_bf16_f32 v140, v140, v141
	v_cvt_pk_bf16_f32 v141, v147, v148
	v_addc_co_u32_e32 v143, vcc, 0, v143, vcc
	global_store_dwordx4 v[142:143], v[138:141], off offset:512
	s_nop 1
	v_pk_mul_f32 v[138:139], v[106:107], v[2:3] op_sel_hi:[1,0]
	v_pk_mul_f32 v[140:141], v[104:105], v[2:3] op_sel_hi:[1,0]
	v_mul_f32_e32 v138, 0xbfb8aa3b, v138
	v_exp_f32_e32 v138, v138
	v_mul_f32_e32 v135, 0xbfb8aa3b, v140
	v_mul_f32_e32 v140, 0xbfb8aa3b, v141
	v_exp_f32_e32 v140, v140
	v_add_f32_e32 v138, 1.0, v138
	v_rcp_f32_e32 v143, v138
	v_mul_f32_e32 v138, 0xbfb8aa3b, v139
	v_exp_f32_e32 v138, v138
	v_add_f32_e32 v140, 1.0, v140
	v_rcp_f32_e32 v142, v140
	v_pk_mul_f32 v[140:141], v[100:101], v[2:3] op_sel_hi:[1,0]
	v_add_f32_e32 v138, 1.0, v138
	v_rcp_f32_e32 v144, v138
	v_pk_mul_f32 v[138:139], v[102:103], v[2:3] op_sel_hi:[1,0]
	v_mul_f32_e32 v2, 0xbfb8aa3b, v140
	v_mul_f32_e32 v138, 0xbfb8aa3b, v138
	v_exp_f32_e32 v138, v138
	v_mul_f32_e32 v140, 0xbfb8aa3b, v141
	v_exp_f32_e32 v135, v135
	v_exp_f32_e32 v2, v2
	v_add_f32_e32 v138, 1.0, v138
	v_rcp_f32_e32 v146, v138
	v_mul_f32_e32 v138, 0xbfb8aa3b, v139
	v_exp_f32_e32 v140, v140
	v_exp_f32_e32 v138, v138
	v_add_f32_e32 v135, 1.0, v135
	v_add_f32_e32 v2, 1.0, v2
	v_add_f32_e32 v140, 1.0, v140
	v_add_f32_e32 v138, 1.0, v138
	v_rcp_f32_e32 v135, v135
	v_rcp_f32_e32 v2, v2
	v_rcp_f32_e32 v145, v140
	v_rcp_f32_e32 v139, v138
	v_lshl_add_u64 v[140:141], v[136:137], 0, v[132:133]
	v_add_co_u32_e32 v140, vcc, s0, v140
	v_cvt_pk_bf16_f32 v136, v135, v142
	v_cvt_pk_bf16_f32 v137, v143, v144
	v_cvt_pk_bf16_f32 v138, v2, v145
	v_cvt_pk_bf16_f32 v139, v146, v139
	v_addc_co_u32_e32 v141, vcc, 0, v141, vcc
	global_store_dwordx4 v[140:141], v[136:139], off offset:512
	s_cbranch_scc1 .LBB0_70
	v_add_u32_e32 v144, 0x80, v134
	v_ashrrev_i32_e32 v145, 31, v144
	v_lshl_add_u64 v[146:147], v[144:145], 2, s[70:71]
	v_mov_b32_e32 v148, v246
	v_mov_b32_e32 v142, v247
	v_mov_b32_e32 v138, v248
	v_mov_b32_e32 v2, v249
	v_lshlrev_b64 v[144:145], 11, v[144:145]
	v_lshl_add_u64 v[144:145], s[94:95], 0, v[144:145]
	v_add_u32_e32 v140, 0x90, v134
	v_ashrrev_i32_e32 v141, 31, v140
	v_lshlrev_b64 v[140:141], 11, v[140:141]
	v_lshl_add_u64 v[140:141], s[94:95], 0, v[140:141]
	v_add_u32_e32 v136, 0xa0, v134
	v_ashrrev_i32_e32 v137, 31, v136
	v_lshlrev_b64 v[136:137], 11, v[136:137]
	v_lshl_add_u64 v[136:137], s[94:95], 0, v[136:137]
	v_add_u32_e32 v134, 0xb0, v134
	v_ashrrev_i32_e32 v135, 31, v134
	v_lshlrev_b64 v[134:135], 11, v[134:135]
	v_lshl_add_u64 v[134:135], s[94:95], 0, v[134:135]
	s_waitcnt vmcnt(0)
	v_pk_mul_f32 v[146:147], v[98:99], v[148:149] op_sel_hi:[1,0]
	s_nop 0
	v_mul_f32_e32 v146, 0xbfb8aa3b, v146
	v_exp_f32_e32 v146, v146
	v_pk_mul_f32 v[150:151], v[96:97], v[148:149] op_sel_hi:[1,0]
	v_add_f32_e32 v146, 1.0, v146
	v_mul_f32_e32 v139, 0xbfb8aa3b, v150
	v_rcp_f32_e32 v150, v146
	v_mul_f32_e32 v146, 0xbfb8aa3b, v147
	v_exp_f32_e32 v146, v146
	v_mul_f32_e32 v143, 0xbfb8aa3b, v151
	v_exp_f32_e32 v139, v139
	v_exp_f32_e32 v143, v143
	v_add_f32_e32 v146, 1.0, v146
	v_rcp_f32_e32 v151, v146
	v_pk_mul_f32 v[146:147], v[94:95], v[148:149] op_sel_hi:[1,0]
	v_pk_mul_f32 v[148:149], v[92:93], v[148:149] op_sel_hi:[1,0]
	v_mul_f32_e32 v146, 0xbfb8aa3b, v146
	v_mul_f32_e32 v148, 0xbfb8aa3b, v148
	v_exp_f32_e32 v148, v148
	v_exp_f32_e32 v146, v146
	v_add_f32_e32 v139, 1.0, v139
	v_add_f32_e32 v143, 1.0, v143
	v_add_f32_e32 v148, 1.0, v148
	v_add_f32_e32 v146, 1.0, v146
	v_rcp_f32_e32 v152, v148
	v_mul_f32_e32 v148, 0xbfb8aa3b, v149
	v_rcp_f32_e32 v154, v146
	v_mul_f32_e32 v146, 0xbfb8aa3b, v147
	v_exp_f32_e32 v148, v148
	v_exp_f32_e32 v146, v146
	v_rcp_f32_e32 v139, v139
	v_rcp_f32_e32 v143, v143
	v_add_f32_e32 v148, 1.0, v148
	v_add_f32_e32 v146, 1.0, v146
	v_rcp_f32_e32 v153, v148
	v_rcp_f32_e32 v147, v146
	v_lshl_add_u64 v[148:149], v[144:145], 0, v[132:133]
	v_add_co_u32_e32 v148, vcc, s0, v148
	v_cvt_pk_bf16_f32 v144, v139, v143
	v_cvt_pk_bf16_f32 v145, v150, v151
	v_cvt_pk_bf16_f32 v146, v152, v153
	v_cvt_pk_bf16_f32 v147, v154, v147
	v_addc_co_u32_e32 v149, vcc, 0, v149, vcc
	global_store_dwordx4 v[148:149], v[144:147], off offset:512
	s_nop 1
	v_pk_mul_f32 v[146:147], v[88:89], v[142:143] op_sel_hi:[1,0]
	v_pk_mul_f32 v[144:145], v[90:91], v[142:143] op_sel_hi:[1,0]
	v_mul_f32_e32 v143, 0xbfb8aa3b, v147
	v_exp_f32_e32 v143, v143
	v_mul_f32_e32 v139, 0xbfb8aa3b, v146
	v_exp_f32_e32 v139, v139
	v_add_f32_e32 v143, 1.0, v143
	v_rcp_f32_e32 v146, v143
	v_mul_f32_e32 v143, 0xbfb8aa3b, v144
	v_exp_f32_e32 v143, v143
	v_add_f32_e32 v139, 1.0, v139
	v_rcp_f32_e32 v139, v139
	v_add_f32_e32 v143, 1.0, v143
	v_rcp_f32_e32 v147, v143
	v_mul_f32_e32 v143, 0xbfb8aa3b, v145
	v_exp_f32_e32 v143, v143
	s_nop 0
	v_add_f32_e32 v143, 1.0, v143
	v_pk_mul_f32 v[144:145], v[86:87], v[142:143] op_sel_hi:[1,0]
	v_rcp_f32_e32 v148, v143
	v_mul_f32_e32 v144, 0xbfb8aa3b, v144
	v_exp_f32_e32 v144, v144
	v_pk_mul_f32 v[142:143], v[84:85], v[142:143] op_sel_hi:[1,0]
	v_add_f32_e32 v144, 1.0, v144
	v_mul_f32_e32 v142, 0xbfb8aa3b, v142
	v_mul_f32_e32 v143, 0xbfb8aa3b, v143
	v_rcp_f32_e32 v149, v144
	v_mul_f32_e32 v144, 0xbfb8aa3b, v145
	v_exp_f32_e32 v142, v142
	v_exp_f32_e32 v143, v143
	v_exp_f32_e32 v144, v144
	v_add_f32_e32 v142, 1.0, v142
	v_add_f32_e32 v143, 1.0, v143
	v_add_f32_e32 v144, 1.0, v144
	v_rcp_f32_e32 v142, v142
	v_rcp_f32_e32 v143, v143
	v_rcp_f32_e32 v150, v144
	v_lshl_add_u64 v[144:145], v[140:141], 0, v[132:133]
	v_add_co_u32_e32 v144, vcc, s0, v144
	v_cvt_pk_bf16_f32 v140, v139, v146
	v_cvt_pk_bf16_f32 v141, v147, v148
	v_cvt_pk_bf16_f32 v142, v142, v143
	v_cvt_pk_bf16_f32 v143, v149, v150
	v_addc_co_u32_e32 v145, vcc, 0, v145, vcc
	global_store_dwordx4 v[144:145], v[140:143], off offset:512
	s_nop 1
	v_pk_mul_f32 v[142:143], v[80:81], v[138:139] op_sel_hi:[1,0]
	v_pk_mul_f32 v[140:141], v[82:83], v[138:139] op_sel_hi:[1,0]
	v_mul_f32_e32 v139, 0xbfb8aa3b, v142
	v_exp_f32_e32 v139, v139
	s_nop 0
	v_add_f32_e32 v139, 1.0, v139
	v_rcp_f32_e32 v142, v139
	v_mul_f32_e32 v139, 0xbfb8aa3b, v143
	v_exp_f32_e32 v139, v139
	s_nop 0
	v_add_f32_e32 v139, 1.0, v139
	v_rcp_f32_e32 v143, v139
	v_mul_f32_e32 v139, 0xbfb8aa3b, v140
	v_exp_f32_e32 v139, v139
	s_nop 0
	v_add_f32_e32 v139, 1.0, v139
	v_rcp_f32_e32 v144, v139
	v_mul_f32_e32 v139, 0xbfb8aa3b, v141
	v_exp_f32_e32 v139, v139
	s_nop 0
	v_add_f32_e32 v139, 1.0, v139
	v_pk_mul_f32 v[140:141], v[78:79], v[138:139] op_sel_hi:[1,0]
	v_rcp_f32_e32 v145, v139
	v_mul_f32_e32 v140, 0xbfb8aa3b, v140
	v_exp_f32_e32 v140, v140
	v_pk_mul_f32 v[138:139], v[76:77], v[138:139] op_sel_hi:[1,0]
	v_add_f32_e32 v140, 1.0, v140
	v_mul_f32_e32 v138, 0xbfb8aa3b, v138
	v_mul_f32_e32 v139, 0xbfb8aa3b, v139
	v_rcp_f32_e32 v146, v140
	v_mul_f32_e32 v140, 0xbfb8aa3b, v141
	v_exp_f32_e32 v138, v138
	v_exp_f32_e32 v139, v139
	v_exp_f32_e32 v140, v140
	v_add_f32_e32 v138, 1.0, v138
	v_add_f32_e32 v139, 1.0, v139
	v_add_f32_e32 v140, 1.0, v140
	v_rcp_f32_e32 v138, v138
	v_rcp_f32_e32 v139, v139
	v_rcp_f32_e32 v147, v140
	v_lshl_add_u64 v[140:141], v[136:137], 0, v[132:133]
	v_add_co_u32_e32 v140, vcc, s0, v140
	v_cvt_pk_bf16_f32 v136, v142, v143
	v_cvt_pk_bf16_f32 v137, v144, v145
	v_cvt_pk_bf16_f32 v138, v138, v139
	v_cvt_pk_bf16_f32 v139, v146, v147
	v_addc_co_u32_e32 v141, vcc, 0, v141, vcc
	global_store_dwordx4 v[140:141], v[136:139], off offset:512
	s_nop 1
	v_pk_mul_f32 v[136:137], v[74:75], v[2:3] op_sel_hi:[1,0]
	v_pk_mul_f32 v[138:139], v[72:73], v[2:3] op_sel_hi:[1,0]
	v_mul_f32_e32 v136, 0xbfb8aa3b, v136
	v_exp_f32_e32 v136, v136
	v_mul_f32_e32 v138, 0xbfb8aa3b, v138
	v_exp_f32_e32 v138, v138
	v_add_f32_e32 v136, 1.0, v136
	v_rcp_f32_e32 v142, v136
	v_mul_f32_e32 v136, 0xbfb8aa3b, v137
	v_exp_f32_e32 v136, v136
	v_add_f32_e32 v138, 1.0, v138
	v_rcp_f32_e32 v140, v138
	v_mul_f32_e32 v138, 0xbfb8aa3b, v139
	v_add_f32_e32 v136, 1.0, v136
	v_rcp_f32_e32 v143, v136
	v_pk_mul_f32 v[136:137], v[70:71], v[2:3] op_sel_hi:[1,0]
	v_exp_f32_e32 v138, v138
	v_mul_f32_e32 v136, 0xbfb8aa3b, v136
	v_exp_f32_e32 v136, v136
	v_add_f32_e32 v138, 1.0, v138
	v_rcp_f32_e32 v141, v138
	v_pk_mul_f32 v[138:139], v[68:69], v[2:3] op_sel_hi:[1,0]
	v_add_f32_e32 v136, 1.0, v136
	v_mul_f32_e32 v2, 0xbfb8aa3b, v138
	v_mul_f32_e32 v138, 0xbfb8aa3b, v139
	v_rcp_f32_e32 v139, v136
	v_mul_f32_e32 v136, 0xbfb8aa3b, v137
	v_exp_f32_e32 v2, v2
	v_exp_f32_e32 v138, v138
	v_exp_f32_e32 v136, v136
	v_add_f32_e32 v2, 1.0, v2
	v_add_f32_e32 v138, 1.0, v138
	v_add_f32_e32 v136, 1.0, v136
	v_rcp_f32_e32 v2, v2
	v_rcp_f32_e32 v138, v138
	v_rcp_f32_e32 v144, v136
	v_lshl_add_u64 v[136:137], v[134:135], 0, v[132:133]
	v_add_co_u32_e32 v136, vcc, s0, v136
	v_cvt_pk_bf16_f32 v132, v140, v141
	v_cvt_pk_bf16_f32 v133, v142, v143
	v_cvt_pk_bf16_f32 v134, v2, v138
	v_cvt_pk_bf16_f32 v135, v139, v144
	v_addc_co_u32_e32 v137, vcc, 0, v137, vcc
	global_store_dwordx4 v[136:137], v[132:135], off offset:512

.LBB0_71:
	s_andn2_b64 vcc, exec, s[0:1]
	s_cbranch_vccnz .LBB0_74
	s_lshl_b32 s0, s48, 8
	s_add_i32 s0, s0, s31
	v_or_b32_e32 v134, s0, v181
	v_ashrrev_i32_e32 v135, 31, v134
	v_lshl_add_u64 v[142:143], v[134:135], 2, s[70:71]
	v_mov_b32_e32 v144, v164
	v_mov_b32_e32 v146, v165
	v_mov_b32_e32 v138, v166
	v_mov_b32_e32 v136, v167
	s_or_b32 s1, s74, s49
	v_or_b32_e32 v2, s1, v242
	s_add_i32 s3, s1, 0xfffff180
	s_add_i32 s4, s0, 0xffffc000
	v_bitop3_b32 v140, s1, 56, v242 bitop3:0xc8
	s_ashr_i32 s1, s3, 6
	v_add_u32_e32 v2, 0xfffff184, v2
	s_ashr_i32 s3, s0, 11
	v_bitop3_b32 v135, s0, v250, v181 bitop3:0xc8
	s_lshr_b32 s4, s4, 4
	v_ashrrev_i32_e32 v139, 6, v2
	v_add_u32_e32 v2, 0x80, v135
	v_mov_b32_e32 v135, s3
	v_mov_b32_e32 v145, s4
	v_cmp_gt_i32_e32 vcc, s20, v134
	v_mov_b64_e32 v[132:133], s[92:93]
	v_or_b32_e32 v137, 4, v140
	v_cndmask_b32_e32 v142, v145, v135, vcc
	v_lshlrev_b32_e32 v143, 1, v142
	v_add_u32_e32 v142, s1, v143
	v_add_u32_e32 v148, v143, v139
	v_ashrrev_i32_e32 v143, 31, v142
	v_lshlrev_b64 v[142:143], 6, v[142:143]
	v_or_b32_e32 v142, v142, v140
	v_cndmask_b32_e32 v2, v244, v2, vcc
	v_ashrrev_i32_e32 v149, 31, v148
	v_mad_u64_u32 v[150:151], s[4:5], v142, s89, v[132:133]
	v_lshlrev_b32_e32 v2, 1, v2
	v_lshlrev_b64 v[148:149], 6, v[148:149]
	v_mad_i32_i24 v151, v143, s89, v151
	v_or_b32_e32 v145, v148, v137
	v_lshl_add_u64 v[142:143], v[150:151], 0, v[2:3]
	s_movk_i32 s17, 0x1000
	v_mad_u64_u32 v[152:153], s[4:5], v145, s89, v[132:133]
	v_add_co_u32_e32 v150, vcc, s17, v142
	v_mad_i32_i24 v153, v149, s89, v153
	s_nop 0
	v_addc_co_u32_e32 v151, vcc, 0, v143, vcc
	s_movk_i32 s16, 0x2000
	v_lshl_add_u64 v[148:149], v[152:153], 0, v[2:3]
	v_add_co_u32_e32 v152, vcc, s16, v142
	s_movk_i32 s21, 0x3000
	s_nop 0
	v_addc_co_u32_e32 v153, vcc, 0, v143, vcc
	v_add_co_u32_e32 v154, vcc, s21, v142
	s_movk_i32 s3, 0x7df
	s_nop 0
	v_addc_co_u32_e32 v155, vcc, 0, v143, vcc
	v_add_co_u32_e32 v156, vcc, s17, v148
	v_or_b32_e32 v141, 16, v134
	s_nop 0
	v_addc_co_u32_e32 v157, vcc, 0, v149, vcc
	v_add_co_u32_e32 v158, vcc, s16, v148
	v_or_b32_e32 v188, 32, v134
	s_nop 0
	v_addc_co_u32_e32 v159, vcc, 0, v149, vcc
	v_or_b32_e32 v189, 48, v134
	s_waitcnt vmcnt(0)
	v_pk_mul_f32 v[162:163], v[128:129], v[144:145] op_sel_hi:[1,0]
	v_pk_mul_f32 v[160:161], v[130:131], v[144:145] op_sel_hi:[1,0]
	v_pk_mul_f32 v[168:169], v[126:127], v[144:145] op_sel_hi:[1,0]
	v_pk_mul_f32 v[144:145], v[124:125], v[144:145] op_sel_hi:[1,0]
	v_cvt_pk_bf16_f32 v2, v162, s0
	v_cvt_pk_bf16_f32 v147, v163, s0
	v_cvt_pk_bf16_f32 v160, v160, s0
	v_cvt_pk_bf16_f32 v161, v161, s0
	v_cvt_pk_bf16_f32 v144, v144, s0
	v_cvt_pk_bf16_f32 v145, v145, s0
	v_cvt_pk_bf16_f32 v162, v168, s0
	global_store_short v[142:143], v2, off
	global_store_short v[150:151], v147, off offset:256
	global_store_short v[152:153], v160, off offset:512
	global_store_short v[154:155], v161, off offset:768
	global_store_short v[148:149], v144, off
	global_store_short v[156:157], v145, off offset:256
	global_store_short v[158:159], v162, off offset:512
	v_add_co_u32_e32 v142, vcc, s21, v148
	v_bitop3_b32 v2, v134, s3, 16 bitop3:0xc8
	s_add_i32 s3, s0, 0xffffc010
	v_cvt_pk_bf16_f32 v163, v169, s0
	v_addc_co_u32_e32 v143, vcc, 0, v149, vcc
	s_lshr_b32 s3, s3, 4
	global_store_short v[142:143], v163, off offset:768
	v_pk_mul_f32 v[142:143], v[122:123], v[146:147] op_sel_hi:[1,0]
	v_pk_mul_f32 v[144:145], v[120:121], v[146:147] op_sel_hi:[1,0]
	v_mov_b32_e32 v147, s3
	v_cmp_gt_i32_e32 vcc, s20, v141
	v_add_u32_e32 v2, 0x80, v2
	v_cvt_pk_bf16_f32 v144, v144, s0
	v_cndmask_b32_e32 v141, v147, v135, vcc
	v_lshlrev_b32_e32 v141, 1, v141
	v_add_u32_e32 v148, s1, v141
	v_ashrrev_i32_e32 v149, 31, v148
	v_lshlrev_b64 v[148:149], 6, v[148:149]
	v_or_b32_e32 v147, v148, v140
	v_cndmask_b32_e32 v2, v244, v2, vcc
	v_mad_u64_u32 v[150:151], s[4:5], v147, s89, v[132:133]
	v_mad_i32_i24 v151, v149, s89, v151
	v_lshlrev_b32_e32 v2, 1, v2
	v_lshl_add_u64 v[148:149], v[150:151], 0, v[2:3]
	global_store_short v[148:149], v144, off
	v_add_co_u32_e32 v144, vcc, s17, v148
	v_cvt_pk_bf16_f32 v147, v145, s0
	s_nop 0
	v_addc_co_u32_e32 v145, vcc, 0, v149, vcc
	global_store_short v[144:145], v147, off offset:256
	v_add_co_u32_e32 v144, vcc, s16, v148
	v_cvt_pk_bf16_f32 v142, v142, s0
	s_nop 0
	v_addc_co_u32_e32 v145, vcc, 0, v149, vcc
	global_store_short v[144:145], v142, off offset:512
	v_add_co_u32_e32 v142, vcc, s21, v148
	v_cvt_pk_bf16_f32 v144, v143, s0
	s_nop 0
	v_addc_co_u32_e32 v143, vcc, 0, v149, vcc
	global_store_short v[142:143], v144, off offset:768
	v_pk_mul_f32 v[142:143], v[118:119], v[146:147] op_sel_hi:[1,0]
	v_pk_mul_f32 v[144:145], v[116:117], v[146:147] op_sel_hi:[1,0]
	v_add_u32_e32 v146, v141, v139
	v_ashrrev_i32_e32 v147, 31, v146
	v_lshlrev_b64 v[146:147], 6, v[146:147]
	v_or_b32_e32 v141, v146, v137
	v_mad_u64_u32 v[148:149], s[4:5], v141, s89, v[132:133]
	v_mad_i32_i24 v149, v147, s89, v149
	v_lshl_add_u64 v[146:147], v[148:149], 0, v[2:3]
	v_cvt_pk_bf16_f32 v2, v144, s0
	v_add_co_u32_e32 v144, vcc, s17, v146
	global_store_short v[146:147], v2, off
	v_cvt_pk_bf16_f32 v2, v145, s0
	v_addc_co_u32_e32 v145, vcc, 0, v147, vcc
	global_store_short v[144:145], v2, off offset:256
	v_add_co_u32_e32 v144, vcc, s16, v146
	v_cvt_pk_bf16_f32 v2, v142, s0
	s_nop 0
	v_addc_co_u32_e32 v145, vcc, 0, v147, vcc
	v_add_co_u32_e32 v142, vcc, s21, v146
	global_store_short v[144:145], v2, off offset:512
	v_cvt_pk_bf16_f32 v2, v143, s0
	v_addc_co_u32_e32 v143, vcc, 0, v147, vcc
	s_movk_i32 s3, 0x7ef
	global_store_short v[142:143], v2, off offset:768
	v_bitop3_b32 v2, v134, s3, 32 bitop3:0xc8
	s_add_i32 s3, s0, 0xffffc020
	s_lshr_b32 s3, s3, 4
	v_mov_b32_e32 v141, s3
	v_cmp_gt_i32_e32 vcc, s20, v188
	v_add_u32_e32 v2, 0x80, v2
	v_pk_mul_f32 v[144:145], v[112:113], v[138:139] op_sel_hi:[1,0]
	v_cndmask_b32_e32 v141, v141, v135, vcc
	v_lshlrev_b32_e32 v141, 1, v141
	v_add_u32_e32 v146, s1, v141
	v_ashrrev_i32_e32 v147, 31, v146
	v_lshlrev_b64 v[146:147], 6, v[146:147]
	v_or_b32_e32 v146, v146, v140
	v_cndmask_b32_e32 v2, v244, v2, vcc
	v_mad_u64_u32 v[148:149], s[4:5], v146, s89, v[132:133]
	v_mad_i32_i24 v149, v147, s89, v149
	v_lshlrev_b32_e32 v2, 1, v2
	v_lshl_add_u64 v[146:147], v[148:149], 0, v[2:3]
	v_cvt_pk_bf16_f32 v144, v144, s0
	global_store_short v[146:147], v144, off
	v_add_co_u32_e32 v144, vcc, s17, v146
	v_cvt_pk_bf16_f32 v148, v145, s0
	s_nop 0
	v_addc_co_u32_e32 v145, vcc, 0, v147, vcc
	v_pk_mul_f32 v[142:143], v[114:115], v[138:139] op_sel_hi:[1,0]
	global_store_short v[144:145], v148, off offset:256
	v_add_co_u32_e32 v144, vcc, s16, v146
	v_cvt_pk_bf16_f32 v142, v142, s0
	s_nop 0
	v_addc_co_u32_e32 v145, vcc, 0, v147, vcc
	global_store_short v[144:145], v142, off offset:512
	v_add_co_u32_e32 v142, vcc, s21, v146
	v_add_u32_e32 v146, v141, v139
	v_cvt_pk_bf16_f32 v144, v143, s0
	v_addc_co_u32_e32 v143, vcc, 0, v147, vcc
	v_ashrrev_i32_e32 v147, 31, v146
	v_lshlrev_b64 v[146:147], 6, v[146:147]
	global_store_short v[142:143], v144, off offset:768
	v_pk_mul_f32 v[142:143], v[110:111], v[138:139] op_sel_hi:[1,0]
	v_pk_mul_f32 v[144:145], v[108:109], v[138:139] op_sel_hi:[1,0]
	v_or_b32_e32 v138, v146, v137
	v_mad_u64_u32 v[148:149], s[4:5], v138, s89, v[132:133]
	v_mad_i32_i24 v149, v147, s89, v149
	v_lshl_add_u64 v[146:147], v[148:149], 0, v[2:3]
	v_cvt_pk_bf16_f32 v2, v144, s0
	v_add_co_u32_e32 v144, vcc, s17, v146
	global_store_short v[146:147], v2, off
	v_cvt_pk_bf16_f32 v2, v145, s0
	v_addc_co_u32_e32 v145, vcc, 0, v147, vcc
	global_store_short v[144:145], v2, off offset:256
	v_add_co_u32_e32 v144, vcc, s16, v146
	v_cvt_pk_bf16_f32 v2, v142, s0
	s_nop 0
	v_addc_co_u32_e32 v145, vcc, 0, v147, vcc
	v_add_co_u32_e32 v142, vcc, s21, v146
	global_store_short v[144:145], v2, off offset:512
	v_cvt_pk_bf16_f32 v2, v143, s0
	v_addc_co_u32_e32 v143, vcc, 0, v147, vcc
	s_movk_i32 s3, 0x7ff
	global_store_short v[142:143], v2, off offset:768
	v_bitop3_b32 v2, v134, s3, 48 bitop3:0xc8
	s_add_i32 s3, s0, 0xffffc030
	s_lshr_b32 s3, s3, 4
	v_mov_b32_e32 v134, s3
	v_cmp_gt_i32_e32 vcc, s20, v189
	v_add_u32_e32 v2, 0x80, v2
	v_pk_mul_f32 v[144:145], v[104:105], v[136:137] op_sel_hi:[1,0]
	v_cndmask_b32_e32 v134, v134, v135, vcc
	v_lshlrev_b32_e32 v138, 1, v134
	v_add_u32_e32 v134, s1, v138
	v_ashrrev_i32_e32 v135, 31, v134
	v_lshlrev_b64 v[134:135], 6, v[134:135]
	v_or_b32_e32 v134, v134, v140
	v_cndmask_b32_e32 v2, v244, v2, vcc
	v_mad_u64_u32 v[146:147], s[4:5], v134, s89, v[132:133]
	v_mad_i32_i24 v147, v135, s89, v147
	v_lshlrev_b32_e32 v2, 1, v2
	v_lshl_add_u64 v[134:135], v[146:147], 0, v[2:3]
	v_cvt_pk_bf16_f32 v141, v144, s0
	v_add_co_u32_e32 v144, vcc, s17, v134
	global_store_short v[134:135], v141, off
	v_cvt_pk_bf16_f32 v141, v145, s0
	v_addc_co_u32_e32 v145, vcc, 0, v135, vcc
	v_pk_mul_f32 v[142:143], v[106:107], v[136:137] op_sel_hi:[1,0]
	global_store_short v[144:145], v141, off offset:256
	v_add_co_u32_e32 v144, vcc, s16, v134
	v_cvt_pk_bf16_f32 v141, v142, s0
	s_nop 0
	v_addc_co_u32_e32 v145, vcc, 0, v135, vcc
	global_store_short v[144:145], v141, off offset:512
	v_add_u32_e32 v144, v138, v139
	v_add_co_u32_e32 v134, vcc, s21, v134
	v_ashrrev_i32_e32 v145, 31, v144
	v_cvt_pk_bf16_f32 v141, v143, s0
	v_addc_co_u32_e32 v135, vcc, 0, v135, vcc
	v_lshlrev_b64 v[144:145], 6, v[144:145]
	global_store_short v[134:135], v141, off offset:768
	v_pk_mul_f32 v[134:135], v[102:103], v[136:137] op_sel_hi:[1,0]
	v_pk_mul_f32 v[142:143], v[100:101], v[136:137] op_sel_hi:[1,0]
	v_or_b32_e32 v136, v144, v137
	v_mad_u64_u32 v[132:133], s[4:5], v136, s89, v[132:133]
	v_mad_i32_i24 v133, v145, s89, v133
	v_lshl_add_u64 v[132:133], v[132:133], 0, v[2:3]
	v_cvt_pk_bf16_f32 v2, v142, s0
	v_add_co_u32_e32 v142, vcc, 0x1000, v132
	global_store_short v[132:133], v2, off
	v_cvt_pk_bf16_f32 v2, v143, s0
	v_addc_co_u32_e32 v143, vcc, 0, v133, vcc
	global_store_short v[142:143], v2, off offset:256
	v_add_co_u32_e32 v142, vcc, 0x2000, v132
	v_cvt_pk_bf16_f32 v2, v134, s0
	s_nop 0
	v_addc_co_u32_e32 v143, vcc, 0, v133, vcc
	v_add_co_u32_e32 v132, vcc, 0x3000, v132
	global_store_short v[142:143], v2, off offset:512
	v_cvt_pk_bf16_f32 v2, v135, s0
	v_addc_co_u32_e32 v133, vcc, 0, v133, vcc
	s_cmp_eq_u32 s48, 64
	global_store_short v[132:133], v2, off offset:768
	s_cbranch_scc1 .LBB0_74
	s_add_i32 s3, s0, 0x80
	v_or_b32_e32 v134, s3, v181
	v_ashrrev_i32_e32 v135, 31, v134
	v_lshl_add_u64 v[142:143], v[134:135], 2, s[70:71]
	v_mov_b32_e32 v138, v246
	v_mov_b32_e32 v144, v247
	s_add_i32 s4, s0, 0xffffc080
	s_ashr_i32 s5, s3, 11
	v_bitop3_b32 v2, s3, v250, v181 bitop3:0xc8
	s_lshr_b32 s3, s4, 4
	v_mov_b32_e32 v136, s3
	v_mov_b32_e32 v197, s5
	v_cmp_gt_i32_e32 vcc, s20, v134
	v_mov_b64_e32 v[132:133], s[92:93]
	v_add_u32_e32 v2, 0x80, v2
	v_cndmask_b32_e32 v147, v136, v197, vcc
	v_mov_b32_e32 v146, v248
	v_mov_b32_e32 v136, v249
	v_lshlrev_b32_e32 v143, 1, v147
	v_add_u32_e32 v142, s1, v143
	v_add_u32_e32 v148, v143, v139
	v_ashrrev_i32_e32 v143, 31, v142
	v_lshlrev_b64 v[142:143], 6, v[142:143]
	v_or_b32_e32 v142, v142, v140
	v_cndmask_b32_e32 v2, v244, v2, vcc
	v_ashrrev_i32_e32 v149, 31, v148
	v_mad_u64_u32 v[150:151], s[4:5], v142, s89, v[132:133]
	v_lshlrev_b32_e32 v2, 1, v2
	v_lshlrev_b64 v[148:149], 6, v[148:149]
	v_mad_i32_i24 v151, v143, s89, v151
	v_or_b32_e32 v147, v148, v137
	v_lshl_add_u64 v[142:143], v[150:151], 0, v[2:3]
	v_mad_u64_u32 v[152:153], s[4:5], v147, s89, v[132:133]
	v_add_co_u32_e32 v150, vcc, s17, v142
	v_mad_i32_i24 v153, v149, s89, v153
	s_nop 0
	v_addc_co_u32_e32 v151, vcc, 0, v143, vcc
	v_lshl_add_u64 v[148:149], v[152:153], 0, v[2:3]
	v_add_co_u32_e32 v152, vcc, s16, v142
	s_movk_i32 s3, 0x7df
	s_nop 0
	v_addc_co_u32_e32 v153, vcc, 0, v143, vcc
	v_add_co_u32_e32 v154, vcc, s21, v142
	v_bitop3_b32 v145, v134, s3, 16 bitop3:0xc8
	s_nop 0
	v_addc_co_u32_e32 v155, vcc, 0, v143, vcc
	v_add_co_u32_e32 v156, vcc, s17, v148
	s_add_i32 s3, s0, 0xffffc090
	s_nop 0
	v_addc_co_u32_e32 v157, vcc, 0, v149, vcc
	v_add_co_u32_e32 v158, vcc, s16, v148
	v_or_b32_e32 v135, 16, v134
	s_nop 0
	v_addc_co_u32_e32 v159, vcc, 0, v149, vcc
	v_add_co_u32_e32 v160, vcc, s21, v148
	s_lshr_b32 s3, s3, 4
	s_nop 0
	v_addc_co_u32_e32 v161, vcc, 0, v149, vcc
	v_cmp_gt_i32_e32 vcc, s20, v135
	v_or_b32_e32 v141, 32, v134
	v_or_b32_e32 v196, 48, v134
	s_waitcnt vmcnt(0)
	v_pk_mul_f32 v[168:169], v[96:97], v[138:139] op_sel_hi:[1,0]
	v_pk_mul_f32 v[162:163], v[98:99], v[138:139] op_sel_hi:[1,0]
	v_pk_mul_f32 v[188:189], v[94:95], v[138:139] op_sel_hi:[1,0]
	v_pk_mul_f32 v[190:191], v[92:93], v[138:139] op_sel_hi:[1,0]
	v_cvt_pk_bf16_f32 v2, v168, s0
	v_cvt_pk_bf16_f32 v138, v169, s0
	v_cvt_pk_bf16_f32 v147, v162, s0
	v_cvt_pk_bf16_f32 v162, v163, s0
	v_cvt_pk_bf16_f32 v163, v190, s0
	v_cvt_pk_bf16_f32 v168, v191, s0
	v_cvt_pk_bf16_f32 v169, v188, s0
	v_cvt_pk_bf16_f32 v188, v189, s0
	global_store_short v[142:143], v2, off
	global_store_short v[150:151], v138, off offset:256
	global_store_short v[152:153], v147, off offset:512
	global_store_short v[154:155], v162, off offset:768
	global_store_short v[148:149], v163, off
	global_store_short v[156:157], v168, off offset:256
	global_store_short v[158:159], v169, off offset:512
	global_store_short v[160:161], v188, off offset:768
	v_mov_b32_e32 v138, s3
	v_cndmask_b32_e32 v135, v138, v197, vcc
	v_lshlrev_b32_e32 v135, 1, v135
	v_add_u32_e32 v142, s1, v135
	v_ashrrev_i32_e32 v143, 31, v142
	v_lshlrev_b64 v[142:143], 6, v[142:143]
	v_add_u32_e32 v2, 0x80, v145
	v_or_b32_e32 v138, v142, v140
	v_cndmask_b32_e32 v2, v244, v2, vcc
	v_mad_u64_u32 v[148:149], s[4:5], v138, s89, v[132:133]
	v_mad_i32_i24 v149, v143, s89, v149
	v_lshlrev_b32_e32 v2, 1, v2
	v_pk_mul_f32 v[194:195], v[88:89], v[144:145] op_sel_hi:[1,0]
	v_lshl_add_u64 v[142:143], v[148:149], 0, v[2:3]
	v_cvt_pk_bf16_f32 v138, v194, s0
	v_add_co_u32_e32 v148, vcc, s17, v142
	global_store_short v[142:143], v138, off
	v_cvt_pk_bf16_f32 v138, v195, s0
	v_addc_co_u32_e32 v149, vcc, 0, v143, vcc
	v_pk_mul_f32 v[192:193], v[90:91], v[144:145] op_sel_hi:[1,0]
	global_store_short v[148:149], v138, off offset:256
	v_add_co_u32_e32 v148, vcc, s16, v142
	v_cvt_pk_bf16_f32 v138, v192, s0
	s_nop 0
	v_addc_co_u32_e32 v149, vcc, 0, v143, vcc
	global_store_short v[148:149], v138, off offset:512
	v_add_u32_e32 v148, v135, v139
	v_ashrrev_i32_e32 v149, 31, v148
	v_lshlrev_b64 v[148:149], 6, v[148:149]
	v_or_b32_e32 v135, v148, v137
	v_add_co_u32_e32 v142, vcc, s21, v142
	v_mad_u64_u32 v[150:151], s[4:5], v135, s89, v[132:133]
	v_cvt_pk_bf16_f32 v138, v193, s0
	v_addc_co_u32_e32 v143, vcc, 0, v143, vcc
	v_mad_i32_i24 v151, v149, s89, v151
	global_store_short v[142:143], v138, off offset:768
	v_pk_mul_f32 v[142:143], v[86:87], v[144:145] op_sel_hi:[1,0]
	v_pk_mul_f32 v[144:145], v[84:85], v[144:145] op_sel_hi:[1,0]
	v_lshl_add_u64 v[148:149], v[150:151], 0, v[2:3]
	v_cvt_pk_bf16_f32 v2, v144, s0
	v_add_co_u32_e32 v144, vcc, s17, v148
	global_store_short v[148:149], v2, off
	v_cvt_pk_bf16_f32 v2, v145, s0
	v_addc_co_u32_e32 v145, vcc, 0, v149, vcc
	global_store_short v[144:145], v2, off offset:256
	v_add_co_u32_e32 v144, vcc, s16, v148
	v_cvt_pk_bf16_f32 v2, v142, s0
	s_nop 0
	v_addc_co_u32_e32 v145, vcc, 0, v149, vcc
	v_add_co_u32_e32 v142, vcc, s21, v148
	global_store_short v[144:145], v2, off offset:512
	v_cvt_pk_bf16_f32 v2, v143, s0
	v_addc_co_u32_e32 v143, vcc, 0, v149, vcc
	s_movk_i32 s3, 0x7ef
	global_store_short v[142:143], v2, off offset:768
	v_bitop3_b32 v2, v134, s3, 32 bitop3:0xc8
	s_add_i32 s3, s0, 0xffffc0a0
	s_lshr_b32 s3, s3, 4
	v_mov_b32_e32 v135, s3
	v_cmp_gt_i32_e32 vcc, s20, v141
	v_add_u32_e32 v2, 0x80, v2
	v_pk_mul_f32 v[144:145], v[80:81], v[146:147] op_sel_hi:[1,0]
	v_cndmask_b32_e32 v135, v135, v197, vcc
	v_lshlrev_b32_e32 v135, 1, v135
	v_add_u32_e32 v148, s1, v135
	v_ashrrev_i32_e32 v149, 31, v148
	v_lshlrev_b64 v[148:149], 6, v[148:149]
	v_or_b32_e32 v138, v148, v140
	v_cndmask_b32_e32 v2, v244, v2, vcc
	v_mad_u64_u32 v[150:151], s[4:5], v138, s89, v[132:133]
	v_mad_i32_i24 v151, v149, s89, v151
	v_lshlrev_b32_e32 v2, 1, v2
	v_lshl_add_u64 v[148:149], v[150:151], 0, v[2:3]
	v_cvt_pk_bf16_f32 v138, v144, s0
	v_add_co_u32_e32 v144, vcc, s17, v148
	global_store_short v[148:149], v138, off
	v_cvt_pk_bf16_f32 v138, v145, s0
	v_addc_co_u32_e32 v145, vcc, 0, v149, vcc
	global_store_short v[144:145], v138, off offset:256
	v_add_co_u32_e32 v144, vcc, s16, v148
	v_pk_mul_f32 v[142:143], v[82:83], v[146:147] op_sel_hi:[1,0]
	s_nop 0
	v_addc_co_u32_e32 v145, vcc, 0, v149, vcc
	v_cvt_pk_bf16_f32 v138, v142, s0
	v_add_co_u32_e32 v142, vcc, s21, v148
	global_store_short v[144:145], v138, off offset:512
	v_cvt_pk_bf16_f32 v138, v143, s0
	v_addc_co_u32_e32 v143, vcc, 0, v149, vcc
	global_store_short v[142:143], v138, off offset:768
	v_pk_mul_f32 v[142:143], v[78:79], v[146:147] op_sel_hi:[1,0]
	v_pk_mul_f32 v[144:145], v[76:77], v[146:147] op_sel_hi:[1,0]
	v_add_u32_e32 v146, v135, v139
	v_ashrrev_i32_e32 v147, 31, v146
	v_lshlrev_b64 v[146:147], 6, v[146:147]
	v_or_b32_e32 v135, v146, v137
	v_mad_u64_u32 v[148:149], s[4:5], v135, s89, v[132:133]
	v_mad_i32_i24 v149, v147, s89, v149
	v_lshl_add_u64 v[146:147], v[148:149], 0, v[2:3]
	v_cvt_pk_bf16_f32 v2, v144, s0
	v_add_co_u32_e32 v144, vcc, s17, v146
	global_store_short v[146:147], v2, off
	v_cvt_pk_bf16_f32 v2, v145, s0
	v_addc_co_u32_e32 v145, vcc, 0, v147, vcc
	global_store_short v[144:145], v2, off offset:256
	v_add_co_u32_e32 v144, vcc, s16, v146
	v_cvt_pk_bf16_f32 v2, v142, s0
	s_nop 0
	v_addc_co_u32_e32 v145, vcc, 0, v147, vcc
	global_store_short v[144:145], v2, off offset:512
	v_cvt_pk_bf16_f32 v2, v143, s0
	v_add_co_u32_e32 v142, vcc, s21, v146
	s_addk_i32 s0, 0xc0b0
	s_nop 0
	v_addc_co_u32_e32 v143, vcc, 0, v147, vcc
	s_movk_i32 s3, 0x7ff
	s_lshr_b32 s0, s0, 4
	global_store_short v[142:143], v2, off offset:768
	v_bitop3_b32 v2, v134, s3, 48 bitop3:0xc8
	v_mov_b32_e32 v134, s0
	v_cmp_gt_i32_e32 vcc, s20, v196
	v_add_u32_e32 v2, 0x80, v2
	v_pk_mul_f32 v[144:145], v[72:73], v[136:137] op_sel_hi:[1,0]
	v_cndmask_b32_e32 v134, v134, v197, vcc
	v_lshlrev_b32_e32 v138, 1, v134
	v_add_u32_e32 v134, s1, v138
	v_ashrrev_i32_e32 v135, 31, v134
	v_lshlrev_b64 v[134:135], 6, v[134:135]
	v_or_b32_e32 v134, v134, v140
	v_cndmask_b32_e32 v2, v244, v2, vcc
	v_mad_u64_u32 v[140:141], s[0:1], v134, s89, v[132:133]
	v_mad_i32_i24 v141, v135, s89, v141
	v_lshlrev_b32_e32 v2, 1, v2
	v_lshl_add_u64 v[134:135], v[140:141], 0, v[2:3]
	v_cvt_pk_bf16_f32 v140, v144, s0
	global_store_short v[134:135], v140, off
	v_add_co_u32_e32 v140, vcc, s17, v134
	v_cvt_pk_bf16_f32 v144, v145, s0
	s_nop 0
	v_addc_co_u32_e32 v141, vcc, 0, v135, vcc
	global_store_short v[140:141], v144, off offset:256
	v_add_co_u32_e32 v140, vcc, s16, v134
	v_pk_mul_f32 v[142:143], v[74:75], v[136:137] op_sel_hi:[1,0]
	s_nop 0
	v_addc_co_u32_e32 v141, vcc, 0, v135, vcc
	v_add_u32_e32 v138, v138, v139
	v_cvt_pk_bf16_f32 v142, v142, s0
	v_add_co_u32_e32 v134, vcc, s21, v134
	v_ashrrev_i32_e32 v139, 31, v138
	global_store_short v[140:141], v142, off offset:512
	v_cvt_pk_bf16_f32 v140, v143, s0
	v_addc_co_u32_e32 v135, vcc, 0, v135, vcc
	v_lshlrev_b64 v[138:139], 6, v[138:139]
	global_store_short v[134:135], v140, off offset:768
	v_pk_mul_f32 v[134:135], v[70:71], v[136:137] op_sel_hi:[1,0]
	v_pk_mul_f32 v[140:141], v[68:69], v[136:137] op_sel_hi:[1,0]
	v_or_b32_e32 v136, v138, v137
	v_mad_u64_u32 v[132:133], s[0:1], v136, s89, v[132:133]
	v_mad_i32_i24 v133, v139, s89, v133
	v_lshl_add_u64 v[132:133], v[132:133], 0, v[2:3]
	v_cvt_pk_bf16_f32 v2, v140, s0
	v_add_co_u32_e32 v136, vcc, 0x1000, v132
	global_store_short v[132:133], v2, off
	v_cvt_pk_bf16_f32 v2, v141, s0
	v_addc_co_u32_e32 v137, vcc, 0, v133, vcc
	global_store_short v[136:137], v2, off offset:256
	v_add_co_u32_e32 v136, vcc, 0x2000, v132
	v_cvt_pk_bf16_f32 v2, v134, s0
	s_nop 0
	v_addc_co_u32_e32 v137, vcc, 0, v133, vcc
	v_add_co_u32_e32 v132, vcc, 0x3000, v132
	global_store_short v[136:137], v2, off offset:512
	v_cvt_pk_bf16_f32 v2, v135, s0
	v_addc_co_u32_e32 v133, vcc, 0, v133, vcc
	global_store_short v[132:133], v2, off offset:768

.LBB0_75:
	s_andn2_b64 vcc, exec, s[0:1]
	s_cbranch_vccnz .LBB0_147
	s_cmp_gt_i32 s2, 4
	s_mov_b64 s[0:1], -1
	s_cbranch_scc0 .LBB0_112
	s_lshl_b32 s0, s48, 8
	v_add_u32_e32 v190, s0, v241
	v_ashrrev_i32_e32 v191, 31, v190
	v_lshl_add_u64 v[152:153], v[190:191], 2, s[70:71]
	v_mov_b32_e32 v188, v164
	s_movk_i32 s0, 0x7cf
	v_and_or_b32 v2, v190, s0, 16
	v_cmp_gt_i32_e32 vcc, s20, v190
	v_mov_b32_e32 v133, 0
	v_mov_b32_e32 v132, 1.0
	v_cndmask_b32_e32 v2, v181, v2, vcc
	v_lshlrev_b32_e32 v2, 6, v2
	v_lshl_add_u64 v[136:137], s[84:85], 0, v[2:3]
	v_mov_b32_e32 v140, 1.0
	v_mov_b32_e32 v141, 0
	v_mov_b32_e32 v142, 1.0
	v_mov_b32_e32 v143, 0
	s_and_saveexec_b64 s[0:1], s[38:39]
	s_cbranch_execz .LBB0_79
	v_lshlrev_b32_e32 v2, 2, v170
	v_lshl_add_u64 v[134:135], v[136:137], 0, v[2:3]
	global_load_dwordx4 v[140:143], v[134:135], off

.LBB0_81:
	s_or_b64 exec, exec, s[0:1]
	v_mov_b32_e32 v194, v165
	s_movk_i32 s0, 0x7df
	v_or_b32_e32 v192, 16, v190
	v_bitop3_b32 v2, v190, s0, 16 bitop3:0xc8
	v_add_u32_e32 v2, 16, v2
	v_cmp_gt_i32_e32 vcc, s20, v192
	v_mov_b32_e32 v137, 0
	v_mov_b32_e32 v136, 1.0
	v_cndmask_b32_e32 v2, v181, v2, vcc
	v_lshlrev_b32_e32 v2, 6, v2
	v_lshl_add_u64 v[144:145], s[84:85], 0, v[2:3]
	v_mov_b32_e32 v148, 1.0
	v_mov_b32_e32 v149, 0
	v_mov_b32_e32 v150, 1.0
	v_mov_b32_e32 v151, 0
	s_and_saveexec_b64 s[0:1], s[38:39]
	s_cbranch_execz .LBB0_83
	v_lshlrev_b32_e32 v2, 2, v170
	v_lshl_add_u64 v[138:139], v[144:145], 0, v[2:3]
	global_load_dwordx4 v[148:151], v[138:139], off

.LBB0_85:
	s_or_b64 exec, exec, s[0:1]
	v_mov_b32_e32 v198, v166
	v_or_b32_e32 v196, 32, v190
	s_movk_i32 s0, 0x7ef
	v_and_or_b32 v2, v196, s0, 16
	v_cmp_gt_i32_e32 vcc, s20, v196
	v_mov_b32_e32 v145, 0
	v_mov_b32_e32 v144, 1.0
	v_cndmask_b32_e32 v2, v181, v2, vcc
	v_lshlrev_b32_e32 v2, 6, v2
	v_lshl_add_u64 v[154:155], s[84:85], 0, v[2:3]
	v_mov_b32_e32 v156, 1.0
	v_mov_b32_e32 v157, 0
	v_mov_b32_e32 v158, 1.0
	v_mov_b32_e32 v159, 0
	s_and_saveexec_b64 s[0:1], s[38:39]
	s_cbranch_execz .LBB0_87
	v_lshlrev_b32_e32 v2, 2, v170
	v_lshl_add_u64 v[146:147], v[154:155], 0, v[2:3]
	global_load_dwordx4 v[156:159], v[146:147], off

.LBB0_89:
	s_or_b64 exec, exec, s[0:1]
	v_mov_b32_e32 v202, v167
	s_movk_i32 s0, 0x7ff
	v_or_b32_e32 v200, 48, v190
	v_bitop3_b32 v2, v190, s0, 48 bitop3:0xc8
	v_add_u32_e32 v2, 16, v2
	v_cmp_gt_i32_e32 vcc, s20, v200
	v_mov_b32_e32 v153, 0
	v_mov_b32_e32 v152, 1.0
	v_cndmask_b32_e32 v2, v181, v2, vcc
	v_lshlrev_b32_e32 v2, 6, v2
	v_lshl_add_u64 v[204:205], s[84:85], 0, v[2:3]
	v_mov_b32_e32 v160, 1.0
	v_mov_b32_e32 v161, 0
	v_mov_b32_e32 v162, 1.0
	v_mov_b32_e32 v163, 0
	s_and_saveexec_b64 s[0:1], s[38:39]
	s_cbranch_execz .LBB0_91
	v_lshlrev_b32_e32 v2, 2, v170
	v_lshl_add_u64 v[154:155], v[204:205], 0, v[2:3]
	global_load_dwordx4 v[160:163], v[154:155], off

.LBB0_93:
	s_or_b64 exec, exec, s[0:1]
	s_waitcnt vmcnt(0)
	v_pk_mul_f32 v[206:207], v[128:129], v[188:189] op_sel_hi:[1,0]
	v_mov_b32_e32 v2, v141
	v_pk_mul_f32 v[204:205], v[130:131], v[188:189] op_sel_hi:[1,0]
	v_pk_mul_f32 v[208:209], v[206:207], v[2:3] op_sel:[1,0] op_sel_hi:[0,0]
	v_mov_b32_e32 v2, v143
	v_pk_fma_f32 v[210:211], v[206:207], v[140:141], v[208:209] neg_lo:[0,0,1] neg_hi:[0,0,1]
	v_pk_fma_f32 v[140:141], v[206:207], v[140:141], v[208:209] op_sel_hi:[1,0,1]
	v_pk_mul_f32 v[206:207], v[204:205], v[2:3] op_sel:[1,0] op_sel_hi:[0,0]
	v_pk_fma_f32 v[208:209], v[204:205], v[142:143], v[206:207] neg_lo:[0,0,1] neg_hi:[0,0,1]
	v_pk_fma_f32 v[142:143], v[204:205], v[142:143], v[206:207] op_sel_hi:[1,0,1]
	v_pk_mul_f32 v[204:205], v[126:127], v[188:189] op_sel_hi:[1,0]
	v_pk_mul_f32 v[188:189], v[124:125], v[188:189] op_sel_hi:[1,0]
	v_mov_b32_e32 v2, v133
	v_pk_mul_f32 v[206:207], v[188:189], v[2:3] op_sel:[1,0] op_sel_hi:[0,0]
	v_mov_b32_e32 v2, v135
	v_or_b32_e32 v168, s74, v178
	v_pk_fma_f32 v[220:221], v[188:189], v[132:133], v[206:207] neg_lo:[0,0,1] neg_hi:[0,0,1]
	v_pk_fma_f32 v[206:207], v[188:189], v[132:133], v[206:207] op_sel_hi:[1,0,1]
	v_pk_mul_f32 v[132:133], v[204:205], v[2:3] op_sel:[1,0] op_sel_hi:[0,0]
	v_ashrrev_i32_e32 v169, 31, v168
	v_pk_fma_f32 v[222:223], v[204:205], v[134:135], v[132:133] neg_lo:[0,0,1] neg_hi:[0,0,1]
	v_pk_fma_f32 v[134:135], v[204:205], v[134:135], v[132:133] op_sel_hi:[1,0,1]
	v_lshlrev_b64 v[132:133], 8, v[190:191]
	v_lshl_add_u64 v[132:133], s[94:95], 0, v[132:133]
	v_lshlrev_b64 v[188:189], 1, v[168:169]
	v_lshl_add_u64 v[168:169], v[132:133], 0, v[188:189]
	s_mov_b32 s0, 0x949e000
	v_add_co_u32_e32 v140, vcc, s0, v168
	v_cvt_pk_bf16_f32 v132, v210, v141
	v_cvt_pk_bf16_f32 v133, v208, v143
	v_cvt_pk_bf16_f32 v134, v220, v207
	v_cvt_pk_bf16_f32 v135, v222, v135
	v_addc_co_u32_e32 v141, vcc, 0, v169, vcc
	global_store_dwordx4 v[140:141], v[132:135], off offset:1024
	v_mov_b32_e32 v2, v149
	v_ashrrev_i32_e32 v193, 31, v192
	v_pk_mul_f32 v[134:135], v[120:121], v[194:195] op_sel_hi:[1,0]
	v_pk_mul_f32 v[132:133], v[122:123], v[194:195] op_sel_hi:[1,0]
	v_pk_mul_f32 v[140:141], v[134:135], v[2:3] op_sel:[1,0] op_sel_hi:[0,0]
	v_mov_b32_e32 v2, v151
	v_pk_fma_f32 v[142:143], v[134:135], v[148:149], v[140:141] neg_lo:[0,0,1] neg_hi:[0,0,1]
	v_pk_fma_f32 v[134:135], v[134:135], v[148:149], v[140:141] op_sel_hi:[1,0,1]
	v_pk_mul_f32 v[140:141], v[132:133], v[2:3] op_sel:[1,0] op_sel_hi:[0,0]
	v_pk_fma_f32 v[148:149], v[132:133], v[150:151], v[140:141] neg_lo:[0,0,1] neg_hi:[0,0,1]
	v_pk_fma_f32 v[132:133], v[132:133], v[150:151], v[140:141] op_sel_hi:[1,0,1]
	v_pk_mul_f32 v[150:151], v[116:117], v[194:195] op_sel_hi:[1,0]
	v_mov_b32_e32 v2, v137
	v_pk_mul_f32 v[140:141], v[118:119], v[194:195] op_sel_hi:[1,0]
	v_pk_mul_f32 v[168:169], v[150:151], v[2:3] op_sel:[1,0] op_sel_hi:[0,0]
	v_mov_b32_e32 v2, v139
	v_pk_fma_f32 v[194:195], v[150:151], v[136:137], v[168:169] neg_lo:[0,0,1] neg_hi:[0,0,1]
	v_pk_fma_f32 v[136:137], v[150:151], v[136:137], v[168:169] op_sel_hi:[1,0,1]
	v_pk_mul_f32 v[150:151], v[140:141], v[2:3] op_sel:[1,0] op_sel_hi:[0,0]
	v_pk_fma_f32 v[168:169], v[140:141], v[138:139], v[150:151] neg_lo:[0,0,1] neg_hi:[0,0,1]
	v_pk_fma_f32 v[138:139], v[140:141], v[138:139], v[150:151] op_sel_hi:[1,0,1]
	v_lshlrev_b64 v[140:141], 8, v[192:193]
	v_lshl_add_u64 v[140:141], s[94:95], 0, v[140:141]
	v_lshl_add_u64 v[140:141], v[140:141], 0, v[188:189]
	v_add_co_u32_e32 v136, vcc, s0, v140
	v_cvt_pk_bf16_f32 v132, v142, v135
	v_cvt_pk_bf16_f32 v133, v148, v133
	v_cvt_pk_bf16_f32 v134, v194, v137
	v_cvt_pk_bf16_f32 v135, v168, v139
	v_addc_co_u32_e32 v137, vcc, 0, v141, vcc
	global_store_dwordx4 v[136:137], v[132:135], off offset:1024
	v_mov_b32_e32 v2, v157
	v_pk_mul_f32 v[142:143], v[108:109], v[198:199] op_sel_hi:[1,0]
	v_pk_mul_f32 v[134:135], v[112:113], v[198:199] op_sel_hi:[1,0]
	v_pk_mul_f32 v[132:133], v[114:115], v[198:199] op_sel_hi:[1,0]
	v_pk_mul_f32 v[136:137], v[134:135], v[2:3] op_sel:[1,0] op_sel_hi:[0,0]
	v_mov_b32_e32 v2, v159
	v_pk_fma_f32 v[138:139], v[134:135], v[156:157], v[136:137] neg_lo:[0,0,1] neg_hi:[0,0,1]
	v_pk_fma_f32 v[134:135], v[134:135], v[156:157], v[136:137] op_sel_hi:[1,0,1]
	v_pk_mul_f32 v[136:137], v[132:133], v[2:3] op_sel:[1,0] op_sel_hi:[0,0]
	v_mov_b32_e32 v2, v145
	v_pk_fma_f32 v[140:141], v[132:133], v[158:159], v[136:137] neg_lo:[0,0,1] neg_hi:[0,0,1]
	v_pk_fma_f32 v[132:133], v[132:133], v[158:159], v[136:137] op_sel_hi:[1,0,1]
	v_pk_mul_f32 v[136:137], v[110:111], v[198:199] op_sel_hi:[1,0]
	v_pk_mul_f32 v[148:149], v[142:143], v[2:3] op_sel:[1,0] op_sel_hi:[0,0]
	v_mov_b32_e32 v2, v147
	v_ashrrev_i32_e32 v197, 31, v196
	v_pk_fma_f32 v[150:151], v[142:143], v[144:145], v[148:149] neg_lo:[0,0,1] neg_hi:[0,0,1]
	v_pk_fma_f32 v[142:143], v[142:143], v[144:145], v[148:149] op_sel_hi:[1,0,1]
	v_pk_mul_f32 v[144:145], v[136:137], v[2:3] op_sel:[1,0] op_sel_hi:[0,0]
	v_pk_fma_f32 v[148:149], v[136:137], v[146:147], v[144:145] neg_lo:[0,0,1] neg_hi:[0,0,1]
	v_pk_fma_f32 v[136:137], v[136:137], v[146:147], v[144:145] op_sel_hi:[1,0,1]
	v_lshlrev_b64 v[144:145], 8, v[196:197]
	v_lshl_add_u64 v[144:145], s[94:95], 0, v[144:145]
	v_lshl_add_u64 v[144:145], v[144:145], 0, v[188:189]
	v_add_co_u32_e32 v136, vcc, s0, v144
	v_cvt_pk_bf16_f32 v132, v138, v135
	v_cvt_pk_bf16_f32 v133, v140, v133
	v_cvt_pk_bf16_f32 v134, v150, v143
	v_cvt_pk_bf16_f32 v135, v148, v137
	v_addc_co_u32_e32 v137, vcc, 0, v145, vcc
	global_store_dwordx4 v[136:137], v[132:135], off offset:1024
	v_mov_b32_e32 v2, v161
	v_pk_mul_f32 v[142:143], v[100:101], v[202:203] op_sel_hi:[1,0]
	v_pk_mul_f32 v[134:135], v[104:105], v[202:203] op_sel_hi:[1,0]
	v_pk_mul_f32 v[132:133], v[106:107], v[202:203] op_sel_hi:[1,0]
	v_pk_mul_f32 v[136:137], v[134:135], v[2:3] op_sel:[1,0] op_sel_hi:[0,0]
	v_mov_b32_e32 v2, v163
	v_pk_fma_f32 v[138:139], v[134:135], v[160:161], v[136:137] neg_lo:[0,0,1] neg_hi:[0,0,1]
	v_pk_fma_f32 v[134:135], v[134:135], v[160:161], v[136:137] op_sel_hi:[1,0,1]
	v_pk_mul_f32 v[136:137], v[132:133], v[2:3] op_sel:[1,0] op_sel_hi:[0,0]
	v_mov_b32_e32 v2, v153
	v_pk_fma_f32 v[140:141], v[132:133], v[162:163], v[136:137] neg_lo:[0,0,1] neg_hi:[0,0,1]
	v_pk_fma_f32 v[132:133], v[132:133], v[162:163], v[136:137] op_sel_hi:[1,0,1]
	v_pk_mul_f32 v[136:137], v[102:103], v[202:203] op_sel_hi:[1,0]
	v_pk_mul_f32 v[144:145], v[142:143], v[2:3] op_sel:[1,0] op_sel_hi:[0,0]
	v_mov_b32_e32 v2, v155
	v_ashrrev_i32_e32 v201, 31, v200
	v_pk_fma_f32 v[146:147], v[142:143], v[152:153], v[144:145] neg_lo:[0,0,1] neg_hi:[0,0,1]
	v_pk_fma_f32 v[142:143], v[142:143], v[152:153], v[144:145] op_sel_hi:[1,0,1]
	v_pk_mul_f32 v[144:145], v[136:137], v[2:3] op_sel:[1,0] op_sel_hi:[0,0]
	v_pk_fma_f32 v[148:149], v[136:137], v[154:155], v[144:145] neg_lo:[0,0,1] neg_hi:[0,0,1]
	v_pk_fma_f32 v[136:137], v[136:137], v[154:155], v[144:145] op_sel_hi:[1,0,1]
	v_lshlrev_b64 v[144:145], 8, v[200:201]
	v_lshl_add_u64 v[144:145], s[94:95], 0, v[144:145]
	v_lshl_add_u64 v[144:145], v[144:145], 0, v[188:189]
	v_add_co_u32_e32 v136, vcc, 0x949e000, v144
	v_cvt_pk_bf16_f32 v132, v138, v135
	v_cvt_pk_bf16_f32 v133, v140, v133
	v_cvt_pk_bf16_f32 v134, v146, v143
	v_cvt_pk_bf16_f32 v135, v148, v137
	v_addc_co_u32_e32 v137, vcc, 0, v145, vcc
	s_cmp_eq_u32 s48, 64
	global_store_dwordx4 v[136:137], v[132:135], off offset:1024
	s_cbranch_scc1 .LBB0_111
	v_add_u32_e32 v190, 0x80, v190
	v_ashrrev_i32_e32 v191, 31, v190
	v_lshl_add_u64 v[152:153], v[190:191], 2, s[70:71]
	v_mov_b32_e32 v192, v246
	s_movk_i32 s0, 0x7cf
	v_and_or_b32 v2, v190, s0, 16
	v_cmp_gt_i32_e32 vcc, s20, v190
	v_mov_b32_e32 v133, 0
	v_mov_b32_e32 v132, 1.0
	v_cndmask_b32_e32 v2, v181, v2, vcc
	v_lshlrev_b32_e32 v2, 6, v2
	v_lshl_add_u64 v[140:141], s[84:85], 0, v[2:3]
	v_mov_b32_e32 v136, 1.0
	v_mov_b32_e32 v137, 0
	v_mov_b32_e32 v138, 1.0
	v_mov_b32_e32 v139, 0
	s_and_saveexec_b64 s[0:1], s[38:39]
	s_cbranch_execz .LBB0_96
	v_lshlrev_b32_e32 v2, 2, v170
	v_lshl_add_u64 v[134:135], v[140:141], 0, v[2:3]
	global_load_dwordx4 v[136:139], v[134:135], off

.LBB0_98:
	s_or_b64 exec, exec, s[0:1]
	v_mov_b32_e32 v196, v247
	s_movk_i32 s0, 0x7df
	v_or_b32_e32 v194, 16, v190
	v_bitop3_b32 v2, v190, s0, 16 bitop3:0xc8
	v_add_u32_e32 v2, 16, v2
	v_cmp_gt_i32_e32 vcc, s20, v194
	v_mov_b32_e32 v141, 0
	v_mov_b32_e32 v140, 1.0
	v_cndmask_b32_e32 v2, v181, v2, vcc
	v_lshlrev_b32_e32 v2, 6, v2
	v_lshl_add_u64 v[144:145], s[84:85], 0, v[2:3]
	v_mov_b32_e32 v148, 1.0
	v_mov_b32_e32 v149, 0
	v_mov_b32_e32 v150, 1.0
	v_mov_b32_e32 v151, 0
	s_and_saveexec_b64 s[0:1], s[38:39]
	s_cbranch_execz .LBB0_100
	v_lshlrev_b32_e32 v2, 2, v170
	v_lshl_add_u64 v[142:143], v[144:145], 0, v[2:3]
	global_load_dwordx4 v[148:151], v[142:143], off

.LBB0_102:
	s_or_b64 exec, exec, s[0:1]
	v_mov_b32_e32 v200, v248
	v_or_b32_e32 v198, 32, v190
	s_movk_i32 s0, 0x7ef
	v_and_or_b32 v2, v198, s0, 16
	v_cmp_gt_i32_e32 vcc, s20, v198
	v_mov_b32_e32 v145, 0
	v_mov_b32_e32 v144, 1.0
	v_cndmask_b32_e32 v2, v181, v2, vcc
	v_lshlrev_b32_e32 v2, 6, v2
	v_lshl_add_u64 v[154:155], s[84:85], 0, v[2:3]
	v_mov_b32_e32 v156, 1.0
	v_mov_b32_e32 v157, 0
	v_mov_b32_e32 v158, 1.0
	v_mov_b32_e32 v159, 0
	s_and_saveexec_b64 s[0:1], s[38:39]
	s_cbranch_execz .LBB0_104
	v_lshlrev_b32_e32 v2, 2, v170
	v_lshl_add_u64 v[146:147], v[154:155], 0, v[2:3]
	global_load_dwordx4 v[156:159], v[146:147], off

.LBB0_106:
	s_or_b64 exec, exec, s[0:1]
	v_mov_b32_e32 v204, v249
	s_movk_i32 s0, 0x7ff
	v_or_b32_e32 v202, 48, v190
	v_bitop3_b32 v2, v190, s0, 48 bitop3:0xc8
	v_add_u32_e32 v2, 16, v2
	v_cmp_gt_i32_e32 vcc, s20, v202
	v_mov_b32_e32 v153, 0
	v_mov_b32_e32 v152, 1.0
	v_cndmask_b32_e32 v2, v181, v2, vcc
	v_lshlrev_b32_e32 v2, 6, v2
	v_lshl_add_u64 v[206:207], s[84:85], 0, v[2:3]
	v_mov_b32_e32 v160, 1.0
	v_mov_b32_e32 v161, 0
	v_mov_b32_e32 v162, 1.0
	v_mov_b32_e32 v163, 0
	s_and_saveexec_b64 s[0:1], s[38:39]
	s_cbranch_execz .LBB0_108
	v_lshlrev_b32_e32 v2, 2, v170
	v_lshl_add_u64 v[154:155], v[206:207], 0, v[2:3]
	global_load_dwordx4 v[160:163], v[154:155], off

.LBB0_112:
	s_and_b64 vcc, exec, s[0:1]
	s_cbranch_vccz .LBB0_147
	s_lshl_b32 s0, s48, 8
	v_add_u32_e32 v190, s0, v241
	v_ashrrev_i32_e32 v191, 31, v190
	v_lshl_add_u64 v[152:153], v[190:191], 2, s[70:71]
	v_mov_b32_e32 v188, v164
	s_movk_i32 s0, 0x7cf
	v_and_or_b32 v2, v190, s0, 16
	v_cmp_gt_i32_e32 vcc, s20, v190
	v_mov_b32_e32 v198, 0
	v_mov_b32_e32 v132, 1.0
	v_cndmask_b32_e32 v2, v181, v2, vcc
	v_lshlrev_b32_e32 v2, 6, v2
	v_lshl_add_u64 v[136:137], s[84:85], 0, v[2:3]
	v_mov_b32_e32 v140, 1.0
	v_mov_b32_e32 v210, 0
	v_mov_b32_e32 v142, 1.0
	v_mov_b32_e32 v206, 0
	s_and_saveexec_b64 s[0:1], s[38:39]
	s_cbranch_execz .LBB0_115
	v_lshlrev_b32_e32 v2, 2, v170
	v_lshl_add_u64 v[134:135], v[136:137], 0, v[2:3]
	global_load_dwordx4 v[140:143], v[134:135], off

.LBB0_117:
	s_or_b64 exec, exec, s[0:1]
	v_mov_b32_e32 v196, v165
	s_movk_i32 s0, 0x7df
	v_or_b32_e32 v192, 16, v190
	v_bitop3_b32 v2, v190, s0, 16 bitop3:0xc8
	v_add_u32_e32 v2, 16, v2
	v_cmp_gt_i32_e32 vcc, s20, v192
	v_mov_b32_e32 v204, 0
	v_mov_b32_e32 v136, 1.0
	v_cndmask_b32_e32 v2, v181, v2, vcc
	v_lshlrev_b32_e32 v2, 6, v2
	v_lshl_add_u64 v[144:145], s[84:85], 0, v[2:3]
	v_mov_b32_e32 v148, 1.0
	v_mov_b32_e32 v218, 0
	v_mov_b32_e32 v150, 1.0
	v_mov_b32_e32 v216, 0
	s_and_saveexec_b64 s[0:1], s[38:39]
	s_cbranch_execz .LBB0_119
	v_lshlrev_b32_e32 v2, 2, v170
	v_lshl_add_u64 v[138:139], v[144:145], 0, v[2:3]
	global_load_dwordx4 v[148:151], v[138:139], off

.LBB0_121:
	s_or_b64 exec, exec, s[0:1]
	v_mov_b32_e32 v202, v166
	v_or_b32_e32 v194, 32, v190
	s_movk_i32 s0, 0x7ef
	v_and_or_b32 v2, v194, s0, 16
	v_cmp_gt_i32_e32 vcc, s20, v194
	v_mov_b32_e32 v212, 0
	v_mov_b32_e32 v144, 1.0
	v_cndmask_b32_e32 v2, v181, v2, vcc
	v_lshlrev_b32_e32 v2, 6, v2
	v_lshl_add_u64 v[154:155], s[84:85], 0, v[2:3]
	v_mov_b32_e32 v156, 1.0
	v_mov_b32_e32 v226, 0
	v_mov_b32_e32 v158, 1.0
	v_mov_b32_e32 v224, 0
	s_and_saveexec_b64 s[0:1], s[38:39]
	s_cbranch_execz .LBB0_123
	v_lshlrev_b32_e32 v2, 2, v170
	v_lshl_add_u64 v[146:147], v[154:155], 0, v[2:3]
	global_load_dwordx4 v[156:159], v[146:147], off

.LBB0_125:
	s_or_b64 exec, exec, s[0:1]
	v_mov_b32_e32 v208, v167
	s_movk_i32 s0, 0x7ff
	v_or_b32_e32 v200, 48, v190
	v_bitop3_b32 v2, v190, s0, 48 bitop3:0xc8
	v_add_u32_e32 v2, 16, v2
	v_cmp_gt_i32_e32 vcc, s20, v200
	v_mov_b32_e32 v220, 0
	v_mov_b32_e32 v152, 1.0
	v_cndmask_b32_e32 v2, v181, v2, vcc
	v_lshlrev_b32_e32 v2, 6, v2
	v_lshl_add_u64 v[234:235], s[84:85], 0, v[2:3]
	v_mov_b32_e32 v160, 1.0
	v_mov_b32_e32 v232, 0
	v_mov_b32_e32 v162, 1.0
	v_mov_b32_e32 v230, 0
	s_and_saveexec_b64 s[0:1], s[38:39]
	s_cbranch_execz .LBB0_127
	v_lshlrev_b32_e32 v2, 2, v170
	v_lshl_add_u64 v[154:155], v[234:235], 0, v[2:3]
	global_load_dwordx4 v[160:163], v[154:155], off

.LBB0_129:
	s_or_b64 exec, exec, s[0:1]
	s_waitcnt vmcnt(0)
	s_and_saveexec_b64 s[0:1], s[38:39]
	v_mov_b32_e32 v210, v141
	v_mov_b32_e32 v206, v143
	v_mov_b32_e32 v198, v133
	v_mov_b32_e32 v214, v135
	v_mov_b32_e32 v218, v149
	v_mov_b32_e32 v216, v151
	v_mov_b32_e32 v204, v137
	v_mov_b32_e32 v222, v139
	v_mov_b32_e32 v226, v157
	v_mov_b32_e32 v224, v159
	v_mov_b32_e32 v212, v145
	v_mov_b32_e32 v228, v147
	v_mov_b32_e32 v232, v161
	v_mov_b32_e32 v230, v163
	v_mov_b32_e32 v220, v153
	v_mov_b32_e32 v2, v155
	s_or_b64 exec, exec, s[0:1]
	v_pk_mul_f32 v[168:169], v[128:129], v[188:189] op_sel_hi:[1,0]
	v_pk_mul_f32 v[236:237], v[130:131], v[188:189] op_sel_hi:[1,0]
	v_pk_mul_f32 v[210:211], v[168:169], v[210:211] op_sel:[1,0] op_sel_hi:[0,0]
	v_pk_fma_f32 v[238:239], v[168:169], v[140:141], v[210:211] op_sel_hi:[1,0,1] neg_lo:[0,0,1] neg_hi:[0,0,1]
	v_pk_fma_f32 v[140:141], v[168:169], v[140:141], v[210:211] op_sel_hi:[1,0,1]
	v_pk_mul_f32 v[168:169], v[236:237], v[206:207] op_sel:[1,0] op_sel_hi:[0,0]
	v_pk_fma_f32 v[206:207], v[236:237], v[142:143], v[168:169] op_sel_hi:[1,0,1] neg_lo:[0,0,1] neg_hi:[0,0,1]
	v_pk_fma_f32 v[142:143], v[236:237], v[142:143], v[168:169] op_sel_hi:[1,0,1]
	v_pk_mul_f32 v[168:169], v[126:127], v[188:189] op_sel_hi:[1,0]
	v_pk_mul_f32 v[188:189], v[124:125], v[188:189] op_sel_hi:[1,0]
	v_mov_b32_e32 v207, v143
	s_mov_b32 s4, 0x3e000000
	v_pk_mul_f32 v[198:199], v[188:189], v[198:199] op_sel:[1,0] op_sel_hi:[0,0]
	v_or_b32_e32 v234, s74, v178
	v_pk_mul_f32 v[142:143], v[206:207], s[4:5] op_sel_hi:[1,0]
	v_pk_fma_f32 v[206:207], v[188:189], v[132:133], v[198:199] op_sel_hi:[1,0,1] neg_lo:[0,0,1] neg_hi:[0,0,1]
	v_pk_fma_f32 v[132:133], v[188:189], v[132:133], v[198:199] op_sel_hi:[1,0,1]
	v_pk_mul_f32 v[188:189], v[168:169], v[214:215] op_sel:[1,0] op_sel_hi:[0,0]
	v_ashrrev_i32_e32 v235, 31, v234
	v_pk_fma_f32 v[198:199], v[168:169], v[134:135], v[188:189] op_sel_hi:[1,0,1] neg_lo:[0,0,1] neg_hi:[0,0,1]
	v_pk_fma_f32 v[134:135], v[168:169], v[134:135], v[188:189] op_sel_hi:[1,0,1]
	v_mov_b32_e32 v207, v133
	v_lshlrev_b64 v[132:133], 10, v[190:191]
	v_mov_b32_e32 v239, v141
	v_mov_b32_e32 v199, v135
	v_lshl_add_u64 v[132:133], s[94:95], 0, v[132:133]
	v_lshlrev_b64 v[188:189], 1, v[234:235]
	v_pk_mul_f32 v[140:141], v[238:239], s[4:5] op_sel_hi:[1,0]
	v_pk_mul_f32 v[168:169], v[198:199], s[4:5] op_sel_hi:[1,0]
	v_lshl_add_u64 v[198:199], v[132:133], 0, v[188:189]
	s_mov_b32 s0, 0x847e000
	v_pk_mul_f32 v[134:135], v[206:207], s[4:5] op_sel_hi:[1,0]
	v_cvt_pk_bf16_f32 v132, v140, v141
	v_add_co_u32_e32 v140, vcc, s0, v198
	v_cvt_pk_bf16_f32 v133, v142, v143
	v_cvt_pk_bf16_f32 v134, v134, v135
	v_cvt_pk_bf16_f32 v135, v168, v169
	v_addc_co_u32_e32 v141, vcc, 0, v199, vcc
	global_store_dwordx4 v[140:141], v[132:135], off offset:2048
	v_ashrrev_i32_e32 v193, 31, v192
	v_ashrrev_i32_e32 v195, 31, v194
	v_pk_mul_f32 v[134:135], v[120:121], v[196:197] op_sel_hi:[1,0]
	v_pk_mul_f32 v[132:133], v[122:123], v[196:197] op_sel_hi:[1,0]
	v_pk_mul_f32 v[140:141], v[134:135], v[218:219] op_sel:[1,0] op_sel_hi:[0,0]
	v_pk_fma_f32 v[142:143], v[134:135], v[148:149], v[140:141] op_sel_hi:[1,0,1] neg_lo:[0,0,1] neg_hi:[0,0,1]
	v_pk_fma_f32 v[134:135], v[134:135], v[148:149], v[140:141] op_sel_hi:[1,0,1]
	v_pk_mul_f32 v[140:141], v[132:133], v[216:217] op_sel:[1,0] op_sel_hi:[0,0]
	v_pk_fma_f32 v[148:149], v[132:133], v[150:151], v[140:141] op_sel_hi:[1,0,1] neg_lo:[0,0,1] neg_hi:[0,0,1]
	v_pk_fma_f32 v[132:133], v[132:133], v[150:151], v[140:141] op_sel_hi:[1,0,1]
	v_mov_b32_e32 v143, v135
	v_mov_b32_e32 v149, v133
	v_pk_mul_f32 v[132:133], v[142:143], s[4:5] op_sel_hi:[1,0]
	v_pk_mul_f32 v[142:143], v[116:117], v[196:197] op_sel_hi:[1,0]
	v_pk_mul_f32 v[140:141], v[148:149], s[4:5] op_sel_hi:[1,0]
	v_pk_mul_f32 v[148:149], v[142:143], v[204:205] op_sel:[1,0] op_sel_hi:[0,0]
	v_pk_mul_f32 v[134:135], v[118:119], v[196:197] op_sel_hi:[1,0]
	v_pk_fma_f32 v[150:151], v[142:143], v[136:137], v[148:149] op_sel_hi:[1,0,1] neg_lo:[0,0,1] neg_hi:[0,0,1]
	v_pk_fma_f32 v[136:137], v[142:143], v[136:137], v[148:149] op_sel_hi:[1,0,1]
	v_pk_mul_f32 v[142:143], v[134:135], v[222:223] op_sel:[1,0] op_sel_hi:[0,0]
	v_mov_b32_e32 v151, v137
	v_lshlrev_b64 v[136:137], 10, v[192:193]
	v_pk_fma_f32 v[148:149], v[134:135], v[138:139], v[142:143] op_sel_hi:[1,0,1] neg_lo:[0,0,1] neg_hi:[0,0,1]
	v_pk_fma_f32 v[134:135], v[134:135], v[138:139], v[142:143] op_sel_hi:[1,0,1]
	v_lshl_add_u64 v[136:137], s[94:95], 0, v[136:137]
	v_mov_b32_e32 v149, v135
	v_lshl_add_u64 v[136:137], v[136:137], 0, v[188:189]
	v_pk_mul_f32 v[138:139], v[148:149], s[4:5] op_sel_hi:[1,0]
	v_pk_mul_f32 v[134:135], v[150:151], s[4:5] op_sel_hi:[1,0]
	v_add_co_u32_e32 v136, vcc, s0, v136
	v_cvt_pk_bf16_f32 v132, v132, v133
	v_cvt_pk_bf16_f32 v133, v140, v141
	v_cvt_pk_bf16_f32 v134, v134, v135
	v_cvt_pk_bf16_f32 v135, v138, v139
	v_addc_co_u32_e32 v137, vcc, 0, v137, vcc
	global_store_dwordx4 v[136:137], v[132:135], off offset:2048
	v_ashrrev_i32_e32 v201, 31, v200
	s_cmp_eq_u32 s48, 64
	v_pk_mul_f32 v[134:135], v[112:113], v[202:203] op_sel_hi:[1,0]
	v_pk_mul_f32 v[132:133], v[114:115], v[202:203] op_sel_hi:[1,0]
	v_pk_mul_f32 v[136:137], v[134:135], v[226:227] op_sel:[1,0] op_sel_hi:[0,0]
	v_pk_fma_f32 v[138:139], v[134:135], v[156:157], v[136:137] op_sel_hi:[1,0,1] neg_lo:[0,0,1] neg_hi:[0,0,1]
	v_pk_fma_f32 v[134:135], v[134:135], v[156:157], v[136:137] op_sel_hi:[1,0,1]
	v_pk_mul_f32 v[136:137], v[132:133], v[224:225] op_sel:[1,0] op_sel_hi:[0,0]
	v_pk_fma_f32 v[140:141], v[132:133], v[158:159], v[136:137] op_sel_hi:[1,0,1] neg_lo:[0,0,1] neg_hi:[0,0,1]
	v_pk_fma_f32 v[132:133], v[132:133], v[158:159], v[136:137] op_sel_hi:[1,0,1]
	v_mov_b32_e32 v139, v135
	v_mov_b32_e32 v141, v133
	v_pk_mul_f32 v[132:133], v[138:139], s[4:5] op_sel_hi:[1,0]
	v_pk_mul_f32 v[138:139], v[108:109], v[202:203] op_sel_hi:[1,0]
	v_pk_mul_f32 v[136:137], v[140:141], s[4:5] op_sel_hi:[1,0]
	v_pk_mul_f32 v[140:141], v[138:139], v[212:213] op_sel:[1,0] op_sel_hi:[0,0]
	v_pk_mul_f32 v[134:135], v[110:111], v[202:203] op_sel_hi:[1,0]
	v_pk_fma_f32 v[142:143], v[138:139], v[144:145], v[140:141] op_sel_hi:[1,0,1] neg_lo:[0,0,1] neg_hi:[0,0,1]
	v_pk_fma_f32 v[138:139], v[138:139], v[144:145], v[140:141] op_sel_hi:[1,0,1]
	v_pk_mul_f32 v[140:141], v[134:135], v[228:229] op_sel:[1,0] op_sel_hi:[0,0]
	v_mov_b32_e32 v143, v139
	v_lshlrev_b64 v[138:139], 10, v[194:195]
	v_pk_fma_f32 v[144:145], v[134:135], v[146:147], v[140:141] op_sel_hi:[1,0,1] neg_lo:[0,0,1] neg_hi:[0,0,1]
	v_pk_fma_f32 v[134:135], v[134:135], v[146:147], v[140:141] op_sel_hi:[1,0,1]
	v_lshl_add_u64 v[138:139], s[94:95], 0, v[138:139]
	v_mov_b32_e32 v145, v135
	v_lshl_add_u64 v[138:139], v[138:139], 0, v[188:189]
	v_pk_mul_f32 v[140:141], v[144:145], s[4:5] op_sel_hi:[1,0]
	v_pk_mul_f32 v[134:135], v[142:143], s[4:5] op_sel_hi:[1,0]
	v_cvt_pk_bf16_f32 v132, v132, v133
	v_cvt_pk_bf16_f32 v133, v136, v137
	v_add_co_u32_e32 v136, vcc, s0, v138
	v_cvt_pk_bf16_f32 v134, v134, v135
	v_cvt_pk_bf16_f32 v135, v140, v141
	v_addc_co_u32_e32 v137, vcc, 0, v139, vcc
	global_store_dwordx4 v[136:137], v[132:135], off offset:2048
	s_nop 1
	v_pk_mul_f32 v[134:135], v[104:105], v[208:209] op_sel_hi:[1,0]
	v_pk_mul_f32 v[132:133], v[106:107], v[208:209] op_sel_hi:[1,0]
	v_pk_mul_f32 v[136:137], v[134:135], v[232:233] op_sel:[1,0] op_sel_hi:[0,0]
	v_pk_fma_f32 v[138:139], v[134:135], v[160:161], v[136:137] op_sel_hi:[1,0,1] neg_lo:[0,0,1] neg_hi:[0,0,1]
	v_pk_fma_f32 v[134:135], v[134:135], v[160:161], v[136:137] op_sel_hi:[1,0,1]
	v_pk_mul_f32 v[136:137], v[132:133], v[230:231] op_sel:[1,0] op_sel_hi:[0,0]
	v_pk_fma_f32 v[140:141], v[132:133], v[162:163], v[136:137] op_sel_hi:[1,0,1] neg_lo:[0,0,1] neg_hi:[0,0,1]
	v_pk_fma_f32 v[132:133], v[132:133], v[162:163], v[136:137] op_sel_hi:[1,0,1]
	v_mov_b32_e32 v139, v135
	v_mov_b32_e32 v141, v133
	v_pk_mul_f32 v[132:133], v[138:139], s[4:5] op_sel_hi:[1,0]
	v_pk_mul_f32 v[138:139], v[100:101], v[208:209] op_sel_hi:[1,0]
	v_pk_mul_f32 v[136:137], v[140:141], s[4:5] op_sel_hi:[1,0]
	v_pk_mul_f32 v[140:141], v[138:139], v[220:221] op_sel:[1,0] op_sel_hi:[0,0]
	v_pk_mul_f32 v[134:135], v[102:103], v[208:209] op_sel_hi:[1,0]
	v_pk_fma_f32 v[142:143], v[138:139], v[152:153], v[140:141] op_sel_hi:[1,0,1] neg_lo:[0,0,1] neg_hi:[0,0,1]
	v_pk_fma_f32 v[138:139], v[138:139], v[152:153], v[140:141] op_sel_hi:[1,0,1]
	v_pk_mul_f32 v[140:141], v[134:135], v[2:3] op_sel:[1,0] op_sel_hi:[0,0]
	v_mov_b32_e32 v143, v139
	v_lshlrev_b64 v[138:139], 10, v[200:201]
	v_pk_fma_f32 v[144:145], v[134:135], v[154:155], v[140:141] op_sel_hi:[1,0,1] neg_lo:[0,0,1] neg_hi:[0,0,1]
	v_pk_fma_f32 v[134:135], v[134:135], v[154:155], v[140:141] op_sel_hi:[1,0,1]
	v_lshl_add_u64 v[138:139], s[94:95], 0, v[138:139]
	v_mov_b32_e32 v145, v135
	v_lshl_add_u64 v[138:139], v[138:139], 0, v[188:189]
	v_pk_mul_f32 v[140:141], v[144:145], s[4:5] op_sel_hi:[1,0]
	v_pk_mul_f32 v[134:135], v[142:143], s[4:5] op_sel_hi:[1,0]
	v_cvt_pk_bf16_f32 v132, v132, v133
	v_cvt_pk_bf16_f32 v133, v136, v137
	v_add_co_u32_e32 v136, vcc, 0x847e000, v138
	v_cvt_pk_bf16_f32 v134, v134, v135
	v_cvt_pk_bf16_f32 v135, v140, v141
	v_addc_co_u32_e32 v137, vcc, 0, v139, vcc
	global_store_dwordx4 v[136:137], v[132:135], off offset:2048
	s_cbranch_scc1 .LBB0_147
	v_add_u32_e32 v190, 0x80, v190
	v_ashrrev_i32_e32 v191, 31, v190
	v_lshl_add_u64 v[152:153], v[190:191], 2, s[70:71]
	v_mov_b32_e32 v194, v246
	s_movk_i32 s0, 0x7cf
	v_and_or_b32 v2, v190, s0, 16
	v_cmp_gt_i32_e32 vcc, s20, v190
	v_mov_b32_e32 v200, 0
	v_mov_b32_e32 v132, 1.0
	v_cndmask_b32_e32 v2, v181, v2, vcc
	v_lshlrev_b32_e32 v2, 6, v2
	v_lshl_add_u64 v[136:137], s[84:85], 0, v[2:3]
	v_mov_b32_e32 v140, 1.0
	v_mov_b32_e32 v210, 0
	v_mov_b32_e32 v142, 1.0
	v_mov_b32_e32 v208, 0
	s_and_saveexec_b64 s[0:1], s[38:39]
	s_cbranch_execz .LBB0_132
	v_lshlrev_b32_e32 v2, 2, v170
	v_lshl_add_u64 v[134:135], v[136:137], 0, v[2:3]
	global_load_dwordx4 v[140:143], v[134:135], off

.LBB0_134:
	s_or_b64 exec, exec, s[0:1]
	v_mov_b32_e32 v198, v247
	s_movk_i32 s0, 0x7df
	v_or_b32_e32 v192, 16, v190
	v_bitop3_b32 v2, v190, s0, 16 bitop3:0xc8
	v_add_u32_e32 v2, 16, v2
	v_cmp_gt_i32_e32 vcc, s20, v192
	v_mov_b32_e32 v206, 0
	v_mov_b32_e32 v136, 1.0
	v_cndmask_b32_e32 v2, v181, v2, vcc
	v_lshlrev_b32_e32 v2, 6, v2
	v_lshl_add_u64 v[144:145], s[84:85], 0, v[2:3]
	v_mov_b32_e32 v148, 1.0
	v_mov_b32_e32 v220, 0
	v_mov_b32_e32 v150, 1.0
	v_mov_b32_e32 v218, 0
	s_and_saveexec_b64 s[0:1], s[38:39]
	s_cbranch_execz .LBB0_136
	v_lshlrev_b32_e32 v2, 2, v170
	v_lshl_add_u64 v[138:139], v[144:145], 0, v[2:3]
	global_load_dwordx4 v[148:151], v[138:139], off

.LBB0_138:
	s_or_b64 exec, exec, s[0:1]
	v_mov_b32_e32 v204, v248
	v_or_b32_e32 v196, 32, v190
	s_movk_i32 s0, 0x7ef
	v_and_or_b32 v2, v196, s0, 16
	v_cmp_gt_i32_e32 vcc, s20, v196
	v_mov_b32_e32 v214, 0
	v_mov_b32_e32 v144, 1.0
	v_cndmask_b32_e32 v2, v181, v2, vcc
	v_lshlrev_b32_e32 v2, 6, v2
	v_lshl_add_u64 v[154:155], s[84:85], 0, v[2:3]
	v_mov_b32_e32 v156, 1.0
	v_mov_b32_e32 v228, 0
	v_mov_b32_e32 v158, 1.0
	v_mov_b32_e32 v226, 0
	s_and_saveexec_b64 s[0:1], s[38:39]
	s_cbranch_execz .LBB0_140
	v_lshlrev_b32_e32 v2, 2, v170
	v_lshl_add_u64 v[146:147], v[154:155], 0, v[2:3]
	global_load_dwordx4 v[156:159], v[146:147], off

.LBB0_142:
	s_or_b64 exec, exec, s[0:1]
	v_mov_b32_e32 v212, v249
	s_movk_i32 s0, 0x7ff
	v_or_b32_e32 v202, 48, v190
	v_bitop3_b32 v2, v190, s0, 48 bitop3:0xc8
	v_add_u32_e32 v2, 16, v2
	v_cmp_gt_i32_e32 vcc, s20, v202
	v_mov_b32_e32 v222, 0
	v_mov_b32_e32 v152, 1.0
	v_cndmask_b32_e32 v2, v181, v2, vcc
	v_lshlrev_b32_e32 v2, 6, v2
	v_lshl_add_u64 v[236:237], s[84:85], 0, v[2:3]
	v_mov_b32_e32 v160, 1.0
	v_mov_b32_e32 v234, 0
	v_mov_b32_e32 v162, 1.0
	v_mov_b32_e32 v232, 0
	s_and_saveexec_b64 s[0:1], s[38:39]
	s_cbranch_execz .LBB0_144
	v_lshlrev_b32_e32 v2, 2, v170
	v_lshl_add_u64 v[154:155], v[236:237], 0, v[2:3]
	global_load_dwordx4 v[160:163], v[154:155], off

.LBB0_148:
	s_andn2_b64 vcc, exec, s[0:1]
	s_cbranch_vccnz .LBB0_166
	s_cmp_lt_i32 s2, 2
	s_mov_b64 s[0:1], -1
	s_cbranch_scc1 .LBB0_158
	s_cmp_gt_i32 s2, 2
	s_cbranch_scc0 .LBB0_154
	s_lshl_b32 s0, s48, 8
	v_add_u32_e32 v134, s0, v241
	v_ashrrev_i32_e32 v135, 31, v134
	v_lshl_add_u64 v[146:147], v[134:135], 2, s[70:71]
	v_mov_b32_e32 v148, v164
	v_mov_b32_e32 v144, v165
	v_mov_b32_e32 v140, v166
	v_mov_b32_e32 v2, v167
	v_or_b32_e32 v132, s74, v178
	v_ashrrev_i32_e32 v133, 31, v132
	v_lshlrev_b64 v[132:133], 1, v[132:133]
	s_mov_b32 s0, 0x643f000
	v_or_b32_e32 v142, 16, v134
	v_ashrrev_i32_e32 v143, 31, v142
	v_lshlrev_b64 v[142:143], 11, v[142:143]
	v_lshl_add_u64 v[142:143], s[94:95], 0, v[142:143]
	v_or_b32_e32 v138, 32, v134
	v_ashrrev_i32_e32 v139, 31, v138
	v_lshlrev_b64 v[138:139], 11, v[138:139]
	v_lshl_add_u64 v[138:139], s[94:95], 0, v[138:139]
	v_or_b32_e32 v136, 48, v134
	v_ashrrev_i32_e32 v137, 31, v136
	v_lshlrev_b64 v[136:137], 11, v[136:137]
	v_lshl_add_u64 v[136:137], s[94:95], 0, v[136:137]
	s_cmp_eq_u32 s48, 64
	s_waitcnt vmcnt(0)
	v_pk_mul_f32 v[146:147], v[128:129], v[148:149] op_sel_hi:[1,0]
	s_nop 0
	v_mul_f32_e32 v141, 0xbfb8aa3b, v146
	v_exp_f32_e32 v141, v141
	v_pk_mul_f32 v[150:151], v[130:131], v[148:149] op_sel_hi:[1,0]
	v_add_f32_e32 v141, 1.0, v141
	v_rcp_f32_e32 v152, v141
	v_mul_f32_e32 v141, 0xbfb8aa3b, v147
	v_exp_f32_e32 v141, v141
	s_nop 0
	v_add_f32_e32 v141, 1.0, v141
	v_rcp_f32_e32 v153, v141
	v_mul_f32_e32 v141, 0xbfb8aa3b, v150
	v_exp_f32_e32 v141, v141
	v_pk_mul_f32 v[146:147], v[146:147], v[152:153]
	s_nop 0
	v_cvt_pk_bf16_f32 v146, v146, v147
	v_add_f32_e32 v141, 1.0, v141
	v_rcp_f32_e32 v152, v141
	v_mul_f32_e32 v141, 0xbfb8aa3b, v151
	v_exp_f32_e32 v141, v141
	s_nop 0
	v_add_f32_e32 v141, 1.0, v141
	v_rcp_f32_e32 v153, v141
	s_nop 0
	v_pk_mul_f32 v[150:151], v[150:151], v[152:153]
	v_pk_mul_f32 v[152:153], v[126:127], v[148:149] op_sel_hi:[1,0]
	v_pk_mul_f32 v[148:149], v[124:125], v[148:149] op_sel_hi:[1,0]
	v_cvt_pk_bf16_f32 v147, v150, v151
	v_mul_f32_e32 v141, 0xbfb8aa3b, v148
	v_exp_f32_e32 v141, v141
	s_nop 0
	v_add_f32_e32 v141, 1.0, v141
	v_rcp_f32_e32 v154, v141
	v_mul_f32_e32 v141, 0xbfb8aa3b, v149
	v_exp_f32_e32 v141, v141
	s_nop 0
	v_add_f32_e32 v141, 1.0, v141
	v_rcp_f32_e32 v155, v141
	v_mul_f32_e32 v141, 0xbfb8aa3b, v152
	v_exp_f32_e32 v141, v141
	v_pk_mul_f32 v[148:149], v[148:149], v[154:155]
	s_nop 0
	v_cvt_pk_bf16_f32 v148, v148, v149
	v_add_f32_e32 v141, 1.0, v141
	v_rcp_f32_e32 v154, v141
	v_mul_f32_e32 v141, 0xbfb8aa3b, v153
	v_exp_f32_e32 v141, v141
	s_nop 0
	v_add_f32_e32 v141, 1.0, v141
	v_rcp_f32_e32 v155, v141
	s_nop 0
	v_pk_mul_f32 v[152:153], v[152:153], v[154:155]
	v_lshlrev_b64 v[154:155], 11, v[134:135]
	v_lshl_add_u64 v[154:155], s[94:95], 0, v[154:155]
	v_lshl_add_u64 v[154:155], v[154:155], 0, v[132:133]
	v_add_co_u32_e32 v150, vcc, s0, v154
	v_cvt_pk_bf16_f32 v149, v152, v153
	s_nop 0
	v_addc_co_u32_e32 v151, vcc, 0, v155, vcc
	global_store_dwordx4 v[150:151], v[146:149], off
	s_nop 1
	v_pk_mul_f32 v[146:147], v[120:121], v[144:145] op_sel_hi:[1,0]
	v_pk_mul_f32 v[148:149], v[122:123], v[144:145] op_sel_hi:[1,0]
	v_mul_f32_e32 v135, 0xbfb8aa3b, v146
	v_exp_f32_e32 v135, v135
	s_nop 0
	v_add_f32_e32 v135, 1.0, v135
	v_rcp_f32_e32 v150, v135
	v_mul_f32_e32 v135, 0xbfb8aa3b, v147
	v_exp_f32_e32 v135, v135
	s_nop 0
	v_add_f32_e32 v135, 1.0, v135
	v_rcp_f32_e32 v151, v135
	v_mul_f32_e32 v135, 0xbfb8aa3b, v148
	v_exp_f32_e32 v135, v135
	v_pk_mul_f32 v[146:147], v[146:147], v[150:151]
	v_add_f32_e32 v135, 1.0, v135
	v_rcp_f32_e32 v150, v135
	v_mul_f32_e32 v135, 0xbfb8aa3b, v149
	v_exp_f32_e32 v135, v135
	s_nop 0
	v_add_f32_e32 v135, 1.0, v135
	v_rcp_f32_e32 v151, v135
	s_nop 0
	v_pk_mul_f32 v[148:149], v[148:149], v[150:151]
	v_pk_mul_f32 v[150:151], v[118:119], v[144:145] op_sel_hi:[1,0]
	v_pk_mul_f32 v[144:145], v[116:117], v[144:145] op_sel_hi:[1,0]
	s_nop 0
	v_mul_f32_e32 v135, 0xbfb8aa3b, v144
	v_exp_f32_e32 v135, v135
	s_nop 0
	v_add_f32_e32 v135, 1.0, v135
	v_rcp_f32_e32 v152, v135
	v_mul_f32_e32 v135, 0xbfb8aa3b, v145
	v_exp_f32_e32 v135, v135
	s_nop 0
	v_add_f32_e32 v135, 1.0, v135
	v_rcp_f32_e32 v153, v135
	v_mul_f32_e32 v135, 0xbfb8aa3b, v150
	v_exp_f32_e32 v135, v135
	v_pk_mul_f32 v[144:145], v[144:145], v[152:153]
	s_nop 0
	v_cvt_pk_bf16_f32 v144, v144, v145
	v_add_f32_e32 v135, 1.0, v135
	v_rcp_f32_e32 v152, v135
	v_mul_f32_e32 v135, 0xbfb8aa3b, v151
	v_exp_f32_e32 v135, v135
	s_nop 0
	v_add_f32_e32 v135, 1.0, v135
	v_rcp_f32_e32 v153, v135
	s_nop 0
	v_pk_mul_f32 v[150:151], v[150:151], v[152:153]
	v_lshl_add_u64 v[152:153], v[142:143], 0, v[132:133]
	v_cvt_pk_bf16_f32 v142, v146, v147
	v_add_co_u32_e32 v146, vcc, s0, v152
	v_cvt_pk_bf16_f32 v143, v148, v149
	v_cvt_pk_bf16_f32 v145, v150, v151
	v_addc_co_u32_e32 v147, vcc, 0, v153, vcc
	global_store_dwordx4 v[146:147], v[142:145], off
	s_nop 1
	v_pk_mul_f32 v[144:145], v[112:113], v[140:141] op_sel_hi:[1,0]
	v_pk_mul_f32 v[142:143], v[114:115], v[140:141] op_sel_hi:[1,0]
	v_mul_f32_e32 v135, 0xbfb8aa3b, v144
	v_exp_f32_e32 v135, v135
	s_nop 0
	v_add_f32_e32 v135, 1.0, v135
	v_rcp_f32_e32 v146, v135
	v_mul_f32_e32 v135, 0xbfb8aa3b, v145
	v_exp_f32_e32 v135, v135
	s_nop 0
	v_add_f32_e32 v135, 1.0, v135
	v_rcp_f32_e32 v147, v135
	v_mul_f32_e32 v135, 0xbfb8aa3b, v142
	v_exp_f32_e32 v135, v135
	v_pk_mul_f32 v[144:145], v[144:145], v[146:147]
	v_add_f32_e32 v135, 1.0, v135
	v_rcp_f32_e32 v146, v135
	v_mul_f32_e32 v135, 0xbfb8aa3b, v143
	v_exp_f32_e32 v135, v135
	s_nop 0
	v_add_f32_e32 v135, 1.0, v135
	v_rcp_f32_e32 v147, v135
	s_nop 0
	v_pk_mul_f32 v[142:143], v[142:143], v[146:147]
	v_pk_mul_f32 v[146:147], v[110:111], v[140:141] op_sel_hi:[1,0]
	v_pk_mul_f32 v[140:141], v[108:109], v[140:141] op_sel_hi:[1,0]
	s_nop 0
	v_mul_f32_e32 v135, 0xbfb8aa3b, v140
	v_exp_f32_e32 v135, v135
	s_nop 0
	v_add_f32_e32 v135, 1.0, v135
	v_rcp_f32_e32 v148, v135
	v_mul_f32_e32 v135, 0xbfb8aa3b, v141
	v_exp_f32_e32 v135, v135
	s_nop 0
	v_add_f32_e32 v135, 1.0, v135
	v_rcp_f32_e32 v149, v135
	v_mul_f32_e32 v135, 0xbfb8aa3b, v146
	v_exp_f32_e32 v135, v135
	v_pk_mul_f32 v[140:141], v[140:141], v[148:149]
	s_nop 0
	v_cvt_pk_bf16_f32 v140, v140, v141
	v_add_f32_e32 v135, 1.0, v135
	v_rcp_f32_e32 v148, v135
	v_mul_f32_e32 v135, 0xbfb8aa3b, v147
	v_exp_f32_e32 v135, v135
	s_nop 0
	v_add_f32_e32 v135, 1.0, v135
	v_rcp_f32_e32 v149, v135
	s_nop 0
	v_pk_mul_f32 v[146:147], v[146:147], v[148:149]
	v_lshl_add_u64 v[148:149], v[138:139], 0, v[132:133]
	v_cvt_pk_bf16_f32 v139, v142, v143
	v_add_co_u32_e32 v142, vcc, s0, v148
	v_cvt_pk_bf16_f32 v138, v144, v145
	v_cvt_pk_bf16_f32 v141, v146, v147
	v_addc_co_u32_e32 v143, vcc, 0, v149, vcc
	global_store_dwordx4 v[142:143], v[138:141], off
	v_pk_mul_f32 v[144:145], v[100:101], v[2:3] op_sel_hi:[1,0]
	s_nop 0
	v_pk_mul_f32 v[140:141], v[104:105], v[2:3] op_sel_hi:[1,0]
	v_pk_mul_f32 v[138:139], v[106:107], v[2:3] op_sel_hi:[1,0]
	v_mul_f32_e32 v135, 0xbfb8aa3b, v140
	v_exp_f32_e32 v135, v135
	s_nop 0
	v_add_f32_e32 v135, 1.0, v135
	v_rcp_f32_e32 v142, v135
	v_mul_f32_e32 v135, 0xbfb8aa3b, v141
	v_exp_f32_e32 v135, v135
	s_nop 0
	v_add_f32_e32 v135, 1.0, v135
	v_rcp_f32_e32 v143, v135
	v_mul_f32_e32 v135, 0xbfb8aa3b, v138
	v_exp_f32_e32 v135, v135
	v_pk_mul_f32 v[140:141], v[140:141], v[142:143]
	v_add_f32_e32 v135, 1.0, v135
	v_rcp_f32_e32 v142, v135
	v_mul_f32_e32 v135, 0xbfb8aa3b, v139
	v_exp_f32_e32 v135, v135
	s_nop 0
	v_add_f32_e32 v135, 1.0, v135
	v_rcp_f32_e32 v143, v135
	s_nop 0
	v_pk_mul_f32 v[138:139], v[138:139], v[142:143]
	v_pk_mul_f32 v[142:143], v[102:103], v[2:3] op_sel_hi:[1,0]
	v_mul_f32_e32 v2, 0xbfb8aa3b, v144
	v_exp_f32_e32 v2, v2
	s_nop 0
	v_add_f32_e32 v2, 1.0, v2
	v_rcp_f32_e32 v146, v2
	v_mul_f32_e32 v2, 0xbfb8aa3b, v145
	v_exp_f32_e32 v2, v2
	s_nop 0
	v_add_f32_e32 v2, 1.0, v2
	v_rcp_f32_e32 v147, v2
	v_mul_f32_e32 v2, 0xbfb8aa3b, v142
	v_exp_f32_e32 v2, v2
	v_pk_mul_f32 v[144:145], v[144:145], v[146:147]
	v_add_f32_e32 v2, 1.0, v2
	v_rcp_f32_e32 v146, v2
	v_mul_f32_e32 v2, 0xbfb8aa3b, v143
	v_exp_f32_e32 v2, v2
	s_nop 0
	v_add_f32_e32 v2, 1.0, v2
	v_rcp_f32_e32 v147, v2
	s_nop 0
	v_pk_mul_f32 v[142:143], v[142:143], v[146:147]
	v_lshl_add_u64 v[146:147], v[136:137], 0, v[132:133]
	v_cvt_pk_bf16_f32 v136, v140, v141
	v_add_co_u32_e32 v140, vcc, 0x643f000, v146
	v_cvt_pk_bf16_f32 v137, v138, v139
	v_cvt_pk_bf16_f32 v138, v144, v145
	v_cvt_pk_bf16_f32 v139, v142, v143
	v_addc_co_u32_e32 v141, vcc, 0, v147, vcc
	global_store_dwordx4 v[140:141], v[136:139], off
	s_cbranch_scc1 .LBB0_153
	v_add_u32_e32 v142, 0x80, v134
	v_ashrrev_i32_e32 v143, 31, v142
	v_lshl_add_u64 v[144:145], v[142:143], 2, s[70:71]
	v_mov_b32_e32 v148, v246
	v_mov_b32_e32 v146, v247
	v_mov_b32_e32 v138, v248
	v_mov_b32_e32 v2, v249
	v_lshlrev_b64 v[142:143], 11, v[142:143]
	v_lshl_add_u64 v[142:143], s[94:95], 0, v[142:143]
	v_add_u32_e32 v140, 0x90, v134
	v_ashrrev_i32_e32 v141, 31, v140
	v_lshlrev_b64 v[140:141], 11, v[140:141]
	v_lshl_add_u64 v[140:141], s[94:95], 0, v[140:141]
	v_add_u32_e32 v136, 0xa0, v134
	v_ashrrev_i32_e32 v137, 31, v136
	v_lshlrev_b64 v[136:137], 11, v[136:137]
	v_lshl_add_u64 v[136:137], s[94:95], 0, v[136:137]
	v_add_u32_e32 v134, 0xb0, v134
	v_ashrrev_i32_e32 v135, 31, v134
	v_lshlrev_b64 v[134:135], 11, v[134:135]
	v_lshl_add_u64 v[134:135], s[94:95], 0, v[134:135]
	s_waitcnt vmcnt(0)
	v_pk_mul_f32 v[150:151], v[96:97], v[148:149] op_sel_hi:[1,0]
	s_nop 0
	v_mul_f32_e32 v139, 0xbfb8aa3b, v150
	v_exp_f32_e32 v139, v139
	v_pk_mul_f32 v[144:145], v[98:99], v[148:149] op_sel_hi:[1,0]
	v_add_f32_e32 v139, 1.0, v139
	v_rcp_f32_e32 v152, v139
	v_mul_f32_e32 v139, 0xbfb8aa3b, v151
	v_exp_f32_e32 v139, v139
	s_nop 0
	v_add_f32_e32 v139, 1.0, v139
	v_rcp_f32_e32 v153, v139
	v_mul_f32_e32 v139, 0xbfb8aa3b, v144
	v_exp_f32_e32 v139, v139
	v_pk_mul_f32 v[150:151], v[150:151], v[152:153]
	v_add_f32_e32 v139, 1.0, v139
	v_rcp_f32_e32 v152, v139
	v_mul_f32_e32 v139, 0xbfb8aa3b, v145
	v_exp_f32_e32 v139, v139
	s_nop 0
	v_add_f32_e32 v139, 1.0, v139
	v_rcp_f32_e32 v153, v139
	s_nop 0
	v_pk_mul_f32 v[144:145], v[144:145], v[152:153]
	v_pk_mul_f32 v[152:153], v[94:95], v[148:149] op_sel_hi:[1,0]
	v_pk_mul_f32 v[148:149], v[92:93], v[148:149] op_sel_hi:[1,0]
	s_nop 0
	v_mul_f32_e32 v139, 0xbfb8aa3b, v148
	v_exp_f32_e32 v139, v139
	s_nop 0
	v_add_f32_e32 v139, 1.0, v139
	v_rcp_f32_e32 v154, v139
	v_mul_f32_e32 v139, 0xbfb8aa3b, v149
	v_exp_f32_e32 v139, v139
	s_nop 0
	v_add_f32_e32 v139, 1.0, v139
	v_rcp_f32_e32 v155, v139
	v_mul_f32_e32 v139, 0xbfb8aa3b, v152
	v_exp_f32_e32 v139, v139
	v_pk_mul_f32 v[148:149], v[148:149], v[154:155]
	v_add_f32_e32 v139, 1.0, v139
	v_rcp_f32_e32 v154, v139
	v_mul_f32_e32 v139, 0xbfb8aa3b, v153
	v_exp_f32_e32 v139, v139
	s_nop 0
	v_add_f32_e32 v139, 1.0, v139
	v_rcp_f32_e32 v155, v139
	s_nop 0
	v_pk_mul_f32 v[152:153], v[152:153], v[154:155]
	v_lshl_add_u64 v[154:155], v[142:143], 0, v[132:133]
	v_cvt_pk_bf16_f32 v143, v144, v145
	v_cvt_pk_bf16_f32 v144, v148, v149
	v_add_co_u32_e32 v148, vcc, s0, v154
	v_cvt_pk_bf16_f32 v142, v150, v151
	v_cvt_pk_bf16_f32 v145, v152, v153
	v_addc_co_u32_e32 v149, vcc, 0, v155, vcc
	global_store_dwordx4 v[148:149], v[142:145], off
	s_nop 1
	v_pk_mul_f32 v[142:143], v[88:89], v[146:147] op_sel_hi:[1,0]
	v_pk_mul_f32 v[144:145], v[90:91], v[146:147] op_sel_hi:[1,0]
	v_mul_f32_e32 v139, 0xbfb8aa3b, v142
	v_exp_f32_e32 v139, v139
	s_nop 0
	v_add_f32_e32 v139, 1.0, v139
	v_rcp_f32_e32 v148, v139
	v_mul_f32_e32 v139, 0xbfb8aa3b, v143
	v_exp_f32_e32 v139, v139
	s_nop 0
	v_add_f32_e32 v139, 1.0, v139
	v_rcp_f32_e32 v149, v139
	v_mul_f32_e32 v139, 0xbfb8aa3b, v144
	v_exp_f32_e32 v139, v139
	v_pk_mul_f32 v[142:143], v[142:143], v[148:149]
	v_add_f32_e32 v139, 1.0, v139
	v_rcp_f32_e32 v148, v139
	v_mul_f32_e32 v139, 0xbfb8aa3b, v145
	v_exp_f32_e32 v139, v139
	s_nop 0
	v_add_f32_e32 v139, 1.0, v139
	v_rcp_f32_e32 v149, v139
	s_nop 0
	v_pk_mul_f32 v[144:145], v[144:145], v[148:149]
	v_pk_mul_f32 v[148:149], v[86:87], v[146:147] op_sel_hi:[1,0]
	v_pk_mul_f32 v[146:147], v[84:85], v[146:147] op_sel_hi:[1,0]
	s_nop 0
	v_mul_f32_e32 v139, 0xbfb8aa3b, v146
	v_exp_f32_e32 v139, v139
	s_nop 0
	v_add_f32_e32 v139, 1.0, v139
	v_rcp_f32_e32 v150, v139
	v_mul_f32_e32 v139, 0xbfb8aa3b, v147
	v_exp_f32_e32 v139, v139
	s_nop 0
	v_add_f32_e32 v139, 1.0, v139
	v_rcp_f32_e32 v151, v139
	v_mul_f32_e32 v139, 0xbfb8aa3b, v148
	v_exp_f32_e32 v139, v139
	v_pk_mul_f32 v[146:147], v[146:147], v[150:151]
	v_add_f32_e32 v139, 1.0, v139
	v_rcp_f32_e32 v150, v139
	v_mul_f32_e32 v139, 0xbfb8aa3b, v149
	v_exp_f32_e32 v139, v139
	s_nop 0
	v_add_f32_e32 v139, 1.0, v139
	v_rcp_f32_e32 v151, v139
	s_nop 0
	v_pk_mul_f32 v[148:149], v[148:149], v[150:151]
	v_lshl_add_u64 v[150:151], v[140:141], 0, v[132:133]
	v_cvt_pk_bf16_f32 v141, v144, v145
	v_add_co_u32_e32 v144, vcc, s0, v150
	v_cvt_pk_bf16_f32 v140, v142, v143
	v_cvt_pk_bf16_f32 v142, v146, v147
	v_cvt_pk_bf16_f32 v143, v148, v149
	v_addc_co_u32_e32 v145, vcc, 0, v151, vcc
	global_store_dwordx4 v[144:145], v[140:143], off
	s_nop 1
	v_pk_mul_f32 v[142:143], v[80:81], v[138:139] op_sel_hi:[1,0]
	v_pk_mul_f32 v[140:141], v[82:83], v[138:139] op_sel_hi:[1,0]
	v_mul_f32_e32 v139, 0xbfb8aa3b, v142
	v_exp_f32_e32 v139, v139
	s_nop 0
	v_add_f32_e32 v139, 1.0, v139
	v_rcp_f32_e32 v144, v139
	v_mul_f32_e32 v139, 0xbfb8aa3b, v143
	v_exp_f32_e32 v139, v139
	s_nop 0
	v_add_f32_e32 v139, 1.0, v139
	v_rcp_f32_e32 v145, v139
	v_mul_f32_e32 v139, 0xbfb8aa3b, v140
	v_exp_f32_e32 v139, v139
	v_pk_mul_f32 v[142:143], v[142:143], v[144:145]
	v_add_f32_e32 v139, 1.0, v139
	v_rcp_f32_e32 v144, v139
	v_mul_f32_e32 v139, 0xbfb8aa3b, v141
	v_exp_f32_e32 v139, v139
	s_nop 0
	v_add_f32_e32 v139, 1.0, v139
	v_rcp_f32_e32 v145, v139
	s_nop 0
	v_pk_mul_f32 v[140:141], v[140:141], v[144:145]
	v_pk_mul_f32 v[144:145], v[78:79], v[138:139] op_sel_hi:[1,0]
	v_pk_mul_f32 v[138:139], v[76:77], v[138:139] op_sel_hi:[1,0]
	s_nop 0
	v_mul_f32_e32 v146, 0xbfb8aa3b, v138
	v_mul_f32_e32 v147, 0xbfb8aa3b, v139
	v_exp_f32_e32 v146, v146
	v_exp_f32_e32 v147, v147
	v_add_f32_e32 v146, 1.0, v146
	v_add_f32_e32 v147, 1.0, v147
	v_rcp_f32_e32 v146, v146
	v_rcp_f32_e32 v147, v147
	s_nop 0
	v_pk_mul_f32 v[138:139], v[138:139], v[146:147]
	v_mul_f32_e32 v146, 0xbfb8aa3b, v144
	v_mul_f32_e32 v147, 0xbfb8aa3b, v145
	v_exp_f32_e32 v146, v146
	v_exp_f32_e32 v147, v147
	v_cvt_pk_bf16_f32 v138, v138, v139
	v_add_f32_e32 v146, 1.0, v146
	v_add_f32_e32 v147, 1.0, v147
	v_rcp_f32_e32 v146, v146
	v_rcp_f32_e32 v147, v147
	s_nop 0
	v_pk_mul_f32 v[144:145], v[144:145], v[146:147]
	v_lshl_add_u64 v[146:147], v[136:137], 0, v[132:133]
	v_cvt_pk_bf16_f32 v137, v140, v141
	v_add_co_u32_e32 v140, vcc, s0, v146
	v_cvt_pk_bf16_f32 v136, v142, v143
	v_cvt_pk_bf16_f32 v139, v144, v145
	v_addc_co_u32_e32 v141, vcc, 0, v147, vcc
	global_store_dwordx4 v[140:141], v[136:139], off
	v_pk_mul_f32 v[142:143], v[68:69], v[2:3] op_sel_hi:[1,0]
	s_nop 0
	v_pk_mul_f32 v[138:139], v[72:73], v[2:3] op_sel_hi:[1,0]
	v_pk_mul_f32 v[136:137], v[74:75], v[2:3] op_sel_hi:[1,0]
	v_mul_f32_e32 v140, 0xbfb8aa3b, v138
	v_mul_f32_e32 v141, 0xbfb8aa3b, v139
	v_exp_f32_e32 v140, v140
	v_exp_f32_e32 v141, v141
	v_add_f32_e32 v140, 1.0, v140
	v_add_f32_e32 v141, 1.0, v141
	v_rcp_f32_e32 v140, v140
	v_rcp_f32_e32 v141, v141
	s_nop 0
	v_pk_mul_f32 v[138:139], v[138:139], v[140:141]
	v_mul_f32_e32 v140, 0xbfb8aa3b, v136
	v_mul_f32_e32 v141, 0xbfb8aa3b, v137
	v_exp_f32_e32 v140, v140
	v_exp_f32_e32 v141, v141
	v_add_f32_e32 v140, 1.0, v140
	v_add_f32_e32 v141, 1.0, v141
	v_rcp_f32_e32 v140, v140
	v_rcp_f32_e32 v141, v141
	s_nop 0
	v_pk_mul_f32 v[136:137], v[136:137], v[140:141]
	v_pk_mul_f32 v[140:141], v[70:71], v[2:3] op_sel_hi:[1,0]
	v_mul_f32_e32 v2, 0xbfb8aa3b, v142
	v_exp_f32_e32 v2, v2
	s_nop 0
	v_add_f32_e32 v2, 1.0, v2
	v_rcp_f32_e32 v144, v2
	v_mul_f32_e32 v2, 0xbfb8aa3b, v143
	v_exp_f32_e32 v2, v2
	s_nop 0
	v_add_f32_e32 v2, 1.0, v2
	v_rcp_f32_e32 v145, v2
	v_mul_f32_e32 v2, 0xbfb8aa3b, v140
	v_exp_f32_e32 v2, v2
	v_pk_mul_f32 v[142:143], v[142:143], v[144:145]
	v_add_f32_e32 v2, 1.0, v2
	v_rcp_f32_e32 v144, v2
	v_mul_f32_e32 v2, 0xbfb8aa3b, v141
	v_exp_f32_e32 v2, v2
	s_nop 0
	v_add_f32_e32 v2, 1.0, v2
	v_rcp_f32_e32 v145, v2
	s_nop 0
	v_pk_mul_f32 v[140:141], v[140:141], v[144:145]
	v_lshl_add_u64 v[144:145], v[134:135], 0, v[132:133]
	v_cvt_pk_bf16_f32 v133, v136, v137
	v_add_co_u32_e32 v136, vcc, 0x643f000, v144
	v_cvt_pk_bf16_f32 v132, v138, v139
	v_cvt_pk_bf16_f32 v134, v142, v143
	v_cvt_pk_bf16_f32 v135, v140, v141
	v_addc_co_u32_e32 v137, vcc, 0, v145, vcc
	global_store_dwordx4 v[136:137], v[132:135], off

.LBB0_163:
	s_andn2_b64 vcc, exec, s[0:1]
	s_cbranch_vccnz .LBB0_166
	s_lshl_b32 s0, s48, 8
	v_add_u32_e32 v156, s0, v241
	s_movk_i32 s0, 0x7cf
	v_cmp_gt_i32_e32 vcc, s20, v156
	v_and_or_b32 v2, v156, s0, 16
	v_ashrrev_i32_e32 v157, 31, v156
	v_cndmask_b32_e32 v2, v181, v2, vcc
	v_lshl_add_u64 v[140:141], v[156:157], 2, s[70:71]
	v_lshlrev_b32_e32 v2, 8, v2
	v_mov_b32_e32 v204, v164
	v_lshl_add_u64 v[132:133], v[182:183], 0, v[2:3]
	global_load_dwordx4 v[196:199], v[132:133], off offset:16
	global_load_dwordx4 v[200:203], v[132:133], off
	s_movk_i32 s0, 0x7df
	v_or_b32_e32 v158, 16, v156
	v_bitop3_b32 v2, v156, s0, 16 bitop3:0xc8
	v_cmp_gt_i32_e32 vcc, s20, v158
	v_add_u32_e32 v2, 16, v2
	v_mov_b32_e32 v188, v165
	v_cndmask_b32_e32 v2, v181, v2, vcc
	v_lshlrev_b32_e32 v2, 8, v2
	v_lshl_add_u64 v[132:133], v[182:183], 0, v[2:3]
	global_load_dwordx4 v[144:147], v[132:133], off offset:16
	global_load_dwordx4 v[152:155], v[132:133], off
	v_or_b32_e32 v160, 32, v156
	s_movk_i32 s0, 0x7ef
	v_cmp_gt_i32_e32 vcc, s20, v160
	v_and_or_b32 v2, v160, s0, 16
	v_mov_b32_e32 v190, v166
	v_cndmask_b32_e32 v2, v181, v2, vcc
	v_lshlrev_b32_e32 v2, 8, v2
	v_lshl_add_u64 v[136:137], v[182:183], 0, v[2:3]
	global_load_dwordx4 v[132:135], v[136:137], off offset:16
	s_nop 0
	global_load_dwordx4 v[136:139], v[136:137], off
	s_movk_i32 s0, 0x7ff
	v_or_b32_e32 v162, 48, v156
	v_bitop3_b32 v2, v156, s0, 48 bitop3:0xc8
	v_cmp_gt_i32_e32 vcc, s20, v162
	v_add_u32_e32 v2, 16, v2
	v_mov_b32_e32 v192, v167
	v_cndmask_b32_e32 v2, v181, v2, vcc
	v_lshlrev_b32_e32 v2, 8, v2
	v_lshl_add_u64 v[148:149], v[182:183], 0, v[2:3]
	global_load_dwordx4 v[140:143], v[148:149], off offset:16
	s_nop 0
	global_load_dwordx4 v[148:151], v[148:149], off
	v_or_b32_e32 v194, s74, v178
	v_ashrrev_i32_e32 v195, 31, v194
	s_mov_b32 s0, 0x3e000000
	v_ashrrev_i32_e32 v159, 31, v158
	v_ashrrev_i32_e32 v161, 31, v160
	v_ashrrev_i32_e32 v163, 31, v162
	s_cmp_eq_u32 s48, 64
	s_waitcnt vmcnt(0)
	v_pk_mul_f32 v[128:129], v[128:129], v[204:205] op_sel_hi:[1,0]
	v_pk_mul_f32 v[130:131], v[130:131], v[204:205] op_sel_hi:[1,0]
	v_pk_mul_f32 v[206:207], v[200:201], v[128:129] op_sel:[1,1] op_sel_hi:[1,0]
	v_mov_b32_e32 v2, v203
	v_pk_fma_f32 v[208:209], v[200:201], v[128:129], v[206:207] op_sel_hi:[0,1,1] neg_lo:[0,0,1] neg_hi:[0,0,1]
	v_pk_fma_f32 v[128:129], v[200:201], v[128:129], v[206:207] op_sel_hi:[0,1,1]
	v_pk_mul_f32 v[200:201], v[2:3], v[130:131] op_sel:[0,1] op_sel_hi:[0,0]
	v_pk_mul_f32 v[124:125], v[124:125], v[204:205] op_sel_hi:[1,0]
	v_pk_fma_f32 v[206:207], v[202:203], v[130:131], v[200:201] op_sel_hi:[0,1,1] neg_lo:[0,0,1] neg_hi:[0,0,1]
	v_pk_fma_f32 v[130:131], v[202:203], v[130:131], v[200:201] op_sel_hi:[0,1,1]
	v_pk_mul_f32 v[126:127], v[126:127], v[204:205] op_sel_hi:[1,0]
	v_pk_mul_f32 v[200:201], v[196:197], v[124:125] op_sel:[1,1] op_sel_hi:[1,0]
	v_mov_b32_e32 v2, v199
	v_pk_fma_f32 v[202:203], v[196:197], v[124:125], v[200:201] op_sel_hi:[0,1,1] neg_lo:[0,0,1] neg_hi:[0,0,1]
	v_pk_fma_f32 v[124:125], v[196:197], v[124:125], v[200:201] op_sel_hi:[0,1,1]
	v_pk_mul_f32 v[196:197], v[2:3], v[126:127] op_sel:[0,1] op_sel_hi:[0,0]
	v_pk_fma_f32 v[200:201], v[198:199], v[126:127], v[196:197] op_sel_hi:[0,1,1] neg_lo:[0,0,1] neg_hi:[0,0,1]
	v_pk_fma_f32 v[126:127], v[198:199], v[126:127], v[196:197] op_sel_hi:[0,1,1]
	v_mov_b32_e32 v207, v131
	v_mov_b32_e32 v209, v129
	v_mov_b32_e32 v201, v127
	v_mov_b32_e32 v203, v125
	v_lshlrev_b64 v[124:125], 10, v[156:157]
	v_pk_mul_f32 v[130:131], v[206:207], s[0:1] op_sel_hi:[1,0]
	v_pk_mul_f32 v[128:129], v[208:209], s[0:1] op_sel_hi:[1,0]
	v_pk_mul_f32 v[196:197], v[200:201], s[0:1] op_sel_hi:[1,0]
	v_pk_mul_f32 v[198:199], v[202:203], s[0:1] op_sel_hi:[1,0]
	v_lshl_add_u64 v[126:127], s[94:95], 0, v[124:125]
	v_lshlrev_b64 v[124:125], 1, v[194:195]
	v_lshl_add_u64 v[194:195], v[126:127], 0, v[124:125]
	v_cvt_pk_bf16_f32 v126, v128, v129
	v_cvt_pk_bf16_f32 v127, v130, v131
	v_cvt_pk_bf16_f32 v128, v198, v199
	v_cvt_pk_bf16_f32 v129, v196, v197
	v_pk_mul_f32 v[120:121], v[120:121], v[188:189] op_sel_hi:[1,0]
	global_store_dwordx4 v[194:195], v[126:129], off
	v_pk_mul_f32 v[122:123], v[122:123], v[188:189] op_sel_hi:[1,0]
	v_mov_b32_e32 v2, v155
	v_pk_mul_f32 v[126:127], v[152:153], v[120:121] op_sel:[1,1] op_sel_hi:[1,0]
	v_pk_mul_f32 v[116:117], v[116:117], v[188:189] op_sel_hi:[1,0]
	v_pk_fma_f32 v[128:129], v[152:153], v[120:121], v[126:127] op_sel_hi:[0,1,1] neg_lo:[0,0,1] neg_hi:[0,0,1]
	v_pk_fma_f32 v[120:121], v[152:153], v[120:121], v[126:127] op_sel_hi:[0,1,1]
	v_pk_mul_f32 v[126:127], v[2:3], v[122:123] op_sel:[0,1] op_sel_hi:[0,0]
	v_pk_fma_f32 v[130:131], v[154:155], v[122:123], v[126:127] op_sel_hi:[0,1,1] neg_lo:[0,0,1] neg_hi:[0,0,1]
	v_pk_fma_f32 v[122:123], v[154:155], v[122:123], v[126:127] op_sel_hi:[0,1,1]
	v_mov_b32_e32 v129, v121
	v_pk_mul_f32 v[118:119], v[118:119], v[188:189] op_sel_hi:[1,0]
	v_pk_mul_f32 v[126:127], v[144:145], v[116:117] op_sel:[1,1] op_sel_hi:[1,0]
	v_mov_b32_e32 v2, v147
	v_mov_b32_e32 v131, v123
	v_pk_mul_f32 v[120:121], v[128:129], s[0:1] op_sel_hi:[1,0]
	v_pk_fma_f32 v[128:129], v[144:145], v[116:117], v[126:127] op_sel_hi:[0,1,1] neg_lo:[0,0,1] neg_hi:[0,0,1]
	v_pk_fma_f32 v[116:117], v[144:145], v[116:117], v[126:127] op_sel_hi:[0,1,1]
	v_pk_mul_f32 v[126:127], v[2:3], v[118:119] op_sel:[0,1] op_sel_hi:[0,0]
	v_pk_mul_f32 v[122:123], v[130:131], s[0:1] op_sel_hi:[1,0]
	v_pk_fma_f32 v[130:131], v[146:147], v[118:119], v[126:127] op_sel_hi:[0,1,1] neg_lo:[0,0,1] neg_hi:[0,0,1]
	v_pk_fma_f32 v[118:119], v[146:147], v[118:119], v[126:127] op_sel_hi:[0,1,1]
	v_mov_b32_e32 v131, v119
	v_mov_b32_e32 v129, v117
	v_lshlrev_b64 v[116:117], 10, v[158:159]
	v_pk_mul_f32 v[126:127], v[130:131], s[0:1] op_sel_hi:[1,0]
	v_pk_mul_f32 v[118:119], v[128:129], s[0:1] op_sel_hi:[1,0]
	v_lshl_add_u64 v[116:117], s[94:95], 0, v[116:117]
	v_lshl_add_u64 v[128:129], v[116:117], 0, v[124:125]
	v_cvt_pk_bf16_f32 v116, v120, v121
	v_cvt_pk_bf16_f32 v117, v122, v123
	v_cvt_pk_bf16_f32 v118, v118, v119
	v_cvt_pk_bf16_f32 v119, v126, v127
	v_pk_mul_f32 v[112:113], v[112:113], v[190:191] op_sel_hi:[1,0]
	global_store_dwordx4 v[128:129], v[116:119], off
	v_pk_mul_f32 v[114:115], v[114:115], v[190:191] op_sel_hi:[1,0]
	v_mov_b32_e32 v2, v139
	v_pk_mul_f32 v[116:117], v[136:137], v[112:113] op_sel:[1,1] op_sel_hi:[1,0]
	v_pk_mul_f32 v[108:109], v[108:109], v[190:191] op_sel_hi:[1,0]
	v_pk_fma_f32 v[118:119], v[136:137], v[112:113], v[116:117] op_sel_hi:[0,1,1] neg_lo:[0,0,1] neg_hi:[0,0,1]
	v_pk_fma_f32 v[112:113], v[136:137], v[112:113], v[116:117] op_sel_hi:[0,1,1]
	v_pk_mul_f32 v[116:117], v[2:3], v[114:115] op_sel:[0,1] op_sel_hi:[0,0]
	v_pk_fma_f32 v[120:121], v[138:139], v[114:115], v[116:117] op_sel_hi:[0,1,1] neg_lo:[0,0,1] neg_hi:[0,0,1]
	v_pk_fma_f32 v[114:115], v[138:139], v[114:115], v[116:117] op_sel_hi:[0,1,1]
	v_mov_b32_e32 v119, v113
	v_pk_mul_f32 v[110:111], v[110:111], v[190:191] op_sel_hi:[1,0]
	v_pk_mul_f32 v[116:117], v[132:133], v[108:109] op_sel:[1,1] op_sel_hi:[1,0]
	v_mov_b32_e32 v2, v135
	v_mov_b32_e32 v121, v115
	v_pk_mul_f32 v[112:113], v[118:119], s[0:1] op_sel_hi:[1,0]
	v_pk_fma_f32 v[118:119], v[132:133], v[108:109], v[116:117] op_sel_hi:[0,1,1] neg_lo:[0,0,1] neg_hi:[0,0,1]
	v_pk_fma_f32 v[108:109], v[132:133], v[108:109], v[116:117] op_sel_hi:[0,1,1]
	v_pk_mul_f32 v[116:117], v[2:3], v[110:111] op_sel:[0,1] op_sel_hi:[0,0]
	v_pk_mul_f32 v[114:115], v[120:121], s[0:1] op_sel_hi:[1,0]
	v_pk_fma_f32 v[120:121], v[134:135], v[110:111], v[116:117] op_sel_hi:[0,1,1] neg_lo:[0,0,1] neg_hi:[0,0,1]
	v_pk_fma_f32 v[110:111], v[134:135], v[110:111], v[116:117] op_sel_hi:[0,1,1]
	v_mov_b32_e32 v121, v111
	v_mov_b32_e32 v119, v109
	v_lshlrev_b64 v[108:109], 10, v[160:161]
	v_pk_mul_f32 v[116:117], v[120:121], s[0:1] op_sel_hi:[1,0]
	v_pk_mul_f32 v[110:111], v[118:119], s[0:1] op_sel_hi:[1,0]
	v_lshl_add_u64 v[108:109], s[94:95], 0, v[108:109]
	v_lshl_add_u64 v[118:119], v[108:109], 0, v[124:125]
	v_cvt_pk_bf16_f32 v108, v112, v113
	v_cvt_pk_bf16_f32 v109, v114, v115
	v_cvt_pk_bf16_f32 v110, v110, v111
	v_cvt_pk_bf16_f32 v111, v116, v117
	v_pk_mul_f32 v[104:105], v[104:105], v[192:193] op_sel_hi:[1,0]
	global_store_dwordx4 v[118:119], v[108:111], off
	v_pk_mul_f32 v[106:107], v[106:107], v[192:193] op_sel_hi:[1,0]
	v_mov_b32_e32 v2, v151
	v_pk_mul_f32 v[108:109], v[148:149], v[104:105] op_sel:[1,1] op_sel_hi:[1,0]
	v_pk_mul_f32 v[100:101], v[100:101], v[192:193] op_sel_hi:[1,0]
	v_pk_fma_f32 v[110:111], v[148:149], v[104:105], v[108:109] op_sel_hi:[0,1,1] neg_lo:[0,0,1] neg_hi:[0,0,1]
	v_pk_fma_f32 v[104:105], v[148:149], v[104:105], v[108:109] op_sel_hi:[0,1,1]
	v_pk_mul_f32 v[108:109], v[2:3], v[106:107] op_sel:[0,1] op_sel_hi:[0,0]
	v_pk_fma_f32 v[112:113], v[150:151], v[106:107], v[108:109] op_sel_hi:[0,1,1] neg_lo:[0,0,1] neg_hi:[0,0,1]
	v_pk_fma_f32 v[106:107], v[150:151], v[106:107], v[108:109] op_sel_hi:[0,1,1]
	v_mov_b32_e32 v111, v105
	v_pk_mul_f32 v[102:103], v[102:103], v[192:193] op_sel_hi:[1,0]
	v_pk_mul_f32 v[108:109], v[140:141], v[100:101] op_sel:[1,1] op_sel_hi:[1,0]
	v_mov_b32_e32 v2, v143
	v_mov_b32_e32 v113, v107
	v_pk_mul_f32 v[104:105], v[110:111], s[0:1] op_sel_hi:[1,0]
	v_pk_fma_f32 v[110:111], v[140:141], v[100:101], v[108:109] op_sel_hi:[0,1,1] neg_lo:[0,0,1] neg_hi:[0,0,1]
	v_pk_fma_f32 v[100:101], v[140:141], v[100:101], v[108:109] op_sel_hi:[0,1,1]
	v_pk_mul_f32 v[108:109], v[2:3], v[102:103] op_sel:[0,1] op_sel_hi:[0,0]
	v_pk_mul_f32 v[106:107], v[112:113], s[0:1] op_sel_hi:[1,0]
	v_pk_fma_f32 v[112:113], v[142:143], v[102:103], v[108:109] op_sel_hi:[0,1,1] neg_lo:[0,0,1] neg_hi:[0,0,1]
	v_pk_fma_f32 v[102:103], v[142:143], v[102:103], v[108:109] op_sel_hi:[0,1,1]
	v_mov_b32_e32 v113, v103
	v_mov_b32_e32 v111, v101
	v_lshlrev_b64 v[100:101], 10, v[162:163]
	v_pk_mul_f32 v[108:109], v[112:113], s[0:1] op_sel_hi:[1,0]
	v_pk_mul_f32 v[102:103], v[110:111], s[0:1] op_sel_hi:[1,0]
	v_lshl_add_u64 v[100:101], s[94:95], 0, v[100:101]
	v_lshl_add_u64 v[110:111], v[100:101], 0, v[124:125]
	v_cvt_pk_bf16_f32 v100, v104, v105
	v_cvt_pk_bf16_f32 v101, v106, v107
	v_cvt_pk_bf16_f32 v102, v102, v103
	v_cvt_pk_bf16_f32 v103, v108, v109
	global_store_dwordx4 v[110:111], v[100:103], off
	s_cbranch_scc1 .LBB0_166
	v_add_u32_e32 v138, 0x80, v156
	s_movk_i32 s0, 0x7cf
	v_cmp_gt_i32_e32 vcc, s20, v138
	v_and_or_b32 v2, v138, s0, 16
	v_ashrrev_i32_e32 v139, 31, v138
	v_cndmask_b32_e32 v2, v181, v2, vcc
	v_lshl_add_u64 v[112:113], v[138:139], 2, s[70:71]
	v_lshlrev_b32_e32 v2, 8, v2
	v_mov_b32_e32 v148, v246
	v_lshl_add_u64 v[100:101], v[182:183], 0, v[2:3]
	global_load_dwordx4 v[140:143], v[100:101], off offset:16
	global_load_dwordx4 v[144:147], v[100:101], off
	v_add_u32_e32 v126, 0x90, v156
	v_and_b32_e32 v2, 0x7df, v126
	v_cmp_gt_i32_e32 vcc, s20, v126
	v_add_u32_e32 v2, 16, v2
	v_mov_b32_e32 v136, v247
	v_cndmask_b32_e32 v2, v181, v2, vcc
	v_lshlrev_b32_e32 v2, 8, v2
	v_lshl_add_u64 v[100:101], v[182:183], 0, v[2:3]
	global_load_dwordx4 v[108:111], v[100:101], off offset:16
	global_load_dwordx4 v[120:123], v[100:101], off
	v_add_u32_e32 v128, 0xa0, v156
	s_movk_i32 s0, 0x7ef
	v_cmp_gt_i32_e32 vcc, s20, v128
	v_and_or_b32 v2, v128, s0, 16
	v_mov_b32_e32 v132, v248
	v_cndmask_b32_e32 v2, v181, v2, vcc
	v_lshlrev_b32_e32 v2, 8, v2
	v_lshl_add_u64 v[104:105], v[182:183], 0, v[2:3]
	global_load_dwordx4 v[100:103], v[104:105], off offset:16
	s_nop 0
	global_load_dwordx4 v[104:107], v[104:105], off
	v_add_u32_e32 v130, 0xb0, v156
	v_and_b32_e32 v2, 0x7ff, v130
	v_cmp_gt_i32_e32 vcc, s20, v130
	v_add_u32_e32 v2, 16, v2
	v_mov_b32_e32 v134, v249
	v_cndmask_b32_e32 v2, v181, v2, vcc
	v_lshlrev_b32_e32 v2, 8, v2
	v_lshl_add_u64 v[116:117], v[182:183], 0, v[2:3]
	global_load_dwordx4 v[112:115], v[116:117], off offset:16
	s_nop 0
	global_load_dwordx4 v[116:119], v[116:117], off
	s_mov_b32 s0, 0x3e000000
	v_ashrrev_i32_e32 v127, 31, v126
	v_ashrrev_i32_e32 v129, 31, v128
	v_ashrrev_i32_e32 v131, 31, v130
	s_waitcnt vmcnt(0)
	v_pk_mul_f32 v[96:97], v[96:97], v[148:149] op_sel_hi:[1,0]
	v_pk_mul_f32 v[98:99], v[98:99], v[148:149] op_sel_hi:[1,0]
	v_pk_mul_f32 v[150:151], v[144:145], v[96:97] op_sel:[1,1] op_sel_hi:[1,0]
	v_mov_b32_e32 v2, v147
	v_pk_fma_f32 v[152:153], v[144:145], v[96:97], v[150:151] op_sel_hi:[0,1,1] neg_lo:[0,0,1] neg_hi:[0,0,1]
	v_pk_fma_f32 v[96:97], v[144:145], v[96:97], v[150:151] op_sel_hi:[0,1,1]
	v_pk_mul_f32 v[144:145], v[2:3], v[98:99] op_sel:[0,1] op_sel_hi:[0,0]
	v_pk_mul_f32 v[92:93], v[92:93], v[148:149] op_sel_hi:[1,0]
	v_pk_fma_f32 v[150:151], v[146:147], v[98:99], v[144:145] op_sel_hi:[0,1,1] neg_lo:[0,0,1] neg_hi:[0,0,1]
	v_pk_fma_f32 v[98:99], v[146:147], v[98:99], v[144:145] op_sel_hi:[0,1,1]
	v_pk_mul_f32 v[94:95], v[94:95], v[148:149] op_sel_hi:[1,0]
	v_pk_mul_f32 v[144:145], v[140:141], v[92:93] op_sel:[1,1] op_sel_hi:[1,0]
	v_mov_b32_e32 v2, v143
	v_pk_fma_f32 v[146:147], v[140:141], v[92:93], v[144:145] op_sel_hi:[0,1,1] neg_lo:[0,0,1] neg_hi:[0,0,1]
	v_pk_fma_f32 v[92:93], v[140:141], v[92:93], v[144:145] op_sel_hi:[0,1,1]
	v_pk_mul_f32 v[140:141], v[2:3], v[94:95] op_sel:[0,1] op_sel_hi:[0,0]
	v_pk_fma_f32 v[144:145], v[142:143], v[94:95], v[140:141] op_sel_hi:[0,1,1] neg_lo:[0,0,1] neg_hi:[0,0,1]
	v_pk_fma_f32 v[94:95], v[142:143], v[94:95], v[140:141] op_sel_hi:[0,1,1]
	v_mov_b32_e32 v151, v99
	v_mov_b32_e32 v153, v97
	v_mov_b32_e32 v145, v95
	v_mov_b32_e32 v147, v93
	v_lshlrev_b64 v[92:93], 10, v[138:139]
	v_pk_mul_f32 v[98:99], v[150:151], s[0:1] op_sel_hi:[1,0]
	v_pk_mul_f32 v[96:97], v[152:153], s[0:1] op_sel_hi:[1,0]
	v_pk_mul_f32 v[140:141], v[144:145], s[0:1] op_sel_hi:[1,0]
	v_pk_mul_f32 v[94:95], v[146:147], s[0:1] op_sel_hi:[1,0]
	v_lshl_add_u64 v[92:93], s[94:95], 0, v[92:93]
	v_lshl_add_u64 v[138:139], v[92:93], 0, v[124:125]
	v_cvt_pk_bf16_f32 v92, v96, v97
	v_cvt_pk_bf16_f32 v93, v98, v99
	v_cvt_pk_bf16_f32 v94, v94, v95
	v_cvt_pk_bf16_f32 v95, v140, v141
	v_pk_mul_f32 v[88:89], v[88:89], v[136:137] op_sel_hi:[1,0]
	global_store_dwordx4 v[138:139], v[92:95], off
	v_pk_mul_f32 v[90:91], v[90:91], v[136:137] op_sel_hi:[1,0]
	v_mov_b32_e32 v2, v123
	v_pk_mul_f32 v[92:93], v[120:121], v[88:89] op_sel:[1,1] op_sel_hi:[1,0]
	v_pk_mul_f32 v[84:85], v[84:85], v[136:137] op_sel_hi:[1,0]
	v_pk_fma_f32 v[94:95], v[120:121], v[88:89], v[92:93] op_sel_hi:[0,1,1] neg_lo:[0,0,1] neg_hi:[0,0,1]
	v_pk_fma_f32 v[88:89], v[120:121], v[88:89], v[92:93] op_sel_hi:[0,1,1]
	v_pk_mul_f32 v[92:93], v[2:3], v[90:91] op_sel:[0,1] op_sel_hi:[0,0]
	v_pk_fma_f32 v[96:97], v[122:123], v[90:91], v[92:93] op_sel_hi:[0,1,1] neg_lo:[0,0,1] neg_hi:[0,0,1]
	v_pk_fma_f32 v[90:91], v[122:123], v[90:91], v[92:93] op_sel_hi:[0,1,1]
	v_mov_b32_e32 v95, v89
	v_pk_mul_f32 v[86:87], v[86:87], v[136:137] op_sel_hi:[1,0]
	v_pk_mul_f32 v[92:93], v[108:109], v[84:85] op_sel:[1,1] op_sel_hi:[1,0]
	v_mov_b32_e32 v2, v111
	v_mov_b32_e32 v97, v91
	v_pk_mul_f32 v[88:89], v[94:95], s[0:1] op_sel_hi:[1,0]
	v_pk_fma_f32 v[94:95], v[108:109], v[84:85], v[92:93] op_sel_hi:[0,1,1] neg_lo:[0,0,1] neg_hi:[0,0,1]
	v_pk_fma_f32 v[84:85], v[108:109], v[84:85], v[92:93] op_sel_hi:[0,1,1]
	v_pk_mul_f32 v[92:93], v[2:3], v[86:87] op_sel:[0,1] op_sel_hi:[0,0]
	v_pk_mul_f32 v[90:91], v[96:97], s[0:1] op_sel_hi:[1,0]
	v_pk_fma_f32 v[96:97], v[110:111], v[86:87], v[92:93] op_sel_hi:[0,1,1] neg_lo:[0,0,1] neg_hi:[0,0,1]
	v_pk_fma_f32 v[86:87], v[110:111], v[86:87], v[92:93] op_sel_hi:[0,1,1]
	v_mov_b32_e32 v97, v87
	v_mov_b32_e32 v95, v85
	v_lshlrev_b64 v[84:85], 10, v[126:127]
	v_pk_mul_f32 v[92:93], v[96:97], s[0:1] op_sel_hi:[1,0]
	v_pk_mul_f32 v[86:87], v[94:95], s[0:1] op_sel_hi:[1,0]
	v_lshl_add_u64 v[84:85], s[94:95], 0, v[84:85]
	v_lshl_add_u64 v[94:95], v[84:85], 0, v[124:125]
	v_cvt_pk_bf16_f32 v84, v88, v89
	v_cvt_pk_bf16_f32 v85, v90, v91
	v_cvt_pk_bf16_f32 v86, v86, v87
	v_cvt_pk_bf16_f32 v87, v92, v93
	v_pk_mul_f32 v[80:81], v[80:81], v[132:133] op_sel_hi:[1,0]
	global_store_dwordx4 v[94:95], v[84:87], off
	v_pk_mul_f32 v[82:83], v[82:83], v[132:133] op_sel_hi:[1,0]
	v_mov_b32_e32 v2, v107
	v_pk_mul_f32 v[84:85], v[104:105], v[80:81] op_sel:[1,1] op_sel_hi:[1,0]
	v_pk_mul_f32 v[76:77], v[76:77], v[132:133] op_sel_hi:[1,0]
	v_pk_fma_f32 v[86:87], v[104:105], v[80:81], v[84:85] op_sel_hi:[0,1,1] neg_lo:[0,0,1] neg_hi:[0,0,1]
	v_pk_fma_f32 v[80:81], v[104:105], v[80:81], v[84:85] op_sel_hi:[0,1,1]
	v_pk_mul_f32 v[84:85], v[2:3], v[82:83] op_sel:[0,1] op_sel_hi:[0,0]
	v_pk_fma_f32 v[88:89], v[106:107], v[82:83], v[84:85] op_sel_hi:[0,1,1] neg_lo:[0,0,1] neg_hi:[0,0,1]
	v_pk_fma_f32 v[82:83], v[106:107], v[82:83], v[84:85] op_sel_hi:[0,1,1]
	v_mov_b32_e32 v87, v81
	v_pk_mul_f32 v[78:79], v[78:79], v[132:133] op_sel_hi:[1,0]
	v_pk_mul_f32 v[84:85], v[100:101], v[76:77] op_sel:[1,1] op_sel_hi:[1,0]
	v_mov_b32_e32 v2, v103
	v_mov_b32_e32 v89, v83
	v_pk_mul_f32 v[80:81], v[86:87], s[0:1] op_sel_hi:[1,0]
	v_pk_fma_f32 v[86:87], v[100:101], v[76:77], v[84:85] op_sel_hi:[0,1,1] neg_lo:[0,0,1] neg_hi:[0,0,1]
	v_pk_fma_f32 v[76:77], v[100:101], v[76:77], v[84:85] op_sel_hi:[0,1,1]
	v_pk_mul_f32 v[84:85], v[2:3], v[78:79] op_sel:[0,1] op_sel_hi:[0,0]
	v_pk_mul_f32 v[82:83], v[88:89], s[0:1] op_sel_hi:[1,0]
	v_pk_fma_f32 v[88:89], v[102:103], v[78:79], v[84:85] op_sel_hi:[0,1,1] neg_lo:[0,0,1] neg_hi:[0,0,1]
	v_pk_fma_f32 v[78:79], v[102:103], v[78:79], v[84:85] op_sel_hi:[0,1,1]
	v_mov_b32_e32 v89, v79
	v_mov_b32_e32 v87, v77
	v_lshlrev_b64 v[76:77], 10, v[128:129]
	v_pk_mul_f32 v[84:85], v[88:89], s[0:1] op_sel_hi:[1,0]
	v_pk_mul_f32 v[78:79], v[86:87], s[0:1] op_sel_hi:[1,0]
	v_lshl_add_u64 v[76:77], s[94:95], 0, v[76:77]
	v_lshl_add_u64 v[86:87], v[76:77], 0, v[124:125]
	v_cvt_pk_bf16_f32 v76, v80, v81
	v_cvt_pk_bf16_f32 v77, v82, v83
	v_cvt_pk_bf16_f32 v78, v78, v79
	v_cvt_pk_bf16_f32 v79, v84, v85
	v_pk_mul_f32 v[72:73], v[72:73], v[134:135] op_sel_hi:[1,0]
	global_store_dwordx4 v[86:87], v[76:79], off
	v_pk_mul_f32 v[74:75], v[74:75], v[134:135] op_sel_hi:[1,0]
	v_mov_b32_e32 v2, v119
	v_pk_mul_f32 v[76:77], v[116:117], v[72:73] op_sel:[1,1] op_sel_hi:[1,0]
	v_pk_mul_f32 v[68:69], v[68:69], v[134:135] op_sel_hi:[1,0]
	v_pk_fma_f32 v[78:79], v[116:117], v[72:73], v[76:77] op_sel_hi:[0,1,1] neg_lo:[0,0,1] neg_hi:[0,0,1]
	v_pk_fma_f32 v[72:73], v[116:117], v[72:73], v[76:77] op_sel_hi:[0,1,1]
	v_pk_mul_f32 v[76:77], v[2:3], v[74:75] op_sel:[0,1] op_sel_hi:[0,0]
	v_pk_fma_f32 v[80:81], v[118:119], v[74:75], v[76:77] op_sel_hi:[0,1,1] neg_lo:[0,0,1] neg_hi:[0,0,1]
	v_pk_fma_f32 v[74:75], v[118:119], v[74:75], v[76:77] op_sel_hi:[0,1,1]
	v_mov_b32_e32 v79, v73
	v_pk_mul_f32 v[70:71], v[70:71], v[134:135] op_sel_hi:[1,0]
	v_pk_mul_f32 v[76:77], v[112:113], v[68:69] op_sel:[1,1] op_sel_hi:[1,0]
	v_mov_b32_e32 v2, v115
	v_mov_b32_e32 v81, v75
	v_pk_mul_f32 v[72:73], v[78:79], s[0:1] op_sel_hi:[1,0]
	v_pk_fma_f32 v[78:79], v[112:113], v[68:69], v[76:77] op_sel_hi:[0,1,1] neg_lo:[0,0,1] neg_hi:[0,0,1]
	v_pk_fma_f32 v[68:69], v[112:113], v[68:69], v[76:77] op_sel_hi:[0,1,1]
	v_pk_mul_f32 v[76:77], v[2:3], v[70:71] op_sel:[0,1] op_sel_hi:[0,0]
	v_pk_mul_f32 v[74:75], v[80:81], s[0:1] op_sel_hi:[1,0]
	v_pk_fma_f32 v[80:81], v[114:115], v[70:71], v[76:77] op_sel_hi:[0,1,1] neg_lo:[0,0,1] neg_hi:[0,0,1]
	v_pk_fma_f32 v[70:71], v[114:115], v[70:71], v[76:77] op_sel_hi:[0,1,1]
	v_mov_b32_e32 v81, v71
	v_mov_b32_e32 v79, v69
	v_lshlrev_b64 v[68:69], 10, v[130:131]
	v_pk_mul_f32 v[76:77], v[80:81], s[0:1] op_sel_hi:[1,0]
	v_pk_mul_f32 v[70:71], v[78:79], s[0:1] op_sel_hi:[1,0]
	v_lshl_add_u64 v[68:69], s[94:95], 0, v[68:69]
	v_lshl_add_u64 v[78:79], v[68:69], 0, v[124:125]
	v_cvt_pk_bf16_f32 v68, v72, v73
	v_cvt_pk_bf16_f32 v69, v74, v75
	v_cvt_pk_bf16_f32 v70, v70, v71
	v_cvt_pk_bf16_f32 v71, v76, v77
	global_store_dwordx4 v[78:79], v[68:71], off

.Lsec78_b:
	s_lshl_b32 s2, s48, 8
	v_add_u32_e32 v70, s2, v241
	v_ashrrev_i32_e32 v71, 31, v70
	v_lshl_add_u64 v[68:69], v[70:71], 2, s[70:71]
	v_mov_b32_e32 v82, v164
	v_mov_b32_e32 v80, v165
	v_mov_b32_e32 v76, v166
	v_mov_b32_e32 v2, v167
	s_ashr_i32 s75, s74, 31
	s_mov_b32 s2, 0x9ce6000
	s_cmp_eq_u32 s17, 8
	s_cselect_b32 s2, 0xbd25800, s2
	v_or_b32_e32 v78, 16, v70
	v_ashrrev_i32_e32 v79, 31, v78
	v_lshlrev_b64 v[78:79], 11, v[78:79]
	v_lshl_add_u64 v[78:79], s[94:95], 0, v[78:79]
	v_or_b32_e32 v74, 32, v70
	v_ashrrev_i32_e32 v75, 31, v74
	v_lshlrev_b64 v[74:75], 11, v[74:75]
	v_lshl_add_u64 v[74:75], s[94:95], 0, v[74:75]
	v_or_b32_e32 v72, 48, v70
	v_ashrrev_i32_e32 v73, 31, v72
	v_lshlrev_b64 v[72:73], 11, v[72:73]
	v_lshl_add_u64 v[72:73], s[94:95], 0, v[72:73]
	s_cmp_eq_u32 s48, 64
	s_waitcnt vmcnt(0)
	v_pk_mul_f32 v[68:69], v[66:67], v[82:83] op_sel_hi:[1,0]
	s_nop 0
	v_mul_f32_e32 v68, 0xbfb8aa3b, v68
	v_exp_f32_e32 v68, v68
	v_pk_mul_f32 v[84:85], v[64:65], v[82:83] op_sel_hi:[1,0]
	v_add_f32_e32 v68, 1.0, v68
	v_mul_f32_e32 v77, 0xbfb8aa3b, v84
	v_rcp_f32_e32 v84, v68
	v_mul_f32_e32 v68, 0xbfb8aa3b, v69
	v_exp_f32_e32 v68, v68
	v_mul_f32_e32 v81, 0xbfb8aa3b, v85
	v_exp_f32_e32 v77, v77
	v_exp_f32_e32 v81, v81
	v_add_f32_e32 v68, 1.0, v68
	v_rcp_f32_e32 v85, v68
	v_pk_mul_f32 v[68:69], v[62:63], v[82:83] op_sel_hi:[1,0]
	v_pk_mul_f32 v[82:83], v[60:61], v[82:83] op_sel_hi:[1,0]
	v_mul_f32_e32 v68, 0xbfb8aa3b, v68
	v_mul_f32_e32 v82, 0xbfb8aa3b, v82
	v_exp_f32_e32 v68, v68
	v_exp_f32_e32 v82, v82
	v_add_f32_e32 v77, 1.0, v77
	v_add_f32_e32 v81, 1.0, v81
	v_add_f32_e32 v68, 1.0, v68
	v_add_f32_e32 v82, 1.0, v82
	v_rcp_f32_e32 v90, v68
	v_mul_f32_e32 v68, 0xbfb8aa3b, v69
	v_rcp_f32_e32 v88, v82
	v_mul_f32_e32 v82, 0xbfb8aa3b, v83
	v_exp_f32_e32 v68, v68
	v_exp_f32_e32 v82, v82
	v_rcp_f32_e32 v77, v77
	v_rcp_f32_e32 v81, v81
	v_add_f32_e32 v68, 1.0, v68
	v_add_f32_e32 v82, 1.0, v82
	v_rcp_f32_e32 v91, v68
	v_lshlrev_b64 v[68:69], 11, v[70:71]
	v_rcp_f32_e32 v89, v82
	v_lshl_add_u64 v[82:83], s[94:95], 0, v[68:69]
	v_lshl_add_u64 v[68:69], s[74:75], 0, v[178:179]
	v_lshlrev_b64 v[68:69], 1, v[68:69]
	v_lshl_add_u64 v[86:87], v[82:83], 0, v[68:69]
	v_add_co_u32_e32 v86, vcc, s2, v86
	v_cvt_pk_bf16_f32 v82, v77, v81
	v_cvt_pk_bf16_f32 v83, v84, v85
	v_cvt_pk_bf16_f32 v84, v88, v89
	v_cvt_pk_bf16_f32 v85, v90, v91
	v_addc_co_u32_e32 v87, vcc, 0, v87, vcc
	global_store_dwordx4 v[86:87], v[82:85], off offset:768
	s_nop 1
	v_pk_mul_f32 v[82:83], v[58:59], v[80:81] op_sel_hi:[1,0]
	v_pk_mul_f32 v[84:85], v[56:57], v[80:81] op_sel_hi:[1,0]
	v_mul_f32_e32 v81, 0xbfb8aa3b, v82
	v_exp_f32_e32 v81, v81
	v_mul_f32_e32 v71, 0xbfb8aa3b, v84
	v_mul_f32_e32 v77, 0xbfb8aa3b, v85
	v_exp_f32_e32 v71, v71
	v_add_f32_e32 v81, 1.0, v81
	v_rcp_f32_e32 v84, v81
	v_mul_f32_e32 v81, 0xbfb8aa3b, v83
	v_exp_f32_e32 v81, v81
	v_exp_f32_e32 v77, v77
	v_add_f32_e32 v71, 1.0, v71
	v_rcp_f32_e32 v71, v71
	v_add_f32_e32 v81, 1.0, v81
	v_pk_mul_f32 v[82:83], v[54:55], v[80:81] op_sel_hi:[1,0]
	v_rcp_f32_e32 v85, v81
	v_mul_f32_e32 v82, 0xbfb8aa3b, v82
	v_exp_f32_e32 v82, v82
	v_pk_mul_f32 v[80:81], v[52:53], v[80:81] op_sel_hi:[1,0]
	v_add_f32_e32 v77, 1.0, v77
	v_mul_f32_e32 v80, 0xbfb8aa3b, v80
	v_add_f32_e32 v82, 1.0, v82
	v_mul_f32_e32 v81, 0xbfb8aa3b, v81
	v_rcp_f32_e32 v86, v82
	v_mul_f32_e32 v82, 0xbfb8aa3b, v83
	v_exp_f32_e32 v80, v80
	v_exp_f32_e32 v81, v81
	v_exp_f32_e32 v82, v82
	v_rcp_f32_e32 v77, v77
	v_add_f32_e32 v80, 1.0, v80
	v_add_f32_e32 v81, 1.0, v81
	v_add_f32_e32 v82, 1.0, v82
	v_rcp_f32_e32 v80, v80
	v_rcp_f32_e32 v81, v81
	v_rcp_f32_e32 v87, v82
	v_lshl_add_u64 v[82:83], v[78:79], 0, v[68:69]
	v_add_co_u32_e32 v82, vcc, s2, v82
	v_cvt_pk_bf16_f32 v78, v71, v77
	v_cvt_pk_bf16_f32 v79, v84, v85
	v_cvt_pk_bf16_f32 v80, v80, v81
	v_cvt_pk_bf16_f32 v81, v86, v87
	v_addc_co_u32_e32 v83, vcc, 0, v83, vcc
	global_store_dwordx4 v[82:83], v[78:81], off offset:768
	s_nop 1
	v_pk_mul_f32 v[80:81], v[48:49], v[76:77] op_sel_hi:[1,0]
	v_pk_mul_f32 v[78:79], v[50:51], v[76:77] op_sel_hi:[1,0]
	v_mul_f32_e32 v77, 0xbfb8aa3b, v81
	v_exp_f32_e32 v77, v77
	v_mul_f32_e32 v71, 0xbfb8aa3b, v80
	v_exp_f32_e32 v71, v71
	v_add_f32_e32 v77, 1.0, v77
	v_rcp_f32_e32 v80, v77
	v_mul_f32_e32 v77, 0xbfb8aa3b, v78
	v_exp_f32_e32 v77, v77
	v_add_f32_e32 v71, 1.0, v71
	v_rcp_f32_e32 v71, v71
	v_add_f32_e32 v77, 1.0, v77
	v_rcp_f32_e32 v81, v77
	v_mul_f32_e32 v77, 0xbfb8aa3b, v79
	v_exp_f32_e32 v77, v77
	s_nop 0
	v_add_f32_e32 v77, 1.0, v77
	v_pk_mul_f32 v[78:79], v[46:47], v[76:77] op_sel_hi:[1,0]
	v_rcp_f32_e32 v82, v77
	v_mul_f32_e32 v78, 0xbfb8aa3b, v78
	v_exp_f32_e32 v78, v78
	v_pk_mul_f32 v[76:77], v[44:45], v[76:77] op_sel_hi:[1,0]
	v_add_f32_e32 v78, 1.0, v78
	v_mul_f32_e32 v76, 0xbfb8aa3b, v76
	v_mul_f32_e32 v77, 0xbfb8aa3b, v77
	v_rcp_f32_e32 v83, v78
	v_mul_f32_e32 v78, 0xbfb8aa3b, v79
	v_exp_f32_e32 v76, v76
	v_exp_f32_e32 v77, v77
	v_exp_f32_e32 v78, v78
	v_add_f32_e32 v76, 1.0, v76
	v_add_f32_e32 v77, 1.0, v77
	v_add_f32_e32 v78, 1.0, v78
	v_rcp_f32_e32 v76, v76
	v_rcp_f32_e32 v77, v77
	v_rcp_f32_e32 v84, v78
	v_lshl_add_u64 v[78:79], v[74:75], 0, v[68:69]
	v_add_co_u32_e32 v78, vcc, s2, v78
	v_cvt_pk_bf16_f32 v74, v71, v80
	v_cvt_pk_bf16_f32 v75, v81, v82
	v_cvt_pk_bf16_f32 v76, v76, v77
	v_cvt_pk_bf16_f32 v77, v83, v84
	v_addc_co_u32_e32 v79, vcc, 0, v79, vcc
	global_store_dwordx4 v[78:79], v[74:77], off offset:768
	s_nop 1
	v_pk_mul_f32 v[74:75], v[42:43], v[2:3] op_sel_hi:[1,0]
	v_pk_mul_f32 v[76:77], v[40:41], v[2:3] op_sel_hi:[1,0]
	v_mul_f32_e32 v74, 0xbfb8aa3b, v74
	v_exp_f32_e32 v74, v74
	v_mul_f32_e32 v71, 0xbfb8aa3b, v76
	v_mul_f32_e32 v76, 0xbfb8aa3b, v77
	v_exp_f32_e32 v76, v76
	v_add_f32_e32 v74, 1.0, v74
	v_rcp_f32_e32 v79, v74
	v_mul_f32_e32 v74, 0xbfb8aa3b, v75
	v_exp_f32_e32 v74, v74
	v_add_f32_e32 v76, 1.0, v76
	v_rcp_f32_e32 v78, v76
	v_pk_mul_f32 v[76:77], v[36:37], v[2:3] op_sel_hi:[1,0]
	v_add_f32_e32 v74, 1.0, v74
	v_rcp_f32_e32 v80, v74
	v_pk_mul_f32 v[74:75], v[38:39], v[2:3] op_sel_hi:[1,0]
	v_mul_f32_e32 v2, 0xbfb8aa3b, v76
	v_mul_f32_e32 v74, 0xbfb8aa3b, v74
	v_exp_f32_e32 v74, v74
	v_mul_f32_e32 v76, 0xbfb8aa3b, v77
	v_exp_f32_e32 v71, v71
	v_exp_f32_e32 v2, v2
	v_add_f32_e32 v74, 1.0, v74
	v_rcp_f32_e32 v82, v74
	v_mul_f32_e32 v74, 0xbfb8aa3b, v75
	v_exp_f32_e32 v76, v76
	v_exp_f32_e32 v74, v74
	v_add_f32_e32 v71, 1.0, v71
	v_add_f32_e32 v2, 1.0, v2
	v_add_f32_e32 v76, 1.0, v76
	v_add_f32_e32 v74, 1.0, v74
	v_rcp_f32_e32 v71, v71
	v_rcp_f32_e32 v2, v2
	v_rcp_f32_e32 v81, v76
	v_rcp_f32_e32 v75, v74
	v_lshl_add_u64 v[76:77], v[72:73], 0, v[68:69]
	v_add_co_u32_e32 v76, vcc, s2, v76
	v_cvt_pk_bf16_f32 v72, v71, v78
	v_cvt_pk_bf16_f32 v73, v79, v80
	v_cvt_pk_bf16_f32 v74, v2, v81
	v_cvt_pk_bf16_f32 v75, v82, v75
	v_addc_co_u32_e32 v77, vcc, 0, v77, vcc
	global_store_dwordx4 v[76:77], v[72:75], off offset:768
	s_cbranch_scc1 .LBB0_176
	v_add_u32_e32 v80, 0x80, v70
	v_ashrrev_i32_e32 v81, 31, v80
	v_lshl_add_u64 v[82:83], v[80:81], 2, s[70:71]
	v_mov_b32_e32 v84, v246
	v_mov_b32_e32 v78, v247
	v_mov_b32_e32 v74, v248
	v_mov_b32_e32 v2, v249
	v_lshlrev_b64 v[80:81], 11, v[80:81]
	v_lshl_add_u64 v[80:81], s[94:95], 0, v[80:81]
	v_add_u32_e32 v76, 0x90, v70
	v_ashrrev_i32_e32 v77, 31, v76
	v_lshlrev_b64 v[76:77], 11, v[76:77]
	v_lshl_add_u64 v[76:77], s[94:95], 0, v[76:77]
	v_add_u32_e32 v72, 0xa0, v70
	v_ashrrev_i32_e32 v73, 31, v72
	v_lshlrev_b64 v[72:73], 11, v[72:73]
	v_lshl_add_u64 v[72:73], s[94:95], 0, v[72:73]
	v_add_u32_e32 v70, 0xb0, v70
	v_ashrrev_i32_e32 v71, 31, v70
	v_lshlrev_b64 v[70:71], 11, v[70:71]
	v_lshl_add_u64 v[70:71], s[94:95], 0, v[70:71]
	s_waitcnt vmcnt(0)
	v_pk_mul_f32 v[82:83], v[34:35], v[84:85] op_sel_hi:[1,0]
	s_nop 0
	v_mul_f32_e32 v82, 0xbfb8aa3b, v82
	v_exp_f32_e32 v82, v82
	v_pk_mul_f32 v[86:87], v[32:33], v[84:85] op_sel_hi:[1,0]
	v_add_f32_e32 v82, 1.0, v82
	v_mul_f32_e32 v75, 0xbfb8aa3b, v86
	v_rcp_f32_e32 v86, v82
	v_mul_f32_e32 v82, 0xbfb8aa3b, v83
	v_exp_f32_e32 v82, v82
	v_mul_f32_e32 v79, 0xbfb8aa3b, v87
	v_exp_f32_e32 v75, v75
	v_exp_f32_e32 v79, v79
	v_add_f32_e32 v82, 1.0, v82
	v_rcp_f32_e32 v87, v82
	v_pk_mul_f32 v[82:83], v[30:31], v[84:85] op_sel_hi:[1,0]
	v_pk_mul_f32 v[84:85], v[28:29], v[84:85] op_sel_hi:[1,0]
	v_mul_f32_e32 v82, 0xbfb8aa3b, v82
	v_mul_f32_e32 v84, 0xbfb8aa3b, v84
	v_exp_f32_e32 v84, v84
	v_exp_f32_e32 v82, v82
	v_add_f32_e32 v75, 1.0, v75
	v_add_f32_e32 v79, 1.0, v79
	v_add_f32_e32 v84, 1.0, v84
	v_add_f32_e32 v82, 1.0, v82
	v_rcp_f32_e32 v88, v84
	v_mul_f32_e32 v84, 0xbfb8aa3b, v85
	v_rcp_f32_e32 v90, v82
	v_mul_f32_e32 v82, 0xbfb8aa3b, v83
	v_exp_f32_e32 v84, v84
	v_exp_f32_e32 v82, v82
	v_rcp_f32_e32 v75, v75
	v_rcp_f32_e32 v79, v79
	v_add_f32_e32 v84, 1.0, v84
	v_add_f32_e32 v82, 1.0, v82
	v_rcp_f32_e32 v89, v84
	v_rcp_f32_e32 v83, v82
	v_lshl_add_u64 v[84:85], v[80:81], 0, v[68:69]
	v_add_co_u32_e32 v84, vcc, s2, v84
	v_cvt_pk_bf16_f32 v80, v75, v79
	v_cvt_pk_bf16_f32 v81, v86, v87
	v_cvt_pk_bf16_f32 v82, v88, v89
	v_cvt_pk_bf16_f32 v83, v90, v83
	v_addc_co_u32_e32 v85, vcc, 0, v85, vcc
	global_store_dwordx4 v[84:85], v[80:83], off offset:768
	s_nop 1
	v_pk_mul_f32 v[82:83], v[24:25], v[78:79] op_sel_hi:[1,0]
	v_pk_mul_f32 v[80:81], v[26:27], v[78:79] op_sel_hi:[1,0]
	v_mul_f32_e32 v79, 0xbfb8aa3b, v83
	v_exp_f32_e32 v79, v79
	v_mul_f32_e32 v75, 0xbfb8aa3b, v82
	v_exp_f32_e32 v75, v75
	v_add_f32_e32 v79, 1.0, v79
	v_rcp_f32_e32 v82, v79
	v_mul_f32_e32 v79, 0xbfb8aa3b, v80
	v_exp_f32_e32 v79, v79
	v_add_f32_e32 v75, 1.0, v75
	v_rcp_f32_e32 v75, v75
	v_add_f32_e32 v79, 1.0, v79
	v_rcp_f32_e32 v83, v79
	v_mul_f32_e32 v79, 0xbfb8aa3b, v81
	v_exp_f32_e32 v79, v79
	s_nop 0
	v_add_f32_e32 v79, 1.0, v79
	v_pk_mul_f32 v[80:81], v[22:23], v[78:79] op_sel_hi:[1,0]
	v_rcp_f32_e32 v84, v79
	v_mul_f32_e32 v80, 0xbfb8aa3b, v80
	v_exp_f32_e32 v80, v80
	v_pk_mul_f32 v[78:79], v[20:21], v[78:79] op_sel_hi:[1,0]
	v_add_f32_e32 v80, 1.0, v80
	v_mul_f32_e32 v78, 0xbfb8aa3b, v78
	v_mul_f32_e32 v79, 0xbfb8aa3b, v79
	v_rcp_f32_e32 v85, v80
	v_mul_f32_e32 v80, 0xbfb8aa3b, v81
	v_exp_f32_e32 v78, v78
	v_exp_f32_e32 v79, v79
	v_exp_f32_e32 v80, v80
	v_add_f32_e32 v78, 1.0, v78
	v_add_f32_e32 v79, 1.0, v79
	v_add_f32_e32 v80, 1.0, v80
	v_rcp_f32_e32 v78, v78
	v_rcp_f32_e32 v79, v79
	v_rcp_f32_e32 v86, v80
	v_lshl_add_u64 v[80:81], v[76:77], 0, v[68:69]
	v_add_co_u32_e32 v80, vcc, s2, v80
	v_cvt_pk_bf16_f32 v76, v75, v82
	v_cvt_pk_bf16_f32 v77, v83, v84
	v_cvt_pk_bf16_f32 v78, v78, v79
	v_cvt_pk_bf16_f32 v79, v85, v86
	v_addc_co_u32_e32 v81, vcc, 0, v81, vcc
	global_store_dwordx4 v[80:81], v[76:79], off offset:768
	s_nop 1
	v_pk_mul_f32 v[78:79], v[16:17], v[74:75] op_sel_hi:[1,0]
	v_pk_mul_f32 v[76:77], v[18:19], v[74:75] op_sel_hi:[1,0]
	v_mul_f32_e32 v75, 0xbfb8aa3b, v78
	v_exp_f32_e32 v75, v75
	s_nop 0
	v_add_f32_e32 v75, 1.0, v75
	v_rcp_f32_e32 v78, v75
	v_mul_f32_e32 v75, 0xbfb8aa3b, v79
	v_exp_f32_e32 v75, v75
	s_nop 0
	v_add_f32_e32 v75, 1.0, v75
	v_rcp_f32_e32 v79, v75
	v_mul_f32_e32 v75, 0xbfb8aa3b, v76
	v_exp_f32_e32 v75, v75
	s_nop 0
	v_add_f32_e32 v75, 1.0, v75
	v_rcp_f32_e32 v80, v75
	v_mul_f32_e32 v75, 0xbfb8aa3b, v77
	v_exp_f32_e32 v75, v75
	s_nop 0
	v_add_f32_e32 v75, 1.0, v75
	v_pk_mul_f32 v[76:77], v[14:15], v[74:75] op_sel_hi:[1,0]
	v_rcp_f32_e32 v81, v75
	v_mul_f32_e32 v76, 0xbfb8aa3b, v76
	v_exp_f32_e32 v76, v76
	v_pk_mul_f32 v[74:75], v[12:13], v[74:75] op_sel_hi:[1,0]
	v_add_f32_e32 v76, 1.0, v76
	v_mul_f32_e32 v74, 0xbfb8aa3b, v74
	v_mul_f32_e32 v75, 0xbfb8aa3b, v75
	v_rcp_f32_e32 v82, v76
	v_mul_f32_e32 v76, 0xbfb8aa3b, v77
	v_exp_f32_e32 v74, v74
	v_exp_f32_e32 v75, v75
	v_exp_f32_e32 v76, v76
	v_add_f32_e32 v74, 1.0, v74
	v_add_f32_e32 v75, 1.0, v75
	v_add_f32_e32 v76, 1.0, v76
	v_rcp_f32_e32 v74, v74
	v_rcp_f32_e32 v75, v75
	v_rcp_f32_e32 v83, v76
	v_lshl_add_u64 v[76:77], v[72:73], 0, v[68:69]
	v_add_co_u32_e32 v76, vcc, s2, v76
	v_cvt_pk_bf16_f32 v72, v78, v79
	v_cvt_pk_bf16_f32 v73, v80, v81
	v_cvt_pk_bf16_f32 v74, v74, v75
	v_cvt_pk_bf16_f32 v75, v82, v83
	v_addc_co_u32_e32 v77, vcc, 0, v77, vcc
	global_store_dwordx4 v[76:77], v[72:75], off offset:768
	s_nop 1
	v_pk_mul_f32 v[72:73], v[10:11], v[2:3] op_sel_hi:[1,0]
	v_pk_mul_f32 v[74:75], v[8:9], v[2:3] op_sel_hi:[1,0]
	v_mul_f32_e32 v72, 0xbfb8aa3b, v72
	v_exp_f32_e32 v72, v72
	v_mul_f32_e32 v74, 0xbfb8aa3b, v74
	v_exp_f32_e32 v74, v74
	v_add_f32_e32 v72, 1.0, v72
	v_rcp_f32_e32 v78, v72
	v_mul_f32_e32 v72, 0xbfb8aa3b, v73
	v_exp_f32_e32 v72, v72
	v_add_f32_e32 v74, 1.0, v74
	v_rcp_f32_e32 v76, v74
	v_mul_f32_e32 v74, 0xbfb8aa3b, v75
	v_add_f32_e32 v72, 1.0, v72
	v_rcp_f32_e32 v79, v72
	v_pk_mul_f32 v[72:73], v[6:7], v[2:3] op_sel_hi:[1,0]
	v_exp_f32_e32 v74, v74
	v_mul_f32_e32 v72, 0xbfb8aa3b, v72
	v_exp_f32_e32 v72, v72
	v_add_f32_e32 v74, 1.0, v74
	v_rcp_f32_e32 v77, v74
	v_pk_mul_f32 v[74:75], v[4:5], v[2:3] op_sel_hi:[1,0]
	v_add_f32_e32 v72, 1.0, v72
	v_mul_f32_e32 v2, 0xbfb8aa3b, v74
	v_mul_f32_e32 v74, 0xbfb8aa3b, v75
	v_rcp_f32_e32 v75, v72
	v_mul_f32_e32 v72, 0xbfb8aa3b, v73
	v_exp_f32_e32 v2, v2
	v_exp_f32_e32 v74, v74
	v_exp_f32_e32 v72, v72
	v_add_f32_e32 v2, 1.0, v2
	v_add_f32_e32 v74, 1.0, v74
	v_add_f32_e32 v72, 1.0, v72
	v_rcp_f32_e32 v2, v2
	v_rcp_f32_e32 v74, v74
	v_rcp_f32_e32 v80, v72
	v_lshl_add_u64 v[72:73], v[70:71], 0, v[68:69]
	v_add_co_u32_e32 v72, vcc, s2, v72
	v_cvt_pk_bf16_f32 v68, v76, v77
	v_cvt_pk_bf16_f32 v69, v78, v79
	v_cvt_pk_bf16_f32 v70, v2, v74
	v_cvt_pk_bf16_f32 v71, v75, v80
	v_addc_co_u32_e32 v73, vcc, 0, v73, vcc
	global_store_dwordx4 v[72:73], v[68:71], off offset:768

.LBB0_178:
	s_and_b64 vcc, exec, s[4:5]
	s_cbranch_vccz .LBB0_181
	s_lshl_b32 s4, s48, 8
	s_add_i32 s4, s4, s31
	v_or_b32_e32 v70, s4, v181
	v_ashrrev_i32_e32 v71, 31, v70
	v_lshl_add_u64 v[78:79], v[70:71], 2, s[70:71]
	v_mov_b32_e32 v80, v164
	v_mov_b32_e32 v82, v165
	v_mov_b32_e32 v74, v166
	v_mov_b32_e32 v72, v167
	s_or_b32 s5, s16, s49
	v_or_b32_e32 v2, s5, v242
	s_add_i32 s20, s5, 0xfffff180
	s_add_i32 s21, s4, 0xffffc000
	s_movk_i32 s36, 0x4000
	v_bitop3_b32 v76, s5, 56, v242 bitop3:0xc8
	s_ashr_i32 s5, s20, 6
	v_add_u32_e32 v2, 0xfffff184, v2
	s_ashr_i32 s20, s4, 11
	v_bitop3_b32 v71, s4, v250, v181 bitop3:0xc8
	s_lshr_b32 s21, s21, 4
	v_ashrrev_i32_e32 v75, 6, v2
	v_add_u32_e32 v2, 0x80, v71
	v_mov_b32_e32 v71, s20
	v_mov_b32_e32 v81, s21
	v_cmp_gt_i32_e32 vcc, s36, v70
	v_mov_b64_e32 v[68:69], s[92:93]
	v_or_b32_e32 v73, 4, v76
	v_cndmask_b32_e32 v78, v81, v71, vcc
	v_lshlrev_b32_e32 v79, 1, v78
	v_add_u32_e32 v78, s5, v79
	v_add_u32_e32 v84, v79, v75
	v_ashrrev_i32_e32 v79, 31, v78
	v_lshlrev_b64 v[78:79], 6, v[78:79]
	v_or_b32_e32 v78, v78, v76
	v_cndmask_b32_e32 v2, v244, v2, vcc
	v_ashrrev_i32_e32 v85, 31, v84
	v_mad_u64_u32 v[86:87], s[20:21], v78, s89, v[68:69]
	v_lshlrev_b32_e32 v2, 1, v2
	v_lshlrev_b64 v[84:85], 6, v[84:85]
	v_mad_i32_i24 v87, v79, s89, v87
	v_or_b32_e32 v81, v84, v73
	v_lshl_add_u64 v[78:79], v[86:87], 0, v[2:3]
	s_movk_i32 s40, 0x1000
	v_mad_u64_u32 v[88:89], s[20:21], v81, s89, v[68:69]
	v_add_co_u32_e32 v86, vcc, s40, v78
	v_mad_i32_i24 v89, v85, s89, v89
	s_nop 0
	v_addc_co_u32_e32 v87, vcc, 0, v79, vcc
	s_movk_i32 s37, 0x2000
	v_lshl_add_u64 v[84:85], v[88:89], 0, v[2:3]
	v_add_co_u32_e32 v88, vcc, s37, v78
	s_movk_i32 s41, 0x3000
	s_nop 0
	v_addc_co_u32_e32 v89, vcc, 0, v79, vcc
	v_add_co_u32_e32 v90, vcc, s41, v78
	s_movk_i32 s20, 0x7df
	s_nop 0
	v_addc_co_u32_e32 v91, vcc, 0, v79, vcc
	v_add_co_u32_e32 v92, vcc, s40, v84
	v_or_b32_e32 v77, 16, v70
	s_nop 0
	v_addc_co_u32_e32 v93, vcc, 0, v85, vcc
	v_add_co_u32_e32 v94, vcc, s37, v84
	v_or_b32_e32 v102, 32, v70
	s_nop 0
	v_addc_co_u32_e32 v95, vcc, 0, v85, vcc
	v_or_b32_e32 v103, 48, v70
	s_waitcnt vmcnt(0)
	v_pk_mul_f32 v[98:99], v[64:65], v[80:81] op_sel_hi:[1,0]
	v_pk_mul_f32 v[96:97], v[66:67], v[80:81] op_sel_hi:[1,0]
	v_pk_mul_f32 v[100:101], v[62:63], v[80:81] op_sel_hi:[1,0]
	v_pk_mul_f32 v[80:81], v[60:61], v[80:81] op_sel_hi:[1,0]
	v_cvt_pk_bf16_f32 v2, v98, s0
	v_cvt_pk_bf16_f32 v83, v99, s0
	v_cvt_pk_bf16_f32 v96, v96, s0
	v_cvt_pk_bf16_f32 v97, v97, s0
	v_cvt_pk_bf16_f32 v80, v80, s0
	v_cvt_pk_bf16_f32 v81, v81, s0
	v_cvt_pk_bf16_f32 v98, v100, s0
	global_store_short v[78:79], v2, off
	global_store_short v[86:87], v83, off offset:256
	global_store_short v[88:89], v96, off offset:512
	global_store_short v[90:91], v97, off offset:768
	global_store_short v[84:85], v80, off
	global_store_short v[92:93], v81, off offset:256
	global_store_short v[94:95], v98, off offset:512
	v_add_co_u32_e32 v78, vcc, s41, v84
	v_bitop3_b32 v2, v70, s20, 16 bitop3:0xc8
	s_add_i32 s20, s4, 0xffffc010
	v_cvt_pk_bf16_f32 v99, v101, s0
	v_addc_co_u32_e32 v79, vcc, 0, v85, vcc
	s_lshr_b32 s20, s20, 4
	global_store_short v[78:79], v99, off offset:768
	v_pk_mul_f32 v[78:79], v[58:59], v[82:83] op_sel_hi:[1,0]
	v_pk_mul_f32 v[80:81], v[56:57], v[82:83] op_sel_hi:[1,0]
	v_mov_b32_e32 v83, s20
	v_cmp_gt_i32_e32 vcc, s36, v77
	v_add_u32_e32 v2, 0x80, v2
	v_cvt_pk_bf16_f32 v80, v80, s0
	v_cndmask_b32_e32 v77, v83, v71, vcc
	v_lshlrev_b32_e32 v77, 1, v77
	v_add_u32_e32 v84, s5, v77
	v_ashrrev_i32_e32 v85, 31, v84
	v_lshlrev_b64 v[84:85], 6, v[84:85]
	v_or_b32_e32 v83, v84, v76
	v_cndmask_b32_e32 v2, v244, v2, vcc
	v_mad_u64_u32 v[86:87], s[20:21], v83, s89, v[68:69]
	v_mad_i32_i24 v87, v85, s89, v87
	v_lshlrev_b32_e32 v2, 1, v2
	v_lshl_add_u64 v[84:85], v[86:87], 0, v[2:3]
	global_store_short v[84:85], v80, off
	v_add_co_u32_e32 v80, vcc, s40, v84
	v_cvt_pk_bf16_f32 v83, v81, s0
	s_nop 0
	v_addc_co_u32_e32 v81, vcc, 0, v85, vcc
	global_store_short v[80:81], v83, off offset:256
	v_add_co_u32_e32 v80, vcc, s37, v84
	v_cvt_pk_bf16_f32 v78, v78, s0
	s_nop 0
	v_addc_co_u32_e32 v81, vcc, 0, v85, vcc
	global_store_short v[80:81], v78, off offset:512
	v_add_co_u32_e32 v78, vcc, s41, v84
	v_cvt_pk_bf16_f32 v80, v79, s0
	s_nop 0
	v_addc_co_u32_e32 v79, vcc, 0, v85, vcc
	global_store_short v[78:79], v80, off offset:768
	v_pk_mul_f32 v[78:79], v[54:55], v[82:83] op_sel_hi:[1,0]
	v_pk_mul_f32 v[80:81], v[52:53], v[82:83] op_sel_hi:[1,0]
	v_add_u32_e32 v82, v77, v75
	v_ashrrev_i32_e32 v83, 31, v82
	v_lshlrev_b64 v[82:83], 6, v[82:83]
	v_or_b32_e32 v77, v82, v73
	v_mad_u64_u32 v[84:85], s[20:21], v77, s89, v[68:69]
	v_mad_i32_i24 v85, v83, s89, v85
	v_lshl_add_u64 v[82:83], v[84:85], 0, v[2:3]
	v_cvt_pk_bf16_f32 v2, v80, s0
	v_add_co_u32_e32 v80, vcc, s40, v82
	global_store_short v[82:83], v2, off
	v_cvt_pk_bf16_f32 v2, v81, s0
	v_addc_co_u32_e32 v81, vcc, 0, v83, vcc
	global_store_short v[80:81], v2, off offset:256
	v_add_co_u32_e32 v80, vcc, s37, v82
	v_cvt_pk_bf16_f32 v2, v78, s0
	s_nop 0
	v_addc_co_u32_e32 v81, vcc, 0, v83, vcc
	v_add_co_u32_e32 v78, vcc, s41, v82
	global_store_short v[80:81], v2, off offset:512
	v_cvt_pk_bf16_f32 v2, v79, s0
	v_addc_co_u32_e32 v79, vcc, 0, v83, vcc
	s_movk_i32 s20, 0x7ef
	global_store_short v[78:79], v2, off offset:768
	v_bitop3_b32 v2, v70, s20, 32 bitop3:0xc8
	s_add_i32 s20, s4, 0xffffc020
	s_lshr_b32 s20, s20, 4
	v_mov_b32_e32 v77, s20
	v_cmp_gt_i32_e32 vcc, s36, v102
	v_add_u32_e32 v2, 0x80, v2
	v_pk_mul_f32 v[80:81], v[48:49], v[74:75] op_sel_hi:[1,0]
	v_cndmask_b32_e32 v77, v77, v71, vcc
	v_lshlrev_b32_e32 v77, 1, v77
	v_add_u32_e32 v82, s5, v77
	v_ashrrev_i32_e32 v83, 31, v82
	v_lshlrev_b64 v[82:83], 6, v[82:83]
	v_or_b32_e32 v82, v82, v76
	v_cndmask_b32_e32 v2, v244, v2, vcc
	v_mad_u64_u32 v[84:85], s[20:21], v82, s89, v[68:69]
	v_mad_i32_i24 v85, v83, s89, v85
	v_lshlrev_b32_e32 v2, 1, v2
	v_lshl_add_u64 v[82:83], v[84:85], 0, v[2:3]
	v_cvt_pk_bf16_f32 v80, v80, s0
	global_store_short v[82:83], v80, off
	v_add_co_u32_e32 v80, vcc, s40, v82
	v_cvt_pk_bf16_f32 v84, v81, s0
	s_nop 0
	v_addc_co_u32_e32 v81, vcc, 0, v83, vcc
	v_pk_mul_f32 v[78:79], v[50:51], v[74:75] op_sel_hi:[1,0]
	global_store_short v[80:81], v84, off offset:256
	v_add_co_u32_e32 v80, vcc, s37, v82
	v_cvt_pk_bf16_f32 v78, v78, s0
	s_nop 0
	v_addc_co_u32_e32 v81, vcc, 0, v83, vcc
	global_store_short v[80:81], v78, off offset:512
	v_add_co_u32_e32 v78, vcc, s41, v82
	v_add_u32_e32 v82, v77, v75
	v_cvt_pk_bf16_f32 v80, v79, s0
	v_addc_co_u32_e32 v79, vcc, 0, v83, vcc
	v_ashrrev_i32_e32 v83, 31, v82
	v_lshlrev_b64 v[82:83], 6, v[82:83]
	global_store_short v[78:79], v80, off offset:768
	v_pk_mul_f32 v[78:79], v[46:47], v[74:75] op_sel_hi:[1,0]
	v_pk_mul_f32 v[80:81], v[44:45], v[74:75] op_sel_hi:[1,0]
	v_or_b32_e32 v74, v82, v73
	v_mad_u64_u32 v[84:85], s[20:21], v74, s89, v[68:69]
	v_mad_i32_i24 v85, v83, s89, v85
	v_lshl_add_u64 v[82:83], v[84:85], 0, v[2:3]
	v_cvt_pk_bf16_f32 v2, v80, s0
	v_add_co_u32_e32 v80, vcc, s40, v82
	global_store_short v[82:83], v2, off
	v_cvt_pk_bf16_f32 v2, v81, s0
	v_addc_co_u32_e32 v81, vcc, 0, v83, vcc
	global_store_short v[80:81], v2, off offset:256
	v_add_co_u32_e32 v80, vcc, s37, v82
	v_cvt_pk_bf16_f32 v2, v78, s0
	s_nop 0
	v_addc_co_u32_e32 v81, vcc, 0, v83, vcc
	v_add_co_u32_e32 v78, vcc, s41, v82
	global_store_short v[80:81], v2, off offset:512
	v_cvt_pk_bf16_f32 v2, v79, s0
	v_addc_co_u32_e32 v79, vcc, 0, v83, vcc
	s_movk_i32 s20, 0x7ff
	global_store_short v[78:79], v2, off offset:768
	v_bitop3_b32 v2, v70, s20, 48 bitop3:0xc8
	s_add_i32 s20, s4, 0xffffc030
	s_lshr_b32 s20, s20, 4
	v_mov_b32_e32 v70, s20
	v_cmp_gt_i32_e32 vcc, s36, v103
	v_add_u32_e32 v2, 0x80, v2
	v_pk_mul_f32 v[80:81], v[40:41], v[72:73] op_sel_hi:[1,0]
	v_cndmask_b32_e32 v70, v70, v71, vcc
	v_lshlrev_b32_e32 v74, 1, v70
	v_add_u32_e32 v70, s5, v74
	v_ashrrev_i32_e32 v71, 31, v70
	v_lshlrev_b64 v[70:71], 6, v[70:71]
	v_or_b32_e32 v70, v70, v76
	v_cndmask_b32_e32 v2, v244, v2, vcc
	v_mad_u64_u32 v[82:83], s[20:21], v70, s89, v[68:69]
	v_mad_i32_i24 v83, v71, s89, v83
	v_lshlrev_b32_e32 v2, 1, v2
	v_lshl_add_u64 v[70:71], v[82:83], 0, v[2:3]
	v_cvt_pk_bf16_f32 v77, v80, s0
	v_add_co_u32_e32 v80, vcc, s40, v70
	global_store_short v[70:71], v77, off
	v_cvt_pk_bf16_f32 v77, v81, s0
	v_addc_co_u32_e32 v81, vcc, 0, v71, vcc
	v_pk_mul_f32 v[78:79], v[42:43], v[72:73] op_sel_hi:[1,0]
	global_store_short v[80:81], v77, off offset:256
	v_add_co_u32_e32 v80, vcc, s37, v70
	v_cvt_pk_bf16_f32 v77, v78, s0
	s_nop 0
	v_addc_co_u32_e32 v81, vcc, 0, v71, vcc
	global_store_short v[80:81], v77, off offset:512
	v_add_u32_e32 v80, v74, v75
	v_add_co_u32_e32 v70, vcc, s41, v70
	v_ashrrev_i32_e32 v81, 31, v80
	v_cvt_pk_bf16_f32 v77, v79, s0
	v_addc_co_u32_e32 v71, vcc, 0, v71, vcc
	v_lshlrev_b64 v[80:81], 6, v[80:81]
	global_store_short v[70:71], v77, off offset:768
	v_pk_mul_f32 v[70:71], v[38:39], v[72:73] op_sel_hi:[1,0]
	v_pk_mul_f32 v[78:79], v[36:37], v[72:73] op_sel_hi:[1,0]
	v_or_b32_e32 v72, v80, v73
	v_mad_u64_u32 v[68:69], s[20:21], v72, s89, v[68:69]
	v_mad_i32_i24 v69, v81, s89, v69
	v_lshl_add_u64 v[68:69], v[68:69], 0, v[2:3]
	v_cvt_pk_bf16_f32 v2, v78, s0
	v_add_co_u32_e32 v78, vcc, 0x1000, v68
	global_store_short v[68:69], v2, off
	v_cvt_pk_bf16_f32 v2, v79, s0
	v_addc_co_u32_e32 v79, vcc, 0, v69, vcc
	global_store_short v[78:79], v2, off offset:256
	v_add_co_u32_e32 v78, vcc, 0x2000, v68
	v_cvt_pk_bf16_f32 v2, v70, s0
	s_nop 0
	v_addc_co_u32_e32 v79, vcc, 0, v69, vcc
	v_add_co_u32_e32 v68, vcc, 0x3000, v68
	s_movk_i32 s20, 0x4000
	global_store_short v[78:79], v2, off offset:512
	v_cvt_pk_bf16_f32 v2, v71, s0
	v_addc_co_u32_e32 v69, vcc, 0, v69, vcc
	s_cmp_eq_u32 s48, 64
	global_store_short v[68:69], v2, off offset:768
	s_cbranch_scc1 .LBB0_181
	s_add_i32 s20, s4, 0x80
	v_or_b32_e32 v70, s20, v181
	v_ashrrev_i32_e32 v71, 31, v70
	v_lshl_add_u64 v[78:79], v[70:71], 2, s[70:71]
	v_mov_b32_e32 v74, v246
	v_mov_b32_e32 v80, v247
	s_add_i32 s21, s4, 0xffffc080
	s_movk_i32 s37, 0x4000
	s_ashr_i32 s36, s20, 11
	v_bitop3_b32 v2, s20, v250, v181 bitop3:0xc8
	s_lshr_b32 s20, s21, 4
	v_mov_b32_e32 v72, s20
	v_mov_b32_e32 v111, s36
	v_cmp_gt_i32_e32 vcc, s37, v70
	v_mov_b64_e32 v[68:69], s[92:93]
	v_add_u32_e32 v2, 0x80, v2
	v_cndmask_b32_e32 v83, v72, v111, vcc
	v_mov_b32_e32 v82, v248
	v_mov_b32_e32 v72, v249
	v_lshlrev_b32_e32 v79, 1, v83
	v_add_u32_e32 v78, s5, v79
	v_add_u32_e32 v84, v79, v75
	v_ashrrev_i32_e32 v79, 31, v78
	v_lshlrev_b64 v[78:79], 6, v[78:79]
	s_movk_i32 s20, 0x7df
	v_or_b32_e32 v78, v78, v76
	v_bitop3_b32 v81, v70, s20, 16 bitop3:0xc8
	v_cndmask_b32_e32 v2, v244, v2, vcc
	v_ashrrev_i32_e32 v85, 31, v84
	v_mad_u64_u32 v[86:87], s[20:21], v78, s89, v[68:69]
	v_lshlrev_b32_e32 v2, 1, v2
	v_lshlrev_b64 v[84:85], 6, v[84:85]
	v_mad_i32_i24 v87, v79, s89, v87
	v_or_b32_e32 v83, v84, v73
	v_lshl_add_u64 v[78:79], v[86:87], 0, v[2:3]
	v_mad_u64_u32 v[88:89], s[20:21], v83, s89, v[68:69]
	v_add_co_u32_e32 v86, vcc, s40, v78
	v_mad_i32_i24 v89, v85, s89, v89
	s_nop 0
	v_addc_co_u32_e32 v87, vcc, 0, v79, vcc
	s_movk_i32 s36, 0x2000
	v_lshl_add_u64 v[84:85], v[88:89], 0, v[2:3]
	v_add_co_u32_e32 v88, vcc, s36, v78
	s_add_i32 s20, s4, 0xffffc090
	s_nop 0
	v_addc_co_u32_e32 v89, vcc, 0, v79, vcc
	v_add_co_u32_e32 v90, vcc, s41, v78
	v_or_b32_e32 v71, 16, v70
	s_nop 0
	v_addc_co_u32_e32 v91, vcc, 0, v79, vcc
	v_add_co_u32_e32 v92, vcc, s40, v84
	s_lshr_b32 s20, s20, 4
	s_nop 0
	v_addc_co_u32_e32 v93, vcc, 0, v85, vcc
	v_add_co_u32_e32 v94, vcc, s36, v84
	v_or_b32_e32 v77, 32, v70
	s_nop 0
	v_addc_co_u32_e32 v95, vcc, 0, v85, vcc
	v_add_co_u32_e32 v96, vcc, s41, v84
	v_or_b32_e32 v110, 48, v70
	s_nop 0
	v_addc_co_u32_e32 v97, vcc, 0, v85, vcc
	v_cmp_gt_i32_e32 vcc, s37, v71
	s_waitcnt vmcnt(0)
	v_pk_mul_f32 v[100:101], v[32:33], v[74:75] op_sel_hi:[1,0]
	v_pk_mul_f32 v[98:99], v[34:35], v[74:75] op_sel_hi:[1,0]
	v_pk_mul_f32 v[102:103], v[30:31], v[74:75] op_sel_hi:[1,0]
	v_pk_mul_f32 v[104:105], v[28:29], v[74:75] op_sel_hi:[1,0]
	v_cvt_pk_bf16_f32 v2, v100, s0
	v_cvt_pk_bf16_f32 v74, v101, s0
	v_cvt_pk_bf16_f32 v83, v98, s0
	v_cvt_pk_bf16_f32 v98, v99, s0
	v_cvt_pk_bf16_f32 v99, v104, s0
	v_cvt_pk_bf16_f32 v100, v105, s0
	v_cvt_pk_bf16_f32 v101, v102, s0
	v_cvt_pk_bf16_f32 v102, v103, s0
	global_store_short v[78:79], v2, off
	global_store_short v[86:87], v74, off offset:256
	global_store_short v[88:89], v83, off offset:512
	global_store_short v[90:91], v98, off offset:768
	global_store_short v[84:85], v99, off
	global_store_short v[92:93], v100, off offset:256
	global_store_short v[94:95], v101, off offset:512
	global_store_short v[96:97], v102, off offset:768
	v_mov_b32_e32 v74, s20
	v_cndmask_b32_e32 v71, v74, v111, vcc
	v_lshlrev_b32_e32 v71, 1, v71
	v_add_u32_e32 v78, s5, v71
	v_ashrrev_i32_e32 v79, 31, v78
	v_lshlrev_b64 v[78:79], 6, v[78:79]
	v_add_u32_e32 v2, 0x80, v81
	v_or_b32_e32 v74, v78, v76
	v_cndmask_b32_e32 v2, v244, v2, vcc
	v_mad_u64_u32 v[84:85], s[20:21], v74, s89, v[68:69]
	v_mad_i32_i24 v85, v79, s89, v85
	v_lshlrev_b32_e32 v2, 1, v2
	v_pk_mul_f32 v[108:109], v[24:25], v[80:81] op_sel_hi:[1,0]
	v_lshl_add_u64 v[78:79], v[84:85], 0, v[2:3]
	v_cvt_pk_bf16_f32 v74, v108, s0
	v_add_co_u32_e32 v84, vcc, s40, v78
	global_store_short v[78:79], v74, off
	v_cvt_pk_bf16_f32 v74, v109, s0
	v_addc_co_u32_e32 v85, vcc, 0, v79, vcc
	v_pk_mul_f32 v[106:107], v[26:27], v[80:81] op_sel_hi:[1,0]
	global_store_short v[84:85], v74, off offset:256
	v_add_co_u32_e32 v84, vcc, s36, v78
	v_cvt_pk_bf16_f32 v74, v106, s0
	s_nop 0
	v_addc_co_u32_e32 v85, vcc, 0, v79, vcc
	global_store_short v[84:85], v74, off offset:512
	v_add_u32_e32 v84, v71, v75
	v_ashrrev_i32_e32 v85, 31, v84
	v_lshlrev_b64 v[84:85], 6, v[84:85]
	v_or_b32_e32 v71, v84, v73
	v_add_co_u32_e32 v78, vcc, s41, v78
	v_mad_u64_u32 v[86:87], s[20:21], v71, s89, v[68:69]
	v_cvt_pk_bf16_f32 v74, v107, s0
	v_addc_co_u32_e32 v79, vcc, 0, v79, vcc
	v_mad_i32_i24 v87, v85, s89, v87
	global_store_short v[78:79], v74, off offset:768
	v_pk_mul_f32 v[78:79], v[22:23], v[80:81] op_sel_hi:[1,0]
	v_pk_mul_f32 v[80:81], v[20:21], v[80:81] op_sel_hi:[1,0]
	v_lshl_add_u64 v[84:85], v[86:87], 0, v[2:3]
	v_cvt_pk_bf16_f32 v2, v80, s0
	v_add_co_u32_e32 v80, vcc, s40, v84
	global_store_short v[84:85], v2, off
	v_cvt_pk_bf16_f32 v2, v81, s0
	v_addc_co_u32_e32 v81, vcc, 0, v85, vcc
	global_store_short v[80:81], v2, off offset:256
	v_add_co_u32_e32 v80, vcc, s36, v84
	v_cvt_pk_bf16_f32 v2, v78, s0
	s_nop 0
	v_addc_co_u32_e32 v81, vcc, 0, v85, vcc
	v_add_co_u32_e32 v78, vcc, s41, v84
	global_store_short v[80:81], v2, off offset:512
	v_cvt_pk_bf16_f32 v2, v79, s0
	v_addc_co_u32_e32 v79, vcc, 0, v85, vcc
	s_movk_i32 s20, 0x7ef
	global_store_short v[78:79], v2, off offset:768
	v_bitop3_b32 v2, v70, s20, 32 bitop3:0xc8
	s_add_i32 s20, s4, 0xffffc0a0
	s_lshr_b32 s20, s20, 4
	v_mov_b32_e32 v71, s20
	v_cmp_gt_i32_e32 vcc, s37, v77
	v_add_u32_e32 v2, 0x80, v2
	v_pk_mul_f32 v[80:81], v[16:17], v[82:83] op_sel_hi:[1,0]
	v_cndmask_b32_e32 v71, v71, v111, vcc
	v_lshlrev_b32_e32 v71, 1, v71
	v_add_u32_e32 v84, s5, v71
	v_ashrrev_i32_e32 v85, 31, v84
	v_lshlrev_b64 v[84:85], 6, v[84:85]
	v_or_b32_e32 v74, v84, v76
	v_cndmask_b32_e32 v2, v244, v2, vcc
	v_mad_u64_u32 v[86:87], s[20:21], v74, s89, v[68:69]
	v_mad_i32_i24 v87, v85, s89, v87
	v_lshlrev_b32_e32 v2, 1, v2
	v_lshl_add_u64 v[84:85], v[86:87], 0, v[2:3]
	v_cvt_pk_bf16_f32 v74, v80, s0
	v_add_co_u32_e32 v80, vcc, s40, v84
	global_store_short v[84:85], v74, off
	v_cvt_pk_bf16_f32 v74, v81, s0
	v_addc_co_u32_e32 v81, vcc, 0, v85, vcc
	global_store_short v[80:81], v74, off offset:256
	v_add_co_u32_e32 v80, vcc, s36, v84
	v_pk_mul_f32 v[78:79], v[18:19], v[82:83] op_sel_hi:[1,0]
	s_nop 0
	v_addc_co_u32_e32 v81, vcc, 0, v85, vcc
	v_cvt_pk_bf16_f32 v74, v78, s0
	v_add_co_u32_e32 v78, vcc, s41, v84
	global_store_short v[80:81], v74, off offset:512
	v_cvt_pk_bf16_f32 v74, v79, s0
	v_addc_co_u32_e32 v79, vcc, 0, v85, vcc
	global_store_short v[78:79], v74, off offset:768
	v_pk_mul_f32 v[78:79], v[14:15], v[82:83] op_sel_hi:[1,0]
	v_pk_mul_f32 v[80:81], v[12:13], v[82:83] op_sel_hi:[1,0]
	v_add_u32_e32 v82, v71, v75
	v_ashrrev_i32_e32 v83, 31, v82
	v_lshlrev_b64 v[82:83], 6, v[82:83]
	v_or_b32_e32 v71, v82, v73
	v_mad_u64_u32 v[84:85], s[20:21], v71, s89, v[68:69]
	v_mad_i32_i24 v85, v83, s89, v85
	v_lshl_add_u64 v[82:83], v[84:85], 0, v[2:3]
	v_cvt_pk_bf16_f32 v2, v80, s0
	v_add_co_u32_e32 v80, vcc, s40, v82
	global_store_short v[82:83], v2, off
	v_cvt_pk_bf16_f32 v2, v81, s0
	v_addc_co_u32_e32 v81, vcc, 0, v83, vcc
	global_store_short v[80:81], v2, off offset:256
	v_add_co_u32_e32 v80, vcc, s36, v82
	v_cvt_pk_bf16_f32 v2, v78, s0
	s_nop 0
	v_addc_co_u32_e32 v81, vcc, 0, v83, vcc
	v_add_co_u32_e32 v78, vcc, s41, v82
	s_addk_i32 s4, 0xc0b0
	s_movk_i32 s20, 0x4000
	global_store_short v[80:81], v2, off offset:512
	v_cvt_pk_bf16_f32 v2, v79, s0
	v_addc_co_u32_e32 v79, vcc, 0, v83, vcc
	s_movk_i32 s21, 0x7ff
	s_lshr_b32 s4, s4, 4
	global_store_short v[78:79], v2, off offset:768
	v_bitop3_b32 v2, v70, s21, 48 bitop3:0xc8
	v_mov_b32_e32 v70, s4
	v_cmp_gt_i32_e32 vcc, s20, v110
	v_add_u32_e32 v2, 0x80, v2
	v_pk_mul_f32 v[80:81], v[8:9], v[72:73] op_sel_hi:[1,0]
	v_cndmask_b32_e32 v70, v70, v111, vcc
	v_lshlrev_b32_e32 v74, 1, v70
	v_add_u32_e32 v70, s5, v74
	v_ashrrev_i32_e32 v71, 31, v70
	v_lshlrev_b64 v[70:71], 6, v[70:71]
	v_or_b32_e32 v70, v70, v76
	v_cndmask_b32_e32 v2, v244, v2, vcc
	v_mad_u64_u32 v[76:77], s[4:5], v70, s89, v[68:69]
	v_mad_i32_i24 v77, v71, s89, v77
	v_lshlrev_b32_e32 v2, 1, v2
	v_lshl_add_u64 v[70:71], v[76:77], 0, v[2:3]
	v_cvt_pk_bf16_f32 v76, v80, s0
	global_store_short v[70:71], v76, off
	v_add_co_u32_e32 v76, vcc, s40, v70
	v_cvt_pk_bf16_f32 v80, v81, s0
	s_nop 0
	v_addc_co_u32_e32 v77, vcc, 0, v71, vcc
	global_store_short v[76:77], v80, off offset:256
	v_add_co_u32_e32 v76, vcc, s36, v70
	v_pk_mul_f32 v[78:79], v[10:11], v[72:73] op_sel_hi:[1,0]
	s_nop 0
	v_addc_co_u32_e32 v77, vcc, 0, v71, vcc
	v_add_u32_e32 v74, v74, v75
	v_cvt_pk_bf16_f32 v78, v78, s0
	v_add_co_u32_e32 v70, vcc, s41, v70
	v_ashrrev_i32_e32 v75, 31, v74
	global_store_short v[76:77], v78, off offset:512
	v_cvt_pk_bf16_f32 v76, v79, s0
	v_addc_co_u32_e32 v71, vcc, 0, v71, vcc
	v_lshlrev_b64 v[74:75], 6, v[74:75]
	global_store_short v[70:71], v76, off offset:768
	v_pk_mul_f32 v[70:71], v[6:7], v[72:73] op_sel_hi:[1,0]
	v_pk_mul_f32 v[76:77], v[4:5], v[72:73] op_sel_hi:[1,0]
	v_or_b32_e32 v72, v74, v73
	v_mad_u64_u32 v[68:69], s[4:5], v72, s89, v[68:69]
	v_mad_i32_i24 v69, v75, s89, v69
	v_lshl_add_u64 v[68:69], v[68:69], 0, v[2:3]
	v_cvt_pk_bf16_f32 v2, v76, s0
	v_add_co_u32_e32 v72, vcc, 0x1000, v68
	global_store_short v[68:69], v2, off
	v_cvt_pk_bf16_f32 v2, v77, s0
	v_addc_co_u32_e32 v73, vcc, 0, v69, vcc
	global_store_short v[72:73], v2, off offset:256
	v_add_co_u32_e32 v72, vcc, 0x2000, v68
	v_cvt_pk_bf16_f32 v2, v70, s0
	s_nop 0
	v_addc_co_u32_e32 v73, vcc, 0, v69, vcc
	v_add_co_u32_e32 v68, vcc, 0x3000, v68
	global_store_short v[72:73], v2, off offset:512
	v_cvt_pk_bf16_f32 v2, v71, s0
	v_addc_co_u32_e32 v69, vcc, 0, v69, vcc
	global_store_short v[68:69], v2, off offset:768

.LBB0_190:
	s_andn2_b64 vcc, exec, s[4:5]
	s_cbranch_vccnz .LBB0_225
	s_lshl_b32 s2, s48, 8
	v_add_u32_e32 v104, s2, v241
	v_ashrrev_i32_e32 v105, 31, v104
	v_lshl_add_u64 v[88:89], v[104:105], 2, s[70:71]
	v_mov_b32_e32 v102, v164
	s_movk_i32 s2, 0x7cf
	v_and_or_b32 v2, v104, s2, 16
	v_cmp_gt_i32_e32 vcc, s20, v104
	v_mov_b32_e32 v114, 0
	v_mov_b32_e32 v68, 1.0
	v_cndmask_b32_e32 v2, v181, v2, vcc
	v_lshlrev_b32_e32 v2, 6, v2
	v_lshl_add_u64 v[72:73], s[84:85], 0, v[2:3]
	v_lshlrev_b32_e32 v100, 2, v170
	v_mov_b32_e32 v80, 1.0
	v_mov_b32_e32 v126, 0
	v_mov_b32_e32 v82, 1.0
	v_mov_b32_e32 v124, 0
	s_and_saveexec_b64 s[2:3], s[38:39]
	s_cbranch_execz .LBB0_193
	v_mov_b32_e32 v101, v3
	v_lshl_add_u64 v[70:71], v[72:73], 0, v[100:101]
	global_load_dwordx4 v[80:83], v[70:71], off

.LBB0_195:
	s_or_b64 exec, exec, s[2:3]
	v_mov_b32_e32 v110, v165
	s_movk_i32 s2, 0x7df
	v_or_b32_e32 v106, 16, v104
	v_bitop3_b32 v2, v104, s2, 16 bitop3:0xc8
	v_add_u32_e32 v2, 16, v2
	v_cmp_gt_i32_e32 vcc, s20, v106
	v_mov_b32_e32 v118, 0
	v_mov_b32_e32 v72, 1.0
	v_cndmask_b32_e32 v2, v181, v2, vcc
	v_lshlrev_b32_e32 v2, 6, v2
	v_lshl_add_u64 v[76:77], s[84:85], 0, v[2:3]
	v_mov_b32_e32 v84, 1.0
	v_mov_b32_e32 v132, 0
	v_mov_b32_e32 v86, 1.0
	v_mov_b32_e32 v130, 0
	s_and_saveexec_b64 s[2:3], s[38:39]
	s_cbranch_execz .LBB0_197
	v_mov_b32_e32 v101, v3
	v_lshl_add_u64 v[74:75], v[76:77], 0, v[100:101]
	global_load_dwordx4 v[84:87], v[74:75], off

.LBB0_199:
	s_or_b64 exec, exec, s[2:3]
	v_mov_b32_e32 v116, v166
	v_or_b32_e32 v108, 32, v104
	s_movk_i32 s2, 0x7ef
	v_and_or_b32 v2, v108, s2, 16
	v_cmp_gt_i32_e32 vcc, s20, v108
	v_mov_b32_e32 v122, 0
	v_mov_b32_e32 v76, 1.0
	v_cndmask_b32_e32 v2, v181, v2, vcc
	v_lshlrev_b32_e32 v2, 6, v2
	v_lshl_add_u64 v[90:91], s[84:85], 0, v[2:3]
	v_mov_b32_e32 v92, 1.0
	v_mov_b32_e32 v138, 0
	v_mov_b32_e32 v94, 1.0
	v_mov_b32_e32 v136, 0
	s_and_saveexec_b64 s[2:3], s[38:39]
	s_cbranch_execz .LBB0_201
	v_mov_b32_e32 v101, v3
	v_lshl_add_u64 v[78:79], v[90:91], 0, v[100:101]
	global_load_dwordx4 v[92:95], v[78:79], off

.LBB0_203:
	s_or_b64 exec, exec, s[2:3]
	v_mov_b32_e32 v120, v167
	s_movk_i32 s2, 0x7ff
	v_or_b32_e32 v112, 48, v104
	v_bitop3_b32 v2, v104, s2, 48 bitop3:0xc8
	v_add_u32_e32 v2, 16, v2
	v_cmp_gt_i32_e32 vcc, s20, v112
	v_mov_b32_e32 v88, 1.0
	v_mov_b32_e32 v96, 1.0
	v_cndmask_b32_e32 v2, v181, v2, vcc
	v_lshlrev_b32_e32 v2, 6, v2
	v_lshl_add_u64 v[148:149], s[84:85], 0, v[2:3]
	v_mov_b32_e32 v2, 0
	v_mov_b32_e32 v144, 0
	v_mov_b32_e32 v98, 1.0
	v_mov_b32_e32 v142, 0
	s_and_saveexec_b64 s[2:3], s[38:39]
	s_cbranch_execz .LBB0_205
	v_mov_b32_e32 v101, v3
	v_lshl_add_u64 v[90:91], v[148:149], 0, v[100:101]
	global_load_dwordx4 v[96:99], v[90:91], off

.LBB0_207:
	s_or_b64 exec, exec, s[2:3]
	s_waitcnt vmcnt(0)
	s_and_saveexec_b64 s[2:3], s[38:39]
	v_mov_b32_e32 v126, v81
	v_mov_b32_e32 v124, v83
	v_mov_b32_e32 v114, v69
	v_mov_b32_e32 v128, v71
	v_mov_b32_e32 v132, v85
	v_mov_b32_e32 v130, v87
	v_mov_b32_e32 v118, v73
	v_mov_b32_e32 v134, v75
	v_mov_b32_e32 v138, v93
	v_mov_b32_e32 v136, v95
	v_mov_b32_e32 v122, v77
	v_mov_b32_e32 v140, v79
	v_mov_b32_e32 v144, v97
	v_mov_b32_e32 v142, v99
	v_mov_b32_e32 v2, v89
	v_mov_b32_e32 v146, v91
	s_or_b64 exec, exec, s[2:3]
	v_pk_mul_f32 v[148:149], v[66:67], v[102:103] op_sel_hi:[1,0]
	v_pk_mul_f32 v[150:151], v[64:65], v[102:103] op_sel_hi:[1,0]
	v_pk_mul_f32 v[124:125], v[148:149], v[124:125] op_sel:[1,0] op_sel_hi:[0,0]
	v_pk_mul_f32 v[126:127], v[150:151], v[126:127] op_sel:[1,0] op_sel_hi:[0,0]
	v_pk_fma_f32 v[152:153], v[150:151], v[80:81], v[126:127] op_sel_hi:[1,0,1] neg_lo:[0,0,1] neg_hi:[0,0,1]
	v_pk_fma_f32 v[80:81], v[150:151], v[80:81], v[126:127] op_sel_hi:[1,0,1]
	v_pk_fma_f32 v[126:127], v[148:149], v[82:83], v[124:125] op_sel_hi:[1,0,1] neg_lo:[0,0,1] neg_hi:[0,0,1]
	v_pk_fma_f32 v[82:83], v[148:149], v[82:83], v[124:125] op_sel_hi:[1,0,1]
	v_pk_mul_f32 v[124:125], v[62:63], v[102:103] op_sel_hi:[1,0]
	v_pk_mul_f32 v[102:103], v[60:61], v[102:103] op_sel_hi:[1,0]
	v_mov_b32_e32 v127, v83
	s_mov_b32 s4, 0x3e000000
	v_pk_mul_f32 v[114:115], v[102:103], v[114:115] op_sel:[1,0] op_sel_hi:[0,0]
	v_pk_mul_f32 v[82:83], v[126:127], s[4:5] op_sel_hi:[1,0]
	v_pk_fma_f32 v[126:127], v[102:103], v[68:69], v[114:115] op_sel_hi:[1,0,1] neg_lo:[0,0,1] neg_hi:[0,0,1]
	v_pk_fma_f32 v[68:69], v[102:103], v[68:69], v[114:115] op_sel_hi:[1,0,1]
	v_pk_mul_f32 v[102:103], v[124:125], v[128:129] op_sel:[1,0] op_sel_hi:[0,0]
	s_ashr_i32 s75, s74, 31
	v_pk_fma_f32 v[114:115], v[124:125], v[70:71], v[102:103] op_sel_hi:[1,0,1] neg_lo:[0,0,1] neg_hi:[0,0,1]
	v_pk_fma_f32 v[70:71], v[124:125], v[70:71], v[102:103] op_sel_hi:[1,0,1]
	v_mov_b32_e32 v127, v69
	v_lshlrev_b64 v[68:69], 10, v[104:105]
	v_lshl_add_u64 v[102:103], s[74:75], 0, v[178:179]
	v_mov_b32_e32 v153, v81
	v_lshl_add_u64 v[68:69], s[94:95], 0, v[68:69]
	v_lshlrev_b64 v[102:103], 1, v[102:103]
	v_pk_mul_f32 v[80:81], v[152:153], s[4:5] op_sel_hi:[1,0]
	v_mov_b32_e32 v115, v71
	v_lshl_add_u64 v[124:125], v[68:69], 0, v[102:103]
	s_mov_b32 s2, 0x847e000
	v_pk_mul_f32 v[114:115], v[114:115], s[4:5] op_sel_hi:[1,0]
	v_pk_mul_f32 v[70:71], v[126:127], s[4:5] op_sel_hi:[1,0]
	v_cvt_pk_bf16_f32 v68, v80, v81
	v_add_co_u32_e32 v80, vcc, s2, v124
	v_cvt_pk_bf16_f32 v69, v82, v83
	v_cvt_pk_bf16_f32 v70, v70, v71
	v_cvt_pk_bf16_f32 v71, v114, v115
	v_addc_co_u32_e32 v81, vcc, 0, v125, vcc
	global_store_dwordx4 v[80:81], v[68:71], off offset:2304
	v_ashrrev_i32_e32 v107, 31, v106
	v_ashrrev_i32_e32 v109, 31, v108
	v_pk_mul_f32 v[70:71], v[56:57], v[110:111] op_sel_hi:[1,0]
	v_pk_mul_f32 v[68:69], v[58:59], v[110:111] op_sel_hi:[1,0]
	v_pk_mul_f32 v[80:81], v[70:71], v[132:133] op_sel:[1,0] op_sel_hi:[0,0]
	v_pk_fma_f32 v[82:83], v[70:71], v[84:85], v[80:81] op_sel_hi:[1,0,1] neg_lo:[0,0,1] neg_hi:[0,0,1]
	v_pk_fma_f32 v[70:71], v[70:71], v[84:85], v[80:81] op_sel_hi:[1,0,1]
	v_pk_mul_f32 v[80:81], v[68:69], v[130:131] op_sel:[1,0] op_sel_hi:[0,0]
	v_pk_fma_f32 v[84:85], v[68:69], v[86:87], v[80:81] op_sel_hi:[1,0,1] neg_lo:[0,0,1] neg_hi:[0,0,1]
	v_pk_fma_f32 v[68:69], v[68:69], v[86:87], v[80:81] op_sel_hi:[1,0,1]
	v_mov_b32_e32 v83, v71
	v_mov_b32_e32 v85, v69
	v_pk_mul_f32 v[68:69], v[82:83], s[4:5] op_sel_hi:[1,0]
	v_pk_mul_f32 v[82:83], v[52:53], v[110:111] op_sel_hi:[1,0]
	v_pk_mul_f32 v[80:81], v[84:85], s[4:5] op_sel_hi:[1,0]
	v_pk_mul_f32 v[84:85], v[82:83], v[118:119] op_sel:[1,0] op_sel_hi:[0,0]
	v_pk_mul_f32 v[70:71], v[54:55], v[110:111] op_sel_hi:[1,0]
	v_pk_fma_f32 v[86:87], v[82:83], v[72:73], v[84:85] op_sel_hi:[1,0,1] neg_lo:[0,0,1] neg_hi:[0,0,1]
	v_pk_fma_f32 v[72:73], v[82:83], v[72:73], v[84:85] op_sel_hi:[1,0,1]
	v_pk_mul_f32 v[82:83], v[70:71], v[134:135] op_sel:[1,0] op_sel_hi:[0,0]
	v_mov_b32_e32 v87, v73
	v_lshlrev_b64 v[72:73], 10, v[106:107]
	v_pk_fma_f32 v[84:85], v[70:71], v[74:75], v[82:83] op_sel_hi:[1,0,1] neg_lo:[0,0,1] neg_hi:[0,0,1]
	v_pk_fma_f32 v[70:71], v[70:71], v[74:75], v[82:83] op_sel_hi:[1,0,1]
	v_lshl_add_u64 v[72:73], s[94:95], 0, v[72:73]
	v_mov_b32_e32 v85, v71
	v_lshl_add_u64 v[72:73], v[72:73], 0, v[102:103]
	v_pk_mul_f32 v[74:75], v[84:85], s[4:5] op_sel_hi:[1,0]
	v_pk_mul_f32 v[70:71], v[86:87], s[4:5] op_sel_hi:[1,0]
	v_add_co_u32_e32 v72, vcc, s2, v72
	v_cvt_pk_bf16_f32 v68, v68, v69
	v_cvt_pk_bf16_f32 v69, v80, v81
	v_cvt_pk_bf16_f32 v70, v70, v71
	v_cvt_pk_bf16_f32 v71, v74, v75
	v_addc_co_u32_e32 v73, vcc, 0, v73, vcc
	global_store_dwordx4 v[72:73], v[68:71], off offset:2304
	v_ashrrev_i32_e32 v113, 31, v112
	s_cmp_eq_u32 s48, 64
	v_pk_mul_f32 v[70:71], v[48:49], v[116:117] op_sel_hi:[1,0]
	v_pk_mul_f32 v[68:69], v[50:51], v[116:117] op_sel_hi:[1,0]
	v_pk_mul_f32 v[72:73], v[70:71], v[138:139] op_sel:[1,0] op_sel_hi:[0,0]
	v_pk_fma_f32 v[74:75], v[70:71], v[92:93], v[72:73] op_sel_hi:[1,0,1] neg_lo:[0,0,1] neg_hi:[0,0,1]
	v_pk_fma_f32 v[70:71], v[70:71], v[92:93], v[72:73] op_sel_hi:[1,0,1]
	v_pk_mul_f32 v[72:73], v[68:69], v[136:137] op_sel:[1,0] op_sel_hi:[0,0]
	v_pk_fma_f32 v[80:81], v[68:69], v[94:95], v[72:73] op_sel_hi:[1,0,1] neg_lo:[0,0,1] neg_hi:[0,0,1]
	v_pk_fma_f32 v[68:69], v[68:69], v[94:95], v[72:73] op_sel_hi:[1,0,1]
	v_mov_b32_e32 v75, v71
	v_mov_b32_e32 v81, v69
	v_pk_mul_f32 v[68:69], v[74:75], s[4:5] op_sel_hi:[1,0]
	v_pk_mul_f32 v[74:75], v[44:45], v[116:117] op_sel_hi:[1,0]
	v_pk_mul_f32 v[72:73], v[80:81], s[4:5] op_sel_hi:[1,0]
	v_pk_mul_f32 v[80:81], v[74:75], v[122:123] op_sel:[1,0] op_sel_hi:[0,0]
	v_pk_mul_f32 v[70:71], v[46:47], v[116:117] op_sel_hi:[1,0]
	v_pk_fma_f32 v[82:83], v[74:75], v[76:77], v[80:81] op_sel_hi:[1,0,1] neg_lo:[0,0,1] neg_hi:[0,0,1]
	v_pk_fma_f32 v[74:75], v[74:75], v[76:77], v[80:81] op_sel_hi:[1,0,1]
	v_pk_mul_f32 v[76:77], v[70:71], v[140:141] op_sel:[1,0] op_sel_hi:[0,0]
	v_mov_b32_e32 v83, v75
	v_lshlrev_b64 v[74:75], 10, v[108:109]
	v_pk_fma_f32 v[80:81], v[70:71], v[78:79], v[76:77] op_sel_hi:[1,0,1] neg_lo:[0,0,1] neg_hi:[0,0,1]
	v_pk_fma_f32 v[70:71], v[70:71], v[78:79], v[76:77] op_sel_hi:[1,0,1]
	v_lshl_add_u64 v[74:75], s[94:95], 0, v[74:75]
	v_mov_b32_e32 v81, v71
	v_lshl_add_u64 v[74:75], v[74:75], 0, v[102:103]
	v_pk_mul_f32 v[76:77], v[80:81], s[4:5] op_sel_hi:[1,0]
	v_pk_mul_f32 v[70:71], v[82:83], s[4:5] op_sel_hi:[1,0]
	v_cvt_pk_bf16_f32 v68, v68, v69
	v_cvt_pk_bf16_f32 v69, v72, v73
	v_add_co_u32_e32 v72, vcc, s2, v74
	v_cvt_pk_bf16_f32 v70, v70, v71
	v_cvt_pk_bf16_f32 v71, v76, v77
	v_addc_co_u32_e32 v73, vcc, 0, v75, vcc
	global_store_dwordx4 v[72:73], v[68:71], off offset:2304
	s_nop 1
	v_pk_mul_f32 v[70:71], v[40:41], v[120:121] op_sel_hi:[1,0]
	v_pk_mul_f32 v[68:69], v[42:43], v[120:121] op_sel_hi:[1,0]
	v_pk_mul_f32 v[72:73], v[70:71], v[144:145] op_sel:[1,0] op_sel_hi:[0,0]
	v_pk_fma_f32 v[74:75], v[70:71], v[96:97], v[72:73] op_sel_hi:[1,0,1] neg_lo:[0,0,1] neg_hi:[0,0,1]
	v_pk_fma_f32 v[70:71], v[70:71], v[96:97], v[72:73] op_sel_hi:[1,0,1]
	v_pk_mul_f32 v[72:73], v[68:69], v[142:143] op_sel:[1,0] op_sel_hi:[0,0]
	v_pk_fma_f32 v[76:77], v[68:69], v[98:99], v[72:73] op_sel_hi:[1,0,1] neg_lo:[0,0,1] neg_hi:[0,0,1]
	v_pk_fma_f32 v[68:69], v[68:69], v[98:99], v[72:73] op_sel_hi:[1,0,1]
	v_mov_b32_e32 v75, v71
	v_mov_b32_e32 v77, v69
	v_pk_mul_f32 v[68:69], v[74:75], s[4:5] op_sel_hi:[1,0]
	v_pk_mul_f32 v[74:75], v[36:37], v[120:121] op_sel_hi:[1,0]
	v_pk_mul_f32 v[72:73], v[76:77], s[4:5] op_sel_hi:[1,0]
	v_pk_mul_f32 v[76:77], v[74:75], v[2:3] op_sel:[1,0] op_sel_hi:[0,0]
	v_pk_mul_f32 v[70:71], v[38:39], v[120:121] op_sel_hi:[1,0]
	v_pk_fma_f32 v[78:79], v[74:75], v[88:89], v[76:77] op_sel_hi:[1,0,1] neg_lo:[0,0,1] neg_hi:[0,0,1]
	v_pk_fma_f32 v[74:75], v[74:75], v[88:89], v[76:77] op_sel_hi:[1,0,1]
	v_pk_mul_f32 v[76:77], v[70:71], v[146:147] op_sel:[1,0] op_sel_hi:[0,0]
	v_mov_b32_e32 v79, v75
	v_lshlrev_b64 v[74:75], 10, v[112:113]
	v_pk_fma_f32 v[80:81], v[70:71], v[90:91], v[76:77] op_sel_hi:[1,0,1] neg_lo:[0,0,1] neg_hi:[0,0,1]
	v_pk_fma_f32 v[70:71], v[70:71], v[90:91], v[76:77] op_sel_hi:[1,0,1]
	v_lshl_add_u64 v[74:75], s[94:95], 0, v[74:75]
	v_mov_b32_e32 v81, v71
	v_lshl_add_u64 v[74:75], v[74:75], 0, v[102:103]
	v_pk_mul_f32 v[76:77], v[80:81], s[4:5] op_sel_hi:[1,0]
	v_pk_mul_f32 v[70:71], v[78:79], s[4:5] op_sel_hi:[1,0]
	v_cvt_pk_bf16_f32 v68, v68, v69
	v_cvt_pk_bf16_f32 v69, v72, v73
	v_add_co_u32_e32 v72, vcc, 0x847e000, v74
	v_cvt_pk_bf16_f32 v70, v70, v71
	v_cvt_pk_bf16_f32 v71, v76, v77
	v_addc_co_u32_e32 v73, vcc, 0, v75, vcc
	global_store_dwordx4 v[72:73], v[68:71], off offset:2304
	s_cbranch_scc1 .LBB0_225
	v_add_u32_e32 v104, 0x80, v104
	v_ashrrev_i32_e32 v105, 31, v104
	v_lshl_add_u64 v[88:89], v[104:105], 2, s[70:71]
	v_mov_b32_e32 v108, v246
	s_movk_i32 s2, 0x7cf
	v_and_or_b32 v2, v104, s2, 16
	v_cmp_gt_i32_e32 vcc, s20, v104
	v_mov_b32_e32 v114, 0
	v_mov_b32_e32 v68, 1.0
	v_cndmask_b32_e32 v2, v181, v2, vcc
	v_lshlrev_b32_e32 v2, 6, v2
	v_lshl_add_u64 v[72:73], s[84:85], 0, v[2:3]
	v_mov_b32_e32 v76, 1.0
	v_mov_b32_e32 v126, 0
	v_mov_b32_e32 v78, 1.0
	v_mov_b32_e32 v124, 0
	s_and_saveexec_b64 s[2:3], s[38:39]
	s_cbranch_execz .LBB0_210
	v_mov_b32_e32 v101, v3
	v_lshl_add_u64 v[70:71], v[72:73], 0, v[100:101]
	global_load_dwordx4 v[76:79], v[70:71], off

.LBB0_212:
	s_or_b64 exec, exec, s[2:3]
	v_mov_b32_e32 v112, v247
	s_movk_i32 s2, 0x7df
	v_or_b32_e32 v106, 16, v104
	v_bitop3_b32 v2, v104, s2, 16 bitop3:0xc8
	v_add_u32_e32 v2, 16, v2
	v_cmp_gt_i32_e32 vcc, s20, v106
	v_mov_b32_e32 v120, 0
	v_mov_b32_e32 v72, 1.0
	v_cndmask_b32_e32 v2, v181, v2, vcc
	v_lshlrev_b32_e32 v2, 6, v2
	v_lshl_add_u64 v[80:81], s[84:85], 0, v[2:3]
	v_mov_b32_e32 v84, 1.0
	v_mov_b32_e32 v134, 0
	v_mov_b32_e32 v86, 1.0
	v_mov_b32_e32 v132, 0
	s_and_saveexec_b64 s[2:3], s[38:39]
	s_cbranch_execz .LBB0_214
	v_mov_b32_e32 v101, v3
	v_lshl_add_u64 v[74:75], v[80:81], 0, v[100:101]
	global_load_dwordx4 v[84:87], v[74:75], off

.LBB0_216:
	s_or_b64 exec, exec, s[2:3]
	v_mov_b32_e32 v118, v248
	v_or_b32_e32 v110, 32, v104
	s_movk_i32 s2, 0x7ef
	v_and_or_b32 v2, v110, s2, 16
	v_cmp_gt_i32_e32 vcc, s20, v110
	v_mov_b32_e32 v128, 0
	v_mov_b32_e32 v80, 1.0
	v_cndmask_b32_e32 v2, v181, v2, vcc
	v_lshlrev_b32_e32 v2, 6, v2
	v_lshl_add_u64 v[90:91], s[84:85], 0, v[2:3]
	v_mov_b32_e32 v92, 1.0
	v_mov_b32_e32 v140, 0
	v_mov_b32_e32 v94, 1.0
	v_mov_b32_e32 v138, 0
	s_and_saveexec_b64 s[2:3], s[38:39]
	s_cbranch_execz .LBB0_218
	v_mov_b32_e32 v101, v3
	v_lshl_add_u64 v[82:83], v[90:91], 0, v[100:101]
	global_load_dwordx4 v[92:95], v[82:83], off

.LBB0_220:
	s_or_b64 exec, exec, s[2:3]
	v_mov_b32_e32 v122, v249
	s_movk_i32 s2, 0x7ff
	v_or_b32_e32 v116, 48, v104
	v_bitop3_b32 v2, v104, s2, 48 bitop3:0xc8
	v_add_u32_e32 v2, 16, v2
	v_cmp_gt_i32_e32 vcc, s20, v116
	v_mov_b32_e32 v88, 1.0
	v_mov_b32_e32 v96, 1.0
	v_cndmask_b32_e32 v2, v181, v2, vcc
	v_lshlrev_b32_e32 v2, 6, v2
	v_lshl_add_u64 v[150:151], s[84:85], 0, v[2:3]
	v_mov_b32_e32 v2, 0
	v_mov_b32_e32 v146, 0
	v_mov_b32_e32 v98, 1.0
	v_mov_b32_e32 v144, 0
	s_and_saveexec_b64 s[2:3], s[38:39]
	s_cbranch_execz .LBB0_222
	v_mov_b32_e32 v101, v3
	v_lshl_add_u64 v[90:91], v[150:151], 0, v[100:101]
	global_load_dwordx4 v[96:99], v[90:91], off

.LBB0_225:
	s_and_b64 vcc, exec, s[0:1]
	s_cbranch_vccz .LBB0_228
	s_lshl_b32 s0, s48, 8
	v_add_u32_e32 v70, s0, v241
	v_ashrrev_i32_e32 v71, 31, v70
	v_lshl_add_u64 v[68:69], v[70:71], 2, s[70:71]
	v_mov_b32_e32 v86, v164
	v_mov_b32_e32 v80, v165
	v_mov_b32_e32 v76, v166
	v_mov_b32_e32 v2, v167
	s_ashr_i32 s75, s74, 31
	s_mov_b32 s0, 0x643f000
	v_or_b32_e32 v78, 16, v70
	v_ashrrev_i32_e32 v79, 31, v78
	v_lshlrev_b64 v[78:79], 11, v[78:79]
	v_lshl_add_u64 v[78:79], s[94:95], 0, v[78:79]
	v_or_b32_e32 v74, 32, v70
	v_ashrrev_i32_e32 v75, 31, v74
	v_lshlrev_b64 v[74:75], 11, v[74:75]
	v_lshl_add_u64 v[74:75], s[94:95], 0, v[74:75]
	v_or_b32_e32 v72, 48, v70
	v_ashrrev_i32_e32 v73, 31, v72
	v_lshlrev_b64 v[72:73], 11, v[72:73]
	v_lshl_add_u64 v[72:73], s[94:95], 0, v[72:73]
	s_cmp_eq_u32 s48, 64
	s_waitcnt vmcnt(0)
	v_pk_mul_f32 v[82:83], v[64:65], v[86:87] op_sel_hi:[1,0]
	s_nop 0
	v_mul_f32_e32 v77, 0xbfb8aa3b, v82
	v_exp_f32_e32 v77, v77
	v_pk_mul_f32 v[68:69], v[66:67], v[86:87] op_sel_hi:[1,0]
	v_add_f32_e32 v77, 1.0, v77
	v_rcp_f32_e32 v84, v77
	v_mul_f32_e32 v77, 0xbfb8aa3b, v83
	v_exp_f32_e32 v77, v77
	s_nop 0
	v_add_f32_e32 v77, 1.0, v77
	v_rcp_f32_e32 v85, v77
	v_mul_f32_e32 v77, 0xbfb8aa3b, v68
	v_exp_f32_e32 v77, v77
	v_pk_mul_f32 v[82:83], v[82:83], v[84:85]
	s_nop 0
	v_cvt_pk_bf16_f32 v82, v82, v83
	v_add_f32_e32 v77, 1.0, v77
	v_rcp_f32_e32 v84, v77
	v_mul_f32_e32 v77, 0xbfb8aa3b, v69
	v_exp_f32_e32 v77, v77
	s_nop 0
	v_add_f32_e32 v77, 1.0, v77
	v_rcp_f32_e32 v85, v77
	s_nop 0
	v_pk_mul_f32 v[84:85], v[68:69], v[84:85]
	v_pk_mul_f32 v[68:69], v[62:63], v[86:87] op_sel_hi:[1,0]
	v_pk_mul_f32 v[86:87], v[60:61], v[86:87] op_sel_hi:[1,0]
	v_cvt_pk_bf16_f32 v83, v84, v85
	v_mul_f32_e32 v77, 0xbfb8aa3b, v86
	v_exp_f32_e32 v77, v77
	s_nop 0
	v_add_f32_e32 v77, 1.0, v77
	v_rcp_f32_e32 v88, v77
	v_mul_f32_e32 v77, 0xbfb8aa3b, v87
	v_exp_f32_e32 v77, v77
	s_nop 0
	v_add_f32_e32 v77, 1.0, v77
	v_rcp_f32_e32 v89, v77
	v_mul_f32_e32 v77, 0xbfb8aa3b, v68
	v_exp_f32_e32 v77, v77
	v_pk_mul_f32 v[86:87], v[86:87], v[88:89]
	s_nop 0
	v_cvt_pk_bf16_f32 v84, v86, v87
	v_add_f32_e32 v77, 1.0, v77
	v_rcp_f32_e32 v88, v77
	v_mul_f32_e32 v77, 0xbfb8aa3b, v69
	v_exp_f32_e32 v77, v77
	s_nop 0
	v_add_f32_e32 v77, 1.0, v77
	v_rcp_f32_e32 v89, v77
	s_nop 0
	v_pk_mul_f32 v[88:89], v[68:69], v[88:89]
	v_lshlrev_b64 v[68:69], 11, v[70:71]
	v_lshl_add_u64 v[90:91], s[94:95], 0, v[68:69]
	v_lshl_add_u64 v[68:69], s[74:75], 0, v[178:179]
	v_lshlrev_b64 v[68:69], 1, v[68:69]
	v_lshl_add_u64 v[90:91], v[90:91], 0, v[68:69]
	v_add_co_u32_e32 v86, vcc, s0, v90
	v_cvt_pk_bf16_f32 v85, v88, v89
	s_nop 0
	v_addc_co_u32_e32 v87, vcc, 0, v91, vcc
	global_store_dwordx4 v[86:87], v[82:85], off offset:256
	s_nop 1
	v_pk_mul_f32 v[82:83], v[56:57], v[80:81] op_sel_hi:[1,0]
	v_pk_mul_f32 v[84:85], v[58:59], v[80:81] op_sel_hi:[1,0]
	v_mul_f32_e32 v71, 0xbfb8aa3b, v82
	v_exp_f32_e32 v71, v71
	s_nop 0
	v_add_f32_e32 v71, 1.0, v71
	v_rcp_f32_e32 v86, v71
	v_mul_f32_e32 v71, 0xbfb8aa3b, v83
	v_exp_f32_e32 v71, v71
	s_nop 0
	v_add_f32_e32 v71, 1.0, v71
	v_rcp_f32_e32 v87, v71
	v_mul_f32_e32 v71, 0xbfb8aa3b, v84
	v_exp_f32_e32 v71, v71
	v_pk_mul_f32 v[82:83], v[82:83], v[86:87]
	v_add_f32_e32 v71, 1.0, v71
	v_rcp_f32_e32 v86, v71
	v_mul_f32_e32 v71, 0xbfb8aa3b, v85
	v_exp_f32_e32 v71, v71
	s_nop 0
	v_add_f32_e32 v71, 1.0, v71
	v_rcp_f32_e32 v87, v71
	s_nop 0
	v_pk_mul_f32 v[84:85], v[84:85], v[86:87]
	v_pk_mul_f32 v[86:87], v[54:55], v[80:81] op_sel_hi:[1,0]
	v_pk_mul_f32 v[80:81], v[52:53], v[80:81] op_sel_hi:[1,0]
	s_nop 0
	v_mul_f32_e32 v71, 0xbfb8aa3b, v80
	v_exp_f32_e32 v71, v71
	s_nop 0
	v_add_f32_e32 v71, 1.0, v71
	v_rcp_f32_e32 v88, v71
	v_mul_f32_e32 v71, 0xbfb8aa3b, v81
	v_exp_f32_e32 v71, v71
	s_nop 0
	v_add_f32_e32 v71, 1.0, v71
	v_rcp_f32_e32 v89, v71
	v_mul_f32_e32 v71, 0xbfb8aa3b, v86
	v_exp_f32_e32 v71, v71
	v_pk_mul_f32 v[80:81], v[80:81], v[88:89]
	s_nop 0
	v_cvt_pk_bf16_f32 v80, v80, v81
	v_add_f32_e32 v71, 1.0, v71
	v_rcp_f32_e32 v88, v71
	v_mul_f32_e32 v71, 0xbfb8aa3b, v87
	v_exp_f32_e32 v71, v71
	s_nop 0
	v_add_f32_e32 v71, 1.0, v71
	v_rcp_f32_e32 v89, v71
	s_nop 0
	v_pk_mul_f32 v[86:87], v[86:87], v[88:89]
	v_lshl_add_u64 v[88:89], v[78:79], 0, v[68:69]
	v_cvt_pk_bf16_f32 v78, v82, v83
	v_add_co_u32_e32 v82, vcc, s0, v88
	v_cvt_pk_bf16_f32 v79, v84, v85
	v_cvt_pk_bf16_f32 v81, v86, v87
	v_addc_co_u32_e32 v83, vcc, 0, v89, vcc
	global_store_dwordx4 v[82:83], v[78:81], off offset:256
	s_nop 1
	v_pk_mul_f32 v[80:81], v[48:49], v[76:77] op_sel_hi:[1,0]
	v_pk_mul_f32 v[78:79], v[50:51], v[76:77] op_sel_hi:[1,0]
	v_mul_f32_e32 v71, 0xbfb8aa3b, v80
	v_exp_f32_e32 v71, v71
	s_nop 0
	v_add_f32_e32 v71, 1.0, v71
	v_rcp_f32_e32 v82, v71
	v_mul_f32_e32 v71, 0xbfb8aa3b, v81
	v_exp_f32_e32 v71, v71
	s_nop 0
	v_add_f32_e32 v71, 1.0, v71
	v_rcp_f32_e32 v83, v71
	v_mul_f32_e32 v71, 0xbfb8aa3b, v78
	v_exp_f32_e32 v71, v71
	v_pk_mul_f32 v[80:81], v[80:81], v[82:83]
	v_add_f32_e32 v71, 1.0, v71
	v_rcp_f32_e32 v82, v71
	v_mul_f32_e32 v71, 0xbfb8aa3b, v79
	v_exp_f32_e32 v71, v71
	s_nop 0
	v_add_f32_e32 v71, 1.0, v71
	v_rcp_f32_e32 v83, v71
	s_nop 0
	v_pk_mul_f32 v[78:79], v[78:79], v[82:83]
	v_pk_mul_f32 v[82:83], v[46:47], v[76:77] op_sel_hi:[1,0]
	v_pk_mul_f32 v[76:77], v[44:45], v[76:77] op_sel_hi:[1,0]
	s_nop 0
	v_mul_f32_e32 v71, 0xbfb8aa3b, v76
	v_exp_f32_e32 v71, v71
	s_nop 0
	v_add_f32_e32 v71, 1.0, v71
	v_rcp_f32_e32 v84, v71
	v_mul_f32_e32 v71, 0xbfb8aa3b, v77
	v_exp_f32_e32 v71, v71
	s_nop 0
	v_add_f32_e32 v71, 1.0, v71
	v_rcp_f32_e32 v85, v71
	v_mul_f32_e32 v71, 0xbfb8aa3b, v82
	v_exp_f32_e32 v71, v71
	v_pk_mul_f32 v[76:77], v[76:77], v[84:85]
	s_nop 0
	v_cvt_pk_bf16_f32 v76, v76, v77
	v_add_f32_e32 v71, 1.0, v71
	v_rcp_f32_e32 v84, v71
	v_mul_f32_e32 v71, 0xbfb8aa3b, v83
	v_exp_f32_e32 v71, v71
	s_nop 0
	v_add_f32_e32 v71, 1.0, v71
	v_rcp_f32_e32 v85, v71
	s_nop 0
	v_pk_mul_f32 v[82:83], v[82:83], v[84:85]
	v_lshl_add_u64 v[84:85], v[74:75], 0, v[68:69]
	v_cvt_pk_bf16_f32 v75, v78, v79
	v_add_co_u32_e32 v78, vcc, s0, v84
	v_cvt_pk_bf16_f32 v74, v80, v81
	v_cvt_pk_bf16_f32 v77, v82, v83
	v_addc_co_u32_e32 v79, vcc, 0, v85, vcc
	global_store_dwordx4 v[78:79], v[74:77], off offset:256
	v_pk_mul_f32 v[80:81], v[36:37], v[2:3] op_sel_hi:[1,0]
	s_nop 0
	v_pk_mul_f32 v[76:77], v[40:41], v[2:3] op_sel_hi:[1,0]
	v_pk_mul_f32 v[74:75], v[42:43], v[2:3] op_sel_hi:[1,0]
	v_mul_f32_e32 v71, 0xbfb8aa3b, v76
	v_exp_f32_e32 v71, v71
	s_nop 0
	v_add_f32_e32 v71, 1.0, v71
	v_rcp_f32_e32 v78, v71
	v_mul_f32_e32 v71, 0xbfb8aa3b, v77
	v_exp_f32_e32 v71, v71
	s_nop 0
	v_add_f32_e32 v71, 1.0, v71
	v_rcp_f32_e32 v79, v71
	v_mul_f32_e32 v71, 0xbfb8aa3b, v74
	v_exp_f32_e32 v71, v71
	v_pk_mul_f32 v[76:77], v[76:77], v[78:79]
	v_add_f32_e32 v71, 1.0, v71
	v_rcp_f32_e32 v78, v71
	v_mul_f32_e32 v71, 0xbfb8aa3b, v75
	v_exp_f32_e32 v71, v71
	s_nop 0
	v_add_f32_e32 v71, 1.0, v71
	v_rcp_f32_e32 v79, v71
	s_nop 0
	v_pk_mul_f32 v[74:75], v[74:75], v[78:79]
	v_pk_mul_f32 v[78:79], v[38:39], v[2:3] op_sel_hi:[1,0]
	v_mul_f32_e32 v2, 0xbfb8aa3b, v80
	v_exp_f32_e32 v2, v2
	s_nop 0
	v_add_f32_e32 v2, 1.0, v2
	v_rcp_f32_e32 v82, v2
	v_mul_f32_e32 v2, 0xbfb8aa3b, v81
	v_exp_f32_e32 v2, v2
	s_nop 0
	v_add_f32_e32 v2, 1.0, v2
	v_rcp_f32_e32 v83, v2
	v_mul_f32_e32 v2, 0xbfb8aa3b, v78
	v_exp_f32_e32 v2, v2
	v_pk_mul_f32 v[80:81], v[80:81], v[82:83]
	v_add_f32_e32 v2, 1.0, v2
	v_rcp_f32_e32 v82, v2
	v_mul_f32_e32 v2, 0xbfb8aa3b, v79
	v_exp_f32_e32 v2, v2
	s_nop 0
	v_add_f32_e32 v2, 1.0, v2
	v_rcp_f32_e32 v83, v2
	s_nop 0
	v_pk_mul_f32 v[78:79], v[78:79], v[82:83]
	v_lshl_add_u64 v[82:83], v[72:73], 0, v[68:69]
	v_cvt_pk_bf16_f32 v72, v76, v77
	v_add_co_u32_e32 v76, vcc, 0x643f000, v82
	v_cvt_pk_bf16_f32 v73, v74, v75
	v_cvt_pk_bf16_f32 v74, v80, v81
	v_cvt_pk_bf16_f32 v75, v78, v79
	v_addc_co_u32_e32 v77, vcc, 0, v83, vcc
	global_store_dwordx4 v[76:77], v[72:75], off offset:256
	s_cbranch_scc1 .LBB0_228
	v_add_u32_e32 v78, 0x80, v70
	v_ashrrev_i32_e32 v79, 31, v78
	v_lshl_add_u64 v[80:81], v[78:79], 2, s[70:71]
	v_mov_b32_e32 v84, v246
	v_mov_b32_e32 v82, v247
	v_mov_b32_e32 v74, v248
	v_mov_b32_e32 v2, v249
	v_lshlrev_b64 v[78:79], 11, v[78:79]
	v_lshl_add_u64 v[78:79], s[94:95], 0, v[78:79]
	v_add_u32_e32 v76, 0x90, v70
	v_ashrrev_i32_e32 v77, 31, v76
	v_lshlrev_b64 v[76:77], 11, v[76:77]
	v_lshl_add_u64 v[76:77], s[94:95], 0, v[76:77]
	v_add_u32_e32 v72, 0xa0, v70
	v_ashrrev_i32_e32 v73, 31, v72
	v_lshlrev_b64 v[72:73], 11, v[72:73]
	v_lshl_add_u64 v[72:73], s[94:95], 0, v[72:73]
	v_add_u32_e32 v70, 0xb0, v70
	v_ashrrev_i32_e32 v71, 31, v70
	v_lshlrev_b64 v[70:71], 11, v[70:71]
	v_lshl_add_u64 v[70:71], s[94:95], 0, v[70:71]
	s_waitcnt vmcnt(0)
	v_pk_mul_f32 v[86:87], v[32:33], v[84:85] op_sel_hi:[1,0]
	s_nop 0
	v_mul_f32_e32 v75, 0xbfb8aa3b, v86
	v_exp_f32_e32 v75, v75
	v_pk_mul_f32 v[80:81], v[34:35], v[84:85] op_sel_hi:[1,0]
	v_add_f32_e32 v75, 1.0, v75
	v_rcp_f32_e32 v88, v75
	v_mul_f32_e32 v75, 0xbfb8aa3b, v87
	v_exp_f32_e32 v75, v75
	s_nop 0
	v_add_f32_e32 v75, 1.0, v75
	v_rcp_f32_e32 v89, v75
	v_mul_f32_e32 v75, 0xbfb8aa3b, v80
	v_exp_f32_e32 v75, v75
	v_pk_mul_f32 v[86:87], v[86:87], v[88:89]
	v_add_f32_e32 v75, 1.0, v75
	v_rcp_f32_e32 v88, v75
	v_mul_f32_e32 v75, 0xbfb8aa3b, v81
	v_exp_f32_e32 v75, v75
	s_nop 0
	v_add_f32_e32 v75, 1.0, v75
	v_rcp_f32_e32 v89, v75
	s_nop 0
	v_pk_mul_f32 v[80:81], v[80:81], v[88:89]
	v_pk_mul_f32 v[88:89], v[30:31], v[84:85] op_sel_hi:[1,0]
	v_pk_mul_f32 v[84:85], v[28:29], v[84:85] op_sel_hi:[1,0]
	s_nop 0
	v_mul_f32_e32 v75, 0xbfb8aa3b, v84
	v_exp_f32_e32 v75, v75
	s_nop 0
	v_add_f32_e32 v75, 1.0, v75
	v_rcp_f32_e32 v90, v75
	v_mul_f32_e32 v75, 0xbfb8aa3b, v85
	v_exp_f32_e32 v75, v75
	s_nop 0
	v_add_f32_e32 v75, 1.0, v75
	v_rcp_f32_e32 v91, v75
	v_mul_f32_e32 v75, 0xbfb8aa3b, v88
	v_exp_f32_e32 v75, v75
	v_pk_mul_f32 v[84:85], v[84:85], v[90:91]
	v_add_f32_e32 v75, 1.0, v75
	v_rcp_f32_e32 v90, v75
	v_mul_f32_e32 v75, 0xbfb8aa3b, v89
	v_exp_f32_e32 v75, v75
	s_nop 0
	v_add_f32_e32 v75, 1.0, v75
	v_rcp_f32_e32 v91, v75
	s_nop 0
	v_pk_mul_f32 v[88:89], v[88:89], v[90:91]
	v_lshl_add_u64 v[90:91], v[78:79], 0, v[68:69]
	v_cvt_pk_bf16_f32 v79, v80, v81
	v_cvt_pk_bf16_f32 v80, v84, v85
	v_add_co_u32_e32 v84, vcc, s0, v90
	v_cvt_pk_bf16_f32 v78, v86, v87
	v_cvt_pk_bf16_f32 v81, v88, v89
	v_addc_co_u32_e32 v85, vcc, 0, v91, vcc
	global_store_dwordx4 v[84:85], v[78:81], off offset:256
	s_nop 1
	v_pk_mul_f32 v[78:79], v[24:25], v[82:83] op_sel_hi:[1,0]
	v_pk_mul_f32 v[80:81], v[26:27], v[82:83] op_sel_hi:[1,0]
	v_mul_f32_e32 v75, 0xbfb8aa3b, v78
	v_exp_f32_e32 v75, v75
	s_nop 0
	v_add_f32_e32 v75, 1.0, v75
	v_rcp_f32_e32 v84, v75
	v_mul_f32_e32 v75, 0xbfb8aa3b, v79
	v_exp_f32_e32 v75, v75
	s_nop 0
	v_add_f32_e32 v75, 1.0, v75
	v_rcp_f32_e32 v85, v75
	v_mul_f32_e32 v75, 0xbfb8aa3b, v80
	v_exp_f32_e32 v75, v75
	v_pk_mul_f32 v[78:79], v[78:79], v[84:85]
	v_add_f32_e32 v75, 1.0, v75
	v_rcp_f32_e32 v84, v75
	v_mul_f32_e32 v75, 0xbfb8aa3b, v81
	v_exp_f32_e32 v75, v75
	s_nop 0
	v_add_f32_e32 v75, 1.0, v75
	v_rcp_f32_e32 v85, v75
	s_nop 0
	v_pk_mul_f32 v[80:81], v[80:81], v[84:85]
	v_pk_mul_f32 v[84:85], v[22:23], v[82:83] op_sel_hi:[1,0]
	v_pk_mul_f32 v[82:83], v[20:21], v[82:83] op_sel_hi:[1,0]
	s_nop 0
	v_mul_f32_e32 v75, 0xbfb8aa3b, v82
	v_exp_f32_e32 v75, v75
	s_nop 0
	v_add_f32_e32 v75, 1.0, v75
	v_rcp_f32_e32 v86, v75
	v_mul_f32_e32 v75, 0xbfb8aa3b, v83
	v_exp_f32_e32 v75, v75
	s_nop 0
	v_add_f32_e32 v75, 1.0, v75
	v_rcp_f32_e32 v87, v75
	v_mul_f32_e32 v75, 0xbfb8aa3b, v84
	v_exp_f32_e32 v75, v75
	v_pk_mul_f32 v[82:83], v[82:83], v[86:87]
	v_add_f32_e32 v75, 1.0, v75
	v_rcp_f32_e32 v86, v75
	v_mul_f32_e32 v75, 0xbfb8aa3b, v85
	v_exp_f32_e32 v75, v75
	s_nop 0
	v_add_f32_e32 v75, 1.0, v75
	v_rcp_f32_e32 v87, v75
	s_nop 0
	v_pk_mul_f32 v[84:85], v[84:85], v[86:87]
	v_lshl_add_u64 v[86:87], v[76:77], 0, v[68:69]
	v_cvt_pk_bf16_f32 v77, v80, v81
	v_add_co_u32_e32 v80, vcc, s0, v86
	v_cvt_pk_bf16_f32 v76, v78, v79
	v_cvt_pk_bf16_f32 v78, v82, v83
	v_cvt_pk_bf16_f32 v79, v84, v85
	v_addc_co_u32_e32 v81, vcc, 0, v87, vcc
	global_store_dwordx4 v[80:81], v[76:79], off offset:256
	s_nop 1
	v_pk_mul_f32 v[78:79], v[16:17], v[74:75] op_sel_hi:[1,0]
	v_pk_mul_f32 v[76:77], v[18:19], v[74:75] op_sel_hi:[1,0]
	v_mul_f32_e32 v75, 0xbfb8aa3b, v78
	v_exp_f32_e32 v75, v75
	s_nop 0
	v_add_f32_e32 v75, 1.0, v75
	v_rcp_f32_e32 v80, v75
	v_mul_f32_e32 v75, 0xbfb8aa3b, v79
	v_exp_f32_e32 v75, v75
	s_nop 0
	v_add_f32_e32 v75, 1.0, v75
	v_rcp_f32_e32 v81, v75
	v_mul_f32_e32 v75, 0xbfb8aa3b, v76
	v_exp_f32_e32 v75, v75
	v_pk_mul_f32 v[78:79], v[78:79], v[80:81]
	v_add_f32_e32 v75, 1.0, v75
	v_rcp_f32_e32 v80, v75
	v_mul_f32_e32 v75, 0xbfb8aa3b, v77
	v_exp_f32_e32 v75, v75
	s_nop 0
	v_add_f32_e32 v75, 1.0, v75
	v_rcp_f32_e32 v81, v75
	s_nop 0
	v_pk_mul_f32 v[76:77], v[76:77], v[80:81]
	v_pk_mul_f32 v[80:81], v[14:15], v[74:75] op_sel_hi:[1,0]
	v_pk_mul_f32 v[74:75], v[12:13], v[74:75] op_sel_hi:[1,0]
	s_nop 0
	v_mul_f32_e32 v82, 0xbfb8aa3b, v74
	v_mul_f32_e32 v83, 0xbfb8aa3b, v75
	v_exp_f32_e32 v82, v82
	v_exp_f32_e32 v83, v83
	v_add_f32_e32 v82, 1.0, v82
	v_add_f32_e32 v83, 1.0, v83
	v_rcp_f32_e32 v82, v82
	v_rcp_f32_e32 v83, v83
	s_nop 0
	v_pk_mul_f32 v[74:75], v[74:75], v[82:83]
	v_mul_f32_e32 v82, 0xbfb8aa3b, v80
	v_mul_f32_e32 v83, 0xbfb8aa3b, v81
	v_exp_f32_e32 v82, v82
	v_exp_f32_e32 v83, v83
	v_cvt_pk_bf16_f32 v74, v74, v75
	v_add_f32_e32 v82, 1.0, v82
	v_add_f32_e32 v83, 1.0, v83
	v_rcp_f32_e32 v82, v82
	v_rcp_f32_e32 v83, v83
	s_nop 0
	v_pk_mul_f32 v[80:81], v[80:81], v[82:83]
	v_lshl_add_u64 v[82:83], v[72:73], 0, v[68:69]
	v_cvt_pk_bf16_f32 v73, v76, v77
	v_add_co_u32_e32 v76, vcc, s0, v82
	v_cvt_pk_bf16_f32 v72, v78, v79
	v_cvt_pk_bf16_f32 v75, v80, v81
	v_addc_co_u32_e32 v77, vcc, 0, v83, vcc
	global_store_dwordx4 v[76:77], v[72:75], off offset:256
	v_pk_mul_f32 v[78:79], v[4:5], v[2:3] op_sel_hi:[1,0]
	s_mov_b64 s[0:1], 0
	v_pk_mul_f32 v[74:75], v[8:9], v[2:3] op_sel_hi:[1,0]
	v_pk_mul_f32 v[72:73], v[10:11], v[2:3] op_sel_hi:[1,0]
	v_mul_f32_e32 v76, 0xbfb8aa3b, v74
	v_mul_f32_e32 v77, 0xbfb8aa3b, v75
	v_exp_f32_e32 v76, v76
	v_exp_f32_e32 v77, v77
	v_add_f32_e32 v76, 1.0, v76
	v_add_f32_e32 v77, 1.0, v77
	v_rcp_f32_e32 v76, v76
	v_rcp_f32_e32 v77, v77
	s_nop 0
	v_pk_mul_f32 v[74:75], v[74:75], v[76:77]
	v_mul_f32_e32 v76, 0xbfb8aa3b, v72
	v_mul_f32_e32 v77, 0xbfb8aa3b, v73
	v_exp_f32_e32 v76, v76
	v_exp_f32_e32 v77, v77
	v_add_f32_e32 v76, 1.0, v76
	v_add_f32_e32 v77, 1.0, v77
	v_rcp_f32_e32 v76, v76
	v_rcp_f32_e32 v77, v77
	s_nop 0
	v_pk_mul_f32 v[72:73], v[72:73], v[76:77]
	v_pk_mul_f32 v[76:77], v[6:7], v[2:3] op_sel_hi:[1,0]
	v_mul_f32_e32 v2, 0xbfb8aa3b, v78
	v_exp_f32_e32 v2, v2
	s_nop 0
	v_add_f32_e32 v2, 1.0, v2
	v_rcp_f32_e32 v80, v2
	v_mul_f32_e32 v2, 0xbfb8aa3b, v79
	v_exp_f32_e32 v2, v2
	s_nop 0
	v_add_f32_e32 v2, 1.0, v2
	v_rcp_f32_e32 v81, v2
	v_mul_f32_e32 v2, 0xbfb8aa3b, v76
	v_exp_f32_e32 v2, v2
	v_pk_mul_f32 v[78:79], v[78:79], v[80:81]
	v_add_f32_e32 v2, 1.0, v2
	v_rcp_f32_e32 v80, v2
	v_mul_f32_e32 v2, 0xbfb8aa3b, v77
	v_exp_f32_e32 v2, v2
	s_nop 0
	v_add_f32_e32 v2, 1.0, v2
	v_rcp_f32_e32 v81, v2
	s_nop 0
	v_pk_mul_f32 v[76:77], v[76:77], v[80:81]
	v_lshl_add_u64 v[80:81], v[70:71], 0, v[68:69]
	v_cvt_pk_bf16_f32 v69, v72, v73
	v_add_co_u32_e32 v72, vcc, 0x643f000, v80
	v_cvt_pk_bf16_f32 v68, v74, v75
	v_cvt_pk_bf16_f32 v70, v78, v79
	v_cvt_pk_bf16_f32 v71, v76, v77
	v_addc_co_u32_e32 v73, vcc, 0, v81, vcc
	global_store_dwordx4 v[72:73], v[68:71], off offset:256
	s_branch .LBB0_229

.LBB0_239:
	s_andn2_b64 vcc, exec, s[0:1]
	s_cbranch_vccnz .LBB0_45
	s_lshl_b32 s0, s48, 8
	v_add_u32_e32 v92, s0, v241
	s_movk_i32 s0, 0x7cf
	v_cmp_gt_i32_e32 vcc, s20, v92
	v_and_or_b32 v2, v92, s0, 16
	v_ashrrev_i32_e32 v93, 31, v92
	v_cndmask_b32_e32 v2, v181, v2, vcc
	v_lshl_add_u64 v[68:69], v[92:93], 2, s[70:71]
	v_lshlrev_b32_e32 v2, 8, v2
	v_mov_b32_e32 v114, v164
	v_lshl_add_u64 v[70:71], v[182:183], 0, v[2:3]
	global_load_dwordx4 v[106:109], v[70:71], off offset:16
	global_load_dwordx4 v[110:113], v[70:71], off
	s_movk_i32 s0, 0x7df
	v_or_b32_e32 v98, 16, v92
	v_bitop3_b32 v2, v92, s0, 16 bitop3:0xc8
	v_cmp_gt_i32_e32 vcc, s20, v98
	v_add_u32_e32 v2, 16, v2
	v_mov_b32_e32 v104, v165
	v_cndmask_b32_e32 v2, v181, v2, vcc
	v_lshlrev_b32_e32 v2, 8, v2
	v_lshl_add_u64 v[70:71], v[182:183], 0, v[2:3]
	global_load_dwordx4 v[84:87], v[70:71], off offset:16
	global_load_dwordx4 v[88:91], v[70:71], off
	v_or_b32_e32 v100, 32, v92
	s_movk_i32 s0, 0x7ef
	v_cmp_gt_i32_e32 vcc, s20, v100
	v_and_or_b32 v2, v100, s0, 16
	v_mov_b32_e32 v102, v166
	v_cndmask_b32_e32 v2, v181, v2, vcc
	v_lshlrev_b32_e32 v2, 8, v2
	v_lshl_add_u64 v[70:71], v[182:183], 0, v[2:3]
	global_load_dwordx4 v[76:79], v[70:71], off offset:16
	global_load_dwordx4 v[80:83], v[70:71], off
	s_movk_i32 s0, 0x7ff
	v_or_b32_e32 v94, 48, v92
	v_bitop3_b32 v2, v92, s0, 48 bitop3:0xc8
	v_cmp_gt_i32_e32 vcc, s20, v94
	v_add_u32_e32 v2, 16, v2
	v_mov_b32_e32 v96, v167
	v_cndmask_b32_e32 v2, v181, v2, vcc
	v_lshlrev_b32_e32 v2, 8, v2
	v_lshl_add_u64 v[72:73], v[182:183], 0, v[2:3]
	global_load_dwordx4 v[68:71], v[72:73], off offset:16
	s_nop 0
	global_load_dwordx4 v[72:75], v[72:73], off
	s_mov_b32 s0, 0x3e000000
	s_ashr_i32 s75, s74, 31
	v_ashrrev_i32_e32 v99, 31, v98
	v_ashrrev_i32_e32 v101, 31, v100
	v_ashrrev_i32_e32 v95, 31, v94
	s_cmp_eq_u32 s48, 64
	s_waitcnt vmcnt(0)
	v_pk_mul_f32 v[64:65], v[64:65], v[114:115] op_sel_hi:[1,0]
	v_pk_mul_f32 v[66:67], v[66:67], v[114:115] op_sel_hi:[1,0]
	v_pk_mul_f32 v[116:117], v[110:111], v[64:65] op_sel:[1,1] op_sel_hi:[1,0]
	v_mov_b32_e32 v2, v113
	v_pk_fma_f32 v[118:119], v[110:111], v[64:65], v[116:117] op_sel_hi:[0,1,1] neg_lo:[0,0,1] neg_hi:[0,0,1]
	v_pk_fma_f32 v[110:111], v[110:111], v[64:65], v[116:117] op_sel_hi:[0,1,1]
	v_pk_mul_f32 v[60:61], v[60:61], v[114:115] op_sel_hi:[1,0]
	v_pk_mul_f32 v[64:65], v[2:3], v[66:67] op_sel:[0,1] op_sel_hi:[0,0]
	v_mov_b32_e32 v119, v111
	v_pk_mul_f32 v[62:63], v[62:63], v[114:115] op_sel_hi:[1,0]
	v_pk_mul_f32 v[110:111], v[106:107], v[60:61] op_sel:[1,1] op_sel_hi:[1,0]
	v_mov_b32_e32 v2, v109
	v_pk_fma_f32 v[116:117], v[112:113], v[66:67], v[64:65] op_sel_hi:[0,1,1] neg_lo:[0,0,1] neg_hi:[0,0,1]
	v_pk_fma_f32 v[64:65], v[112:113], v[66:67], v[64:65] op_sel_hi:[0,1,1]
	v_pk_fma_f32 v[112:113], v[106:107], v[60:61], v[110:111] op_sel_hi:[0,1,1] neg_lo:[0,0,1] neg_hi:[0,0,1]
	v_pk_fma_f32 v[60:61], v[106:107], v[60:61], v[110:111] op_sel_hi:[0,1,1]
	v_pk_mul_f32 v[106:107], v[2:3], v[62:63] op_sel:[0,1] op_sel_hi:[0,0]
	v_pk_fma_f32 v[110:111], v[108:109], v[62:63], v[106:107] op_sel_hi:[0,1,1] neg_lo:[0,0,1] neg_hi:[0,0,1]
	v_pk_fma_f32 v[62:63], v[108:109], v[62:63], v[106:107] op_sel_hi:[0,1,1]
	v_mov_b32_e32 v111, v63
	v_mov_b32_e32 v113, v61
	v_lshlrev_b64 v[60:61], 10, v[92:93]
	v_mov_b32_e32 v117, v65
	v_pk_mul_f32 v[62:63], v[110:111], s[0:1] op_sel_hi:[1,0]
	v_lshl_add_u64 v[108:109], s[94:95], 0, v[60:61]
	v_lshl_add_u64 v[60:61], s[74:75], 0, v[178:179]
	v_pk_mul_f32 v[56:57], v[56:57], v[104:105] op_sel_hi:[1,0]
	v_pk_mul_f32 v[64:65], v[116:117], s[0:1] op_sel_hi:[1,0]
	v_lshlrev_b64 v[60:61], 1, v[60:61]
	v_cvt_pk_bf16_f32 v111, v62, v63
	v_pk_mul_f32 v[58:59], v[58:59], v[104:105] op_sel_hi:[1,0]
	v_pk_mul_f32 v[62:63], v[88:89], v[56:57] op_sel:[1,1] op_sel_hi:[1,0]
	v_mov_b32_e32 v2, v91
	v_pk_mul_f32 v[66:67], v[118:119], s[0:1] op_sel_hi:[1,0]
	v_pk_mul_f32 v[106:107], v[112:113], s[0:1] op_sel_hi:[1,0]
	v_lshl_add_u64 v[112:113], v[108:109], 0, v[60:61]
	v_cvt_pk_bf16_f32 v109, v64, v65
	v_pk_fma_f32 v[64:65], v[88:89], v[56:57], v[62:63] op_sel_hi:[0,1,1] neg_lo:[0,0,1] neg_hi:[0,0,1]
	v_pk_fma_f32 v[56:57], v[88:89], v[56:57], v[62:63] op_sel_hi:[0,1,1]
	v_pk_mul_f32 v[62:63], v[2:3], v[58:59] op_sel:[0,1] op_sel_hi:[0,0]
	v_pk_mul_f32 v[52:53], v[52:53], v[104:105] op_sel_hi:[1,0]
	v_cvt_pk_bf16_f32 v108, v66, v67
	v_pk_fma_f32 v[66:67], v[90:91], v[58:59], v[62:63] op_sel_hi:[0,1,1] neg_lo:[0,0,1] neg_hi:[0,0,1]
	v_pk_fma_f32 v[58:59], v[90:91], v[58:59], v[62:63] op_sel_hi:[0,1,1]
	v_mov_b32_e32 v65, v57
	v_pk_mul_f32 v[54:55], v[54:55], v[104:105] op_sel_hi:[1,0]
	v_pk_mul_f32 v[62:63], v[84:85], v[52:53] op_sel:[1,1] op_sel_hi:[1,0]
	v_mov_b32_e32 v2, v87
	v_mov_b32_e32 v67, v59
	v_pk_mul_f32 v[56:57], v[64:65], s[0:1] op_sel_hi:[1,0]
	v_pk_fma_f32 v[64:65], v[84:85], v[52:53], v[62:63] op_sel_hi:[0,1,1] neg_lo:[0,0,1] neg_hi:[0,0,1]
	v_pk_fma_f32 v[52:53], v[84:85], v[52:53], v[62:63] op_sel_hi:[0,1,1]
	v_pk_mul_f32 v[62:63], v[2:3], v[54:55] op_sel:[0,1] op_sel_hi:[0,0]
	v_pk_mul_f32 v[58:59], v[66:67], s[0:1] op_sel_hi:[1,0]
	v_pk_fma_f32 v[66:67], v[86:87], v[54:55], v[62:63] op_sel_hi:[0,1,1] neg_lo:[0,0,1] neg_hi:[0,0,1]
	v_pk_fma_f32 v[54:55], v[86:87], v[54:55], v[62:63] op_sel_hi:[0,1,1]
	v_mov_b32_e32 v67, v55
	v_mov_b32_e32 v65, v53
	v_lshlrev_b64 v[52:53], 10, v[98:99]
	v_pk_mul_f32 v[62:63], v[66:67], s[0:1] op_sel_hi:[1,0]
	v_pk_mul_f32 v[54:55], v[64:65], s[0:1] op_sel_hi:[1,0]
	v_lshl_add_u64 v[52:53], s[94:95], 0, v[52:53]
	v_lshl_add_u64 v[64:65], v[52:53], 0, v[60:61]
	v_cvt_pk_bf16_f32 v52, v56, v57
	v_cvt_pk_bf16_f32 v53, v58, v59
	v_cvt_pk_bf16_f32 v54, v54, v55
	v_cvt_pk_bf16_f32 v55, v62, v63
	v_pk_mul_f32 v[48:49], v[48:49], v[102:103] op_sel_hi:[1,0]
	global_store_dwordx4 v[64:65], v[52:55], off offset:256
	v_pk_mul_f32 v[50:51], v[50:51], v[102:103] op_sel_hi:[1,0]
	v_mov_b32_e32 v2, v83
	v_pk_mul_f32 v[52:53], v[80:81], v[48:49] op_sel:[1,1] op_sel_hi:[1,0]
	v_pk_mul_f32 v[44:45], v[44:45], v[102:103] op_sel_hi:[1,0]
	v_pk_fma_f32 v[54:55], v[80:81], v[48:49], v[52:53] op_sel_hi:[0,1,1] neg_lo:[0,0,1] neg_hi:[0,0,1]
	v_pk_fma_f32 v[48:49], v[80:81], v[48:49], v[52:53] op_sel_hi:[0,1,1]
	v_pk_mul_f32 v[52:53], v[2:3], v[50:51] op_sel:[0,1] op_sel_hi:[0,0]
	v_pk_fma_f32 v[56:57], v[82:83], v[50:51], v[52:53] op_sel_hi:[0,1,1] neg_lo:[0,0,1] neg_hi:[0,0,1]
	v_pk_fma_f32 v[50:51], v[82:83], v[50:51], v[52:53] op_sel_hi:[0,1,1]
	v_mov_b32_e32 v55, v49
	v_pk_mul_f32 v[46:47], v[46:47], v[102:103] op_sel_hi:[1,0]
	v_pk_mul_f32 v[52:53], v[76:77], v[44:45] op_sel:[1,1] op_sel_hi:[1,0]
	v_mov_b32_e32 v2, v79
	v_mov_b32_e32 v57, v51
	v_pk_mul_f32 v[48:49], v[54:55], s[0:1] op_sel_hi:[1,0]
	v_pk_fma_f32 v[54:55], v[76:77], v[44:45], v[52:53] op_sel_hi:[0,1,1] neg_lo:[0,0,1] neg_hi:[0,0,1]
	v_pk_fma_f32 v[44:45], v[76:77], v[44:45], v[52:53] op_sel_hi:[0,1,1]
	v_pk_mul_f32 v[52:53], v[2:3], v[46:47] op_sel:[0,1] op_sel_hi:[0,0]
	v_pk_mul_f32 v[50:51], v[56:57], s[0:1] op_sel_hi:[1,0]
	v_pk_fma_f32 v[56:57], v[78:79], v[46:47], v[52:53] op_sel_hi:[0,1,1] neg_lo:[0,0,1] neg_hi:[0,0,1]
	v_pk_fma_f32 v[46:47], v[78:79], v[46:47], v[52:53] op_sel_hi:[0,1,1]
	v_mov_b32_e32 v57, v47
	v_mov_b32_e32 v55, v45
	v_lshlrev_b64 v[44:45], 10, v[100:101]
	v_pk_mul_f32 v[52:53], v[56:57], s[0:1] op_sel_hi:[1,0]
	v_pk_mul_f32 v[46:47], v[54:55], s[0:1] op_sel_hi:[1,0]
	v_lshl_add_u64 v[44:45], s[94:95], 0, v[44:45]
	v_lshl_add_u64 v[54:55], v[44:45], 0, v[60:61]
	v_cvt_pk_bf16_f32 v44, v48, v49
	v_cvt_pk_bf16_f32 v45, v50, v51
	v_cvt_pk_bf16_f32 v46, v46, v47
	v_cvt_pk_bf16_f32 v47, v52, v53
	v_pk_mul_f32 v[40:41], v[40:41], v[96:97] op_sel_hi:[1,0]
	global_store_dwordx4 v[54:55], v[44:47], off offset:256
	v_pk_mul_f32 v[42:43], v[42:43], v[96:97] op_sel_hi:[1,0]
	v_mov_b32_e32 v2, v75
	v_pk_mul_f32 v[44:45], v[72:73], v[40:41] op_sel:[1,1] op_sel_hi:[1,0]
	v_pk_mul_f32 v[36:37], v[36:37], v[96:97] op_sel_hi:[1,0]
	v_pk_fma_f32 v[46:47], v[72:73], v[40:41], v[44:45] op_sel_hi:[0,1,1] neg_lo:[0,0,1] neg_hi:[0,0,1]
	v_pk_fma_f32 v[40:41], v[72:73], v[40:41], v[44:45] op_sel_hi:[0,1,1]
	v_pk_mul_f32 v[44:45], v[2:3], v[42:43] op_sel:[0,1] op_sel_hi:[0,0]
	v_pk_fma_f32 v[48:49], v[74:75], v[42:43], v[44:45] op_sel_hi:[0,1,1] neg_lo:[0,0,1] neg_hi:[0,0,1]
	v_pk_fma_f32 v[42:43], v[74:75], v[42:43], v[44:45] op_sel_hi:[0,1,1]
	v_mov_b32_e32 v47, v41
	v_pk_mul_f32 v[38:39], v[38:39], v[96:97] op_sel_hi:[1,0]
	v_pk_mul_f32 v[44:45], v[68:69], v[36:37] op_sel:[1,1] op_sel_hi:[1,0]
	v_mov_b32_e32 v2, v71
	v_mov_b32_e32 v49, v43
	v_pk_mul_f32 v[40:41], v[46:47], s[0:1] op_sel_hi:[1,0]
	v_pk_fma_f32 v[46:47], v[68:69], v[36:37], v[44:45] op_sel_hi:[0,1,1] neg_lo:[0,0,1] neg_hi:[0,0,1]
	v_pk_fma_f32 v[36:37], v[68:69], v[36:37], v[44:45] op_sel_hi:[0,1,1]
	v_pk_mul_f32 v[44:45], v[2:3], v[38:39] op_sel:[0,1] op_sel_hi:[0,0]
	v_pk_mul_f32 v[42:43], v[48:49], s[0:1] op_sel_hi:[1,0]
	v_pk_fma_f32 v[48:49], v[70:71], v[38:39], v[44:45] op_sel_hi:[0,1,1] neg_lo:[0,0,1] neg_hi:[0,0,1]
	v_pk_fma_f32 v[38:39], v[70:71], v[38:39], v[44:45] op_sel_hi:[0,1,1]
	v_mov_b32_e32 v49, v39
	v_mov_b32_e32 v47, v37
	v_lshlrev_b64 v[36:37], 10, v[94:95]
	v_pk_mul_f32 v[44:45], v[48:49], s[0:1] op_sel_hi:[1,0]
	v_pk_mul_f32 v[38:39], v[46:47], s[0:1] op_sel_hi:[1,0]
	v_lshl_add_u64 v[36:37], s[94:95], 0, v[36:37]
	v_cvt_pk_bf16_f32 v110, v106, v107
	v_lshl_add_u64 v[46:47], v[36:37], 0, v[60:61]
	v_cvt_pk_bf16_f32 v36, v40, v41
	v_cvt_pk_bf16_f32 v37, v42, v43
	v_cvt_pk_bf16_f32 v38, v38, v39
	v_cvt_pk_bf16_f32 v39, v44, v45
	global_store_dwordx4 v[112:113], v[108:111], off offset:256
	global_store_dwordx4 v[46:47], v[36:39], off offset:256
	s_cbranch_scc1 .LBB0_45
	v_add_u32_e32 v74, 0x80, v92
	s_movk_i32 s0, 0x7cf
	v_cmp_gt_i32_e32 vcc, s20, v74
	v_and_or_b32 v2, v74, s0, 16
	v_ashrrev_i32_e32 v75, 31, v74
	v_cndmask_b32_e32 v2, v181, v2, vcc
	v_lshl_add_u64 v[48:49], v[74:75], 2, s[70:71]
	v_lshlrev_b32_e32 v2, 8, v2
	v_mov_b32_e32 v84, v246
	v_lshl_add_u64 v[36:37], v[182:183], 0, v[2:3]
	global_load_dwordx4 v[76:79], v[36:37], off offset:16
	global_load_dwordx4 v[80:83], v[36:37], off
	v_add_u32_e32 v62, 0x90, v92
	v_and_b32_e32 v2, 0x7df, v62
	v_cmp_gt_i32_e32 vcc, s20, v62
	v_add_u32_e32 v2, 16, v2
	v_mov_b32_e32 v72, v247
	v_cndmask_b32_e32 v2, v181, v2, vcc
	v_lshlrev_b32_e32 v2, 8, v2
	v_lshl_add_u64 v[36:37], v[182:183], 0, v[2:3]
	global_load_dwordx4 v[44:47], v[36:37], off offset:16
	global_load_dwordx4 v[56:59], v[36:37], off
	v_add_u32_e32 v64, 0xa0, v92
	s_movk_i32 s0, 0x7ef
	v_cmp_gt_i32_e32 vcc, s20, v64
	v_and_or_b32 v2, v64, s0, 16
	v_mov_b32_e32 v68, v248
	v_cndmask_b32_e32 v2, v181, v2, vcc
	v_lshlrev_b32_e32 v2, 8, v2
	v_lshl_add_u64 v[40:41], v[182:183], 0, v[2:3]
	global_load_dwordx4 v[36:39], v[40:41], off offset:16
	s_nop 0
	global_load_dwordx4 v[40:43], v[40:41], off
	v_add_u32_e32 v66, 0xb0, v92
	v_and_b32_e32 v2, 0x7ff, v66
	v_cmp_gt_i32_e32 vcc, s20, v66
	v_add_u32_e32 v2, 16, v2
	v_mov_b32_e32 v70, v249
	v_cndmask_b32_e32 v2, v181, v2, vcc
	v_lshlrev_b32_e32 v2, 8, v2
	v_lshl_add_u64 v[52:53], v[182:183], 0, v[2:3]
	global_load_dwordx4 v[48:51], v[52:53], off offset:16
	s_nop 0
	global_load_dwordx4 v[52:55], v[52:53], off
	s_mov_b32 s0, 0x3e000000
	v_ashrrev_i32_e32 v63, 31, v62
	v_ashrrev_i32_e32 v65, 31, v64
	v_ashrrev_i32_e32 v67, 31, v66
	s_waitcnt vmcnt(0)
	v_pk_mul_f32 v[32:33], v[32:33], v[84:85] op_sel_hi:[1,0]
	v_pk_mul_f32 v[34:35], v[34:35], v[84:85] op_sel_hi:[1,0]
	v_pk_mul_f32 v[86:87], v[80:81], v[32:33] op_sel:[1,1] op_sel_hi:[1,0]
	v_mov_b32_e32 v2, v83
	v_pk_fma_f32 v[88:89], v[80:81], v[32:33], v[86:87] op_sel_hi:[0,1,1] neg_lo:[0,0,1] neg_hi:[0,0,1]
	v_pk_fma_f32 v[32:33], v[80:81], v[32:33], v[86:87] op_sel_hi:[0,1,1]
	v_pk_mul_f32 v[80:81], v[2:3], v[34:35] op_sel:[0,1] op_sel_hi:[0,0]
	v_pk_mul_f32 v[28:29], v[28:29], v[84:85] op_sel_hi:[1,0]
	v_pk_fma_f32 v[86:87], v[82:83], v[34:35], v[80:81] op_sel_hi:[0,1,1] neg_lo:[0,0,1] neg_hi:[0,0,1]
	v_pk_fma_f32 v[34:35], v[82:83], v[34:35], v[80:81] op_sel_hi:[0,1,1]
	v_pk_mul_f32 v[30:31], v[30:31], v[84:85] op_sel_hi:[1,0]
	v_pk_mul_f32 v[80:81], v[76:77], v[28:29] op_sel:[1,1] op_sel_hi:[1,0]
	v_mov_b32_e32 v2, v79
	v_pk_fma_f32 v[82:83], v[76:77], v[28:29], v[80:81] op_sel_hi:[0,1,1] neg_lo:[0,0,1] neg_hi:[0,0,1]
	v_pk_fma_f32 v[28:29], v[76:77], v[28:29], v[80:81] op_sel_hi:[0,1,1]
	v_pk_mul_f32 v[76:77], v[2:3], v[30:31] op_sel:[0,1] op_sel_hi:[0,0]
	v_pk_fma_f32 v[80:81], v[78:79], v[30:31], v[76:77] op_sel_hi:[0,1,1] neg_lo:[0,0,1] neg_hi:[0,0,1]
	v_pk_fma_f32 v[30:31], v[78:79], v[30:31], v[76:77] op_sel_hi:[0,1,1]
	v_mov_b32_e32 v87, v35
	v_mov_b32_e32 v89, v33
	v_mov_b32_e32 v81, v31
	v_mov_b32_e32 v83, v29
	v_lshlrev_b64 v[28:29], 10, v[74:75]
	v_pk_mul_f32 v[34:35], v[86:87], s[0:1] op_sel_hi:[1,0]
	v_pk_mul_f32 v[32:33], v[88:89], s[0:1] op_sel_hi:[1,0]
	v_pk_mul_f32 v[76:77], v[80:81], s[0:1] op_sel_hi:[1,0]
	v_pk_mul_f32 v[30:31], v[82:83], s[0:1] op_sel_hi:[1,0]
	v_lshl_add_u64 v[28:29], s[94:95], 0, v[28:29]
	v_lshl_add_u64 v[74:75], v[28:29], 0, v[60:61]
	v_cvt_pk_bf16_f32 v28, v32, v33
	v_cvt_pk_bf16_f32 v29, v34, v35
	v_cvt_pk_bf16_f32 v30, v30, v31
	v_cvt_pk_bf16_f32 v31, v76, v77
	v_pk_mul_f32 v[24:25], v[24:25], v[72:73] op_sel_hi:[1,0]
	global_store_dwordx4 v[74:75], v[28:31], off offset:256
	v_pk_mul_f32 v[26:27], v[26:27], v[72:73] op_sel_hi:[1,0]
	v_mov_b32_e32 v2, v59
	v_pk_mul_f32 v[28:29], v[56:57], v[24:25] op_sel:[1,1] op_sel_hi:[1,0]
	v_pk_mul_f32 v[20:21], v[20:21], v[72:73] op_sel_hi:[1,0]
	v_pk_fma_f32 v[30:31], v[56:57], v[24:25], v[28:29] op_sel_hi:[0,1,1] neg_lo:[0,0,1] neg_hi:[0,0,1]
	v_pk_fma_f32 v[24:25], v[56:57], v[24:25], v[28:29] op_sel_hi:[0,1,1]
	v_pk_mul_f32 v[28:29], v[2:3], v[26:27] op_sel:[0,1] op_sel_hi:[0,0]
	v_pk_fma_f32 v[32:33], v[58:59], v[26:27], v[28:29] op_sel_hi:[0,1,1] neg_lo:[0,0,1] neg_hi:[0,0,1]
	v_pk_fma_f32 v[26:27], v[58:59], v[26:27], v[28:29] op_sel_hi:[0,1,1]
	v_mov_b32_e32 v31, v25
	v_pk_mul_f32 v[22:23], v[22:23], v[72:73] op_sel_hi:[1,0]
	v_pk_mul_f32 v[28:29], v[44:45], v[20:21] op_sel:[1,1] op_sel_hi:[1,0]
	v_mov_b32_e32 v2, v47
	v_mov_b32_e32 v33, v27
	v_pk_mul_f32 v[24:25], v[30:31], s[0:1] op_sel_hi:[1,0]
	v_pk_fma_f32 v[30:31], v[44:45], v[20:21], v[28:29] op_sel_hi:[0,1,1] neg_lo:[0,0,1] neg_hi:[0,0,1]
	v_pk_fma_f32 v[20:21], v[44:45], v[20:21], v[28:29] op_sel_hi:[0,1,1]
	v_pk_mul_f32 v[28:29], v[2:3], v[22:23] op_sel:[0,1] op_sel_hi:[0,0]
	v_pk_mul_f32 v[26:27], v[32:33], s[0:1] op_sel_hi:[1,0]
	v_pk_fma_f32 v[32:33], v[46:47], v[22:23], v[28:29] op_sel_hi:[0,1,1] neg_lo:[0,0,1] neg_hi:[0,0,1]
	v_pk_fma_f32 v[22:23], v[46:47], v[22:23], v[28:29] op_sel_hi:[0,1,1]
	v_mov_b32_e32 v33, v23
	v_mov_b32_e32 v31, v21
	v_lshlrev_b64 v[20:21], 10, v[62:63]
	v_pk_mul_f32 v[28:29], v[32:33], s[0:1] op_sel_hi:[1,0]
	v_pk_mul_f32 v[22:23], v[30:31], s[0:1] op_sel_hi:[1,0]
	v_lshl_add_u64 v[20:21], s[94:95], 0, v[20:21]
	v_lshl_add_u64 v[30:31], v[20:21], 0, v[60:61]
	v_cvt_pk_bf16_f32 v20, v24, v25
	v_cvt_pk_bf16_f32 v21, v26, v27
	v_cvt_pk_bf16_f32 v22, v22, v23
	v_cvt_pk_bf16_f32 v23, v28, v29
	v_pk_mul_f32 v[16:17], v[16:17], v[68:69] op_sel_hi:[1,0]
	global_store_dwordx4 v[30:31], v[20:23], off offset:256
	v_pk_mul_f32 v[18:19], v[18:19], v[68:69] op_sel_hi:[1,0]
	v_mov_b32_e32 v2, v43
	v_pk_mul_f32 v[20:21], v[40:41], v[16:17] op_sel:[1,1] op_sel_hi:[1,0]
	v_pk_mul_f32 v[12:13], v[12:13], v[68:69] op_sel_hi:[1,0]
	v_pk_fma_f32 v[22:23], v[40:41], v[16:17], v[20:21] op_sel_hi:[0,1,1] neg_lo:[0,0,1] neg_hi:[0,0,1]
	v_pk_fma_f32 v[16:17], v[40:41], v[16:17], v[20:21] op_sel_hi:[0,1,1]
	v_pk_mul_f32 v[20:21], v[2:3], v[18:19] op_sel:[0,1] op_sel_hi:[0,0]
	v_pk_fma_f32 v[24:25], v[42:43], v[18:19], v[20:21] op_sel_hi:[0,1,1] neg_lo:[0,0,1] neg_hi:[0,0,1]
	v_pk_fma_f32 v[18:19], v[42:43], v[18:19], v[20:21] op_sel_hi:[0,1,1]
	v_mov_b32_e32 v23, v17
	v_pk_mul_f32 v[14:15], v[14:15], v[68:69] op_sel_hi:[1,0]
	v_pk_mul_f32 v[20:21], v[36:37], v[12:13] op_sel:[1,1] op_sel_hi:[1,0]
	v_mov_b32_e32 v2, v39
	v_mov_b32_e32 v25, v19
	v_pk_mul_f32 v[16:17], v[22:23], s[0:1] op_sel_hi:[1,0]
	v_pk_fma_f32 v[22:23], v[36:37], v[12:13], v[20:21] op_sel_hi:[0,1,1] neg_lo:[0,0,1] neg_hi:[0,0,1]
	v_pk_fma_f32 v[12:13], v[36:37], v[12:13], v[20:21] op_sel_hi:[0,1,1]
	v_pk_mul_f32 v[20:21], v[2:3], v[14:15] op_sel:[0,1] op_sel_hi:[0,0]
	v_pk_mul_f32 v[18:19], v[24:25], s[0:1] op_sel_hi:[1,0]
	v_pk_fma_f32 v[24:25], v[38:39], v[14:15], v[20:21] op_sel_hi:[0,1,1] neg_lo:[0,0,1] neg_hi:[0,0,1]
	v_pk_fma_f32 v[14:15], v[38:39], v[14:15], v[20:21] op_sel_hi:[0,1,1]
	v_mov_b32_e32 v25, v15
	v_mov_b32_e32 v23, v13
	v_lshlrev_b64 v[12:13], 10, v[64:65]
	v_pk_mul_f32 v[20:21], v[24:25], s[0:1] op_sel_hi:[1,0]
	v_pk_mul_f32 v[14:15], v[22:23], s[0:1] op_sel_hi:[1,0]
	v_lshl_add_u64 v[12:13], s[94:95], 0, v[12:13]
	v_lshl_add_u64 v[22:23], v[12:13], 0, v[60:61]
	v_cvt_pk_bf16_f32 v12, v16, v17
	v_cvt_pk_bf16_f32 v13, v18, v19
	v_cvt_pk_bf16_f32 v14, v14, v15
	v_cvt_pk_bf16_f32 v15, v20, v21
	v_pk_mul_f32 v[8:9], v[8:9], v[70:71] op_sel_hi:[1,0]
	global_store_dwordx4 v[22:23], v[12:15], off offset:256
	v_pk_mul_f32 v[10:11], v[10:11], v[70:71] op_sel_hi:[1,0]
	v_mov_b32_e32 v2, v55
	v_pk_mul_f32 v[12:13], v[52:53], v[8:9] op_sel:[1,1] op_sel_hi:[1,0]
	v_pk_mul_f32 v[4:5], v[4:5], v[70:71] op_sel_hi:[1,0]
	v_pk_fma_f32 v[14:15], v[52:53], v[8:9], v[12:13] op_sel_hi:[0,1,1] neg_lo:[0,0,1] neg_hi:[0,0,1]
	v_pk_fma_f32 v[8:9], v[52:53], v[8:9], v[12:13] op_sel_hi:[0,1,1]
	v_pk_mul_f32 v[12:13], v[2:3], v[10:11] op_sel:[0,1] op_sel_hi:[0,0]
	v_pk_fma_f32 v[16:17], v[54:55], v[10:11], v[12:13] op_sel_hi:[0,1,1] neg_lo:[0,0,1] neg_hi:[0,0,1]
	v_pk_fma_f32 v[10:11], v[54:55], v[10:11], v[12:13] op_sel_hi:[0,1,1]
	v_mov_b32_e32 v15, v9
	v_pk_mul_f32 v[6:7], v[6:7], v[70:71] op_sel_hi:[1,0]
	v_pk_mul_f32 v[12:13], v[48:49], v[4:5] op_sel:[1,1] op_sel_hi:[1,0]
	v_mov_b32_e32 v2, v51
	v_mov_b32_e32 v17, v11
	v_pk_mul_f32 v[8:9], v[14:15], s[0:1] op_sel_hi:[1,0]
	v_pk_fma_f32 v[14:15], v[48:49], v[4:5], v[12:13] op_sel_hi:[0,1,1] neg_lo:[0,0,1] neg_hi:[0,0,1]
	v_pk_fma_f32 v[4:5], v[48:49], v[4:5], v[12:13] op_sel_hi:[0,1,1]
	v_pk_mul_f32 v[12:13], v[2:3], v[6:7] op_sel:[0,1] op_sel_hi:[0,0]
	v_pk_mul_f32 v[10:11], v[16:17], s[0:1] op_sel_hi:[1,0]
	v_pk_fma_f32 v[16:17], v[50:51], v[6:7], v[12:13] op_sel_hi:[0,1,1] neg_lo:[0,0,1] neg_hi:[0,0,1]
	v_pk_fma_f32 v[6:7], v[50:51], v[6:7], v[12:13] op_sel_hi:[0,1,1]
	v_mov_b32_e32 v17, v7
	v_mov_b32_e32 v15, v5
	v_lshlrev_b64 v[4:5], 10, v[66:67]
	v_pk_mul_f32 v[12:13], v[16:17], s[0:1] op_sel_hi:[1,0]
	v_pk_mul_f32 v[6:7], v[14:15], s[0:1] op_sel_hi:[1,0]
	v_lshl_add_u64 v[4:5], s[94:95], 0, v[4:5]
	v_lshl_add_u64 v[14:15], v[4:5], 0, v[60:61]
	v_cvt_pk_bf16_f32 v4, v8, v9
	v_cvt_pk_bf16_f32 v5, v10, v11
	v_cvt_pk_bf16_f32 v6, v6, v7
	v_cvt_pk_bf16_f32 v7, v12, v13
	global_store_dwordx4 v[14:15], v[4:7], off offset:256
	s_branch .LBB0_45
.LBB0_242:
	v_mov_b64_e32 v[164:165], 0x100
	v_mov_b64_e32 v[166:167], 0xff
	v_mov_b32_e32 v246, 0
	v_mov_b32_e32 v247, 0
	v_mov_b32_e32 v248, 0
	v_mov_b32_e32 v249, 0
	v_mov_b32_e32 v171, 0x3f2aaaaa
	v_mov_b32_e32 v240, 0x37000000
	s_waitcnt vmcnt(0)
	v_readlane_b32 s76, v255, 20
	v_readlane_b32 s72, v255, 28
	s_cmpk_gt_u32 s22, 0xff
	v_readlane_b32 s77, v255, 21
	v_readlane_b32 s73, v255, 29
	v_readlane_b32 s78, v255, 34
	v_mov_b32_e32 v216, 0x3e91f4c4
	v_mov_b32_e32 v218, 0x1100
	v_mov_b64_e32 v[242:243], 0x3ff
	v_mov_b32_e32 v226, 0x48f42400
	v_mov_b32_e32 v228, 0x461c4000
	s_cbranch_scc1 .LBB0_244
	s_barrier
